# pipelined fixed-max attention loop + pipelined GEMM k-loops (P2/P4/P6) + conv tile loads batched + adaLN row prefetch + 64B-aligned hand-written loops
# speedup vs baseline: 1.0245x; 1.0245x over previous
; DI void phase0(const Params& p, char* lds0) {
;     ...
;       for (int kh = 0; kh < 2; ++kh) {
;         __syncthreads();
;         for (int idx = tid; idx < NBR * 512; idx += 256) {
;           int r = idx >> 9, k = idx & 511;
;           float c = r < 16 ? p.cp[r * 1024 + kh * 512 + k] : p.cs[(r - 16) * 1024 + kh * 512 + k];
;           sc[k * 20 + r] = c / (1.f + __expf(-c));
;         }
;         __syncthreads();
;         for (int i = 0; i < 128; ++i) {
;           const int kl = w * 128 + i;
;           const float wv = p.w_ada[(size_t)(kh * 512 + kl) * 6144 + col];
;           const float4* s4 = (const float4*)(sc + kl * 20);
;           float4 a0 = s4[0], a1 = s4[1], a2 = s4[2], a3 = s4[3];
;           float2 a4 = *(const float2*)(sc + kl * 20 + 16);
.LBB0_30:
	v_lshrrev_b32_e32 v12, 9, v7
	v_lshlrev_b32_e32 v8, 10, v12
	v_add_u32_e32 v10, 0xffffc000, v8
	v_cmp_gt_u32_e32 vcc, s18, v7
	v_and_b32_e32 v13, 0x1ff, v7
	s_nop 0
	v_cndmask_b32_e32 v8, v10, v8, vcc
	v_cndmask_b32_e32 v11, v40, v41, vcc
	v_cndmask_b32_e32 v10, v42, v43, vcc
	v_or_b32_e32 v8, v8, v13
	v_lshl_add_u64 v[10:11], v[8:9], 2, v[10:11]
	global_load_dword v8, v[10:11], off
	v_add_u32_e32 v10, 0x100, v7
	v_cmp_lt_u32_e32 vcc, s19, v7
	v_mul_u32_u24_e32 v7, 0x50, v13
	v_lshlrev_b32_e32 v11, 2, v12
	v_add3_u32 v11, v33, v7, v11
	s_or_b64 s[14:15], vcc, s[14:15]
	s_waitcnt vmcnt(0)
	v_mul_f32_e32 v7, 0xbfb8aa3b, v8
	v_exp_f32_e32 v12, v7
	v_mov_b32_e32 v7, v10
	v_add_f32_e32 v10, 1.0, v12
	v_div_scale_f32 v12, s[16:17], v10, v10, v8
	v_rcp_f32_e32 v13, v12
	v_div_scale_f32 v14, vcc, v8, v10, v8
	v_fma_f32 v15, -v12, v13, 1.0
	v_fmac_f32_e32 v13, v15, v13
	v_mul_f32_e32 v15, v14, v13
	v_fma_f32 v16, -v12, v15, v14
	v_fmac_f32_e32 v15, v16, v13
	v_fma_f32 v12, -v12, v15, v14
	v_div_fmas_f32 v12, v12, v13, v15
	v_div_fixup_f32 v8, v12, v10, v8
	ds_write_b32 v11, v8
	s_andn2_b64 exec, exec, s[14:15]
	s_cbranch_execnz .LBB0_30
	s_or_b64 exec, exec, s[14:15]
	v_ashrrev_i32_e32 v7, 31, v6
	v_mov_b32_e32 v12, 0
	v_lshl_add_u64 v[10:11], v[6:7], 2, v[4:5]
	v_mov_b32_e32 v124, v10
	v_mov_b32_e32 v125, v11
	s_mov_b32 s98, 0
.Lpf_mod_a:
	global_load_dword v126, v[124:125], off
	v_add_co_u32_e32 v124, vcc, 0x6000, v124
	s_add_u32 s98, s98, 1
	s_cmp_lt_u32 s98, 0x80
	v_addc_co_u32_e32 v125, vcc, 0, v125, vcc
	s_cbranch_scc1 .Lpf_mod_a
	v_add_co_u32_e32 v124, vcc, 0xc00000, v10
	s_mov_b32 s98, 0
	s_nop 0
	v_addc_co_u32_e32 v125, vcc, 0, v11, vcc
.Lpf_mod_b:
	global_load_dword v126, v[124:125], off
	v_add_co_u32_e32 v124, vcc, 0x6000, v124
	s_add_u32 s98, s98, 1
	s_cmp_lt_u32 s98, 0x80
	v_addc_co_u32_e32 v125, vcc, 0, v125, vcc
	s_cbranch_scc1 .Lpf_mod_b
	s_mov_b64 s[14:15], 0
	v_mov_b32_e32 v7, v35
	v_mov_b32_e32 v13, v12
	v_mov_b32_e32 v14, v12
	v_mov_b32_e32 v15, v12
	v_mov_b32_e32 v16, v12
	v_mov_b32_e32 v17, v12
	v_mov_b32_e32 v18, v12
	v_mov_b32_e32 v19, v12
	v_mov_b32_e32 v20, v12
	v_mov_b32_e32 v21, v12
	v_mov_b32_e32 v22, v12
	v_mov_b32_e32 v23, v12
	v_mov_b32_e32 v24, v12
	v_mov_b32_e32 v25, v12
	v_mov_b32_e32 v26, v12
	v_mov_b32_e32 v27, v12
	v_mov_b32_e32 v28, v12
	v_mov_b32_e32 v29, v12
	s_waitcnt lgkmcnt(0)
	s_barrier

; #define MFMA(a, b, c) __builtin_amdgcn_mfma_f32_32x32x16_bf16((a), (b), (c), 0, 0, 0)
; #define WAIT_V(n) asm volatile("s_waitcnt vmcnt(%0)" ::"n"(n) : "memory")
; #define RAW_BARRIER() do { asm volatile("s_waitcnt lgkmcnt(0)" ::: "memory"); __builtin_amdgcn_s_barrier(); } while (0)
; template <typename FA, typename FB, typename FE>
; DI void gemm_tile(char* lds, int K, int astride, int bstride, FA arow, FB brow, FE epi) {
;     ...
;   stage(0, 0); stage(1, 1); stage(2, 2);
;   for (int kt = 0; kt < nk; ++kt) {
;     if (kt + 2 < nk) WAIT_V(8); else if (kt + 1 < nk) WAIT_V(4); else WAIT_V(0);
;     RAW_BARRIER();
;     if (kt + 3 < nk) stage((kt + 3) & 3, kt + 3);
;     const char* sa = lds + (kt & 3) * 32768 + wm * 4096;
;     const char* sb = lds + (kt & 3) * 32768 + 16384 + wn * 8192;
; #pragma unroll
;     for (int ks = 0; ks < 2; ++ks) {
;       bf16x8 a0 = *(const bf16x8*)(sa + foff[ks]), a1 = *(const bf16x8*)(sa + 2048 + foff[ks]);
; #pragma unroll
;       for (int nt = 0; nt < 4; ++nt) {
;         bf16x8 bb = *(const bf16x8*)(sb + nt * 2048 + foff[ks]);
;         acc[0][nt] = MFMA(a0, bb, acc[0][nt]);
;         acc[1][nt] = MFMA(a1, bb, acc[1][nt]);
;       }
;     }
;   }
.LBB0_120:
	s_waitcnt lgkmcnt(0)
	s_waitcnt vmcnt(8)
	s_barrier
	s_add_i32 s43, s1, 0xfffe8000
	s_and_b32 s43, s43, 0x18000
	s_add_i32 s46, s43, s45
	s_or_b32 s43, s43, s27
	v_add_u32_e32 v244, s46, v159
	v_add_u32_e32 v245, s43, v159
	ds_read_b128 v[196:199], v244
	ds_read_b128 v[204:207], v245 offset:16384
	ds_read_b128 v[200:203], v244 offset:2048
	ds_read_b128 v[208:211], v245 offset:18432
	ds_read_b128 v[212:215], v245 offset:20480
	ds_read_b128 v[216:219], v245 offset:22528
	.p2align 6
.Lgm_P2_loop:
	s_and_b32 s42, s1, 0x18000
	s_add_i32 s42, s0, s42
	s_waitcnt vmcnt(4)
	v_lshl_add_u64 v[138:139], v[134:135], 0, v[160:161]
	v_lshl_add_u64 v[140:141], v[130:131], 0, v[160:161]
	s_mov_b32 m0, s42
	s_barrier
	s_add_i32 s43, s1, 0xfffe8000
	s_and_b32 s43, s43, 0x18000
	s_add_i32 s46, s43, s45
	s_or_b32 s43, s43, s27
	v_add_u32_e32 v246, s46, v162
	v_add_u32_e32 v247, s43, v162
	s_waitcnt lgkmcnt(4)
	v_mfma_f32_32x32x16_bf16 v[114:129], v[196:199], v[204:207], v[114:129]
	global_load_lds_dwordx4 v[138:139], off
	s_add_i32 m0, s42, 0x4000
	ds_read_b128 v[220:223], v246
	s_waitcnt lgkmcnt(4)
	v_mfma_f32_32x32x16_bf16 v[50:65], v[200:203], v[204:207], v[50:65]
	v_lshl_add_u64 v[142:143], v[136:137], 0, v[160:161]
	global_load_lds_dwordx4 v[140:141], off
	s_add_i32 m0, s42, 0x400
	ds_read_b128 v[228:231], v247 offset:16384
	s_waitcnt lgkmcnt(4)
	v_mfma_f32_32x32x16_bf16 v[98:113], v[196:199], v[208:211], v[98:113]
	v_lshl_add_u64 v[144:145], v[132:133], 0, v[160:161]
	global_load_lds_dwordx4 v[142:143], off
	s_add_i32 m0, s42, 0x4400
	ds_read_b128 v[224:227], v246 offset:2048
	v_mfma_f32_32x32x16_bf16 v[34:49], v[200:203], v[208:211], v[34:49]
	ds_read_b128 v[232:235], v247 offset:18432
	global_load_lds_dwordx4 v[144:145], off
	s_waitcnt lgkmcnt(5)
	v_mfma_f32_32x32x16_bf16 v[82:97], v[196:199], v[212:215], v[82:97]
	ds_read_b128 v[236:239], v247 offset:20480
	v_lshl_add_u64 v[130:131], v[130:131], 0, s[20:21]
	v_lshl_add_u64 v[132:133], v[132:133], 0, s[20:21]
	v_mfma_f32_32x32x16_bf16 v[18:33], v[200:203], v[212:215], v[18:33]
	ds_read_b128 v[240:243], v247 offset:22528
	v_lshl_add_u64 v[134:135], v[134:135], 0, 64
	v_lshl_add_u64 v[136:137], v[136:137], 0, 64
	s_waitcnt lgkmcnt(6)
	v_mfma_f32_32x32x16_bf16 v[66:81], v[196:199], v[216:219], v[66:81]
	s_add_i32 s43, s1, 0xffff0000
	s_and_b32 s43, s43, 0x18000
	s_add_i32 s46, s43, s45
	v_mfma_f32_32x32x16_bf16 v[2:17], v[200:203], v[216:219], v[2:17]
	s_or_b32 s43, s43, s27
	v_add_u32_e32 v244, s46, v159
	v_add_u32_e32 v245, s43, v159
	s_waitcnt lgkmcnt(4)
	v_mfma_f32_32x32x16_bf16 v[114:129], v[220:223], v[228:231], v[114:129]
	ds_read_b128 v[196:199], v244
	s_waitcnt lgkmcnt(4)
	v_mfma_f32_32x32x16_bf16 v[50:65], v[224:227], v[228:231], v[50:65]
	ds_read_b128 v[204:207], v245 offset:16384
	s_waitcnt lgkmcnt(4)
	v_mfma_f32_32x32x16_bf16 v[98:113], v[220:223], v[232:235], v[98:113]
	ds_read_b128 v[200:203], v244 offset:2048
	v_mfma_f32_32x32x16_bf16 v[34:49], v[224:227], v[232:235], v[34:49]
	ds_read_b128 v[208:211], v245 offset:18432
	s_waitcnt lgkmcnt(5)
	v_mfma_f32_32x32x16_bf16 v[82:97], v[220:223], v[236:239], v[82:97]
	ds_read_b128 v[212:215], v245 offset:20480
	v_mfma_f32_32x32x16_bf16 v[18:33], v[224:227], v[236:239], v[18:33]
	ds_read_b128 v[216:219], v245 offset:22528
	s_waitcnt lgkmcnt(6)
	v_mfma_f32_32x32x16_bf16 v[66:81], v[220:223], v[240:243], v[66:81]
	s_add_i32 s1, s1, 0x8000
	v_mfma_f32_32x32x16_bf16 v[2:17], v[224:227], v[240:243], v[2:17]
	s_cmp_eq_u32 s1, 0x100000
	s_cbranch_scc0 .Lgm_P2_loop
	s_waitcnt vmcnt(8)
	v_add_u32_e32 v138, s45, v159
	v_add_u32_e32 v142, s27, v159
	s_waitcnt lgkmcnt(0)
	s_barrier
	ds_read_b128 v[130:133], v138 offset:32768
	ds_read_b128 v[134:137], v142 offset:49152
	ds_read_b128 v[138:141], v138 offset:34816
	v_add_u32_e32 v143, s27, v162
	s_add_i32 s0, s44, 0xffff0000
	s_waitcnt lgkmcnt(0)
	v_mfma_f32_32x32x16_bf16 v[114:129], v[130:133], v[134:137], v[114:129]
	s_lshr_b32 s46, s0, 14
	s_ashr_i32 s47, s41, 4
	s_cmpk_lt_i32 s41, 0x100
	s_cselect_b64 s[0:1], -1, 0
	s_and_b64 s[42:43], s[0:1], exec
	s_cselect_b32 s48, 0xf00, s36
	s_cselect_b32 s42, s47, s46
	v_mfma_f32_32x32x16_bf16 v[50:65], v[138:141], v[134:137], v[50:65]
	ds_read_b128 v[134:137], v142 offset:51200
	s_cselect_b32 s43, 0, 0x2000000
	s_add_i32 s46, s45, 0x10000
	s_or_b32 s47, s27, 0x14000
	v_add_u32_e32 v150, s47, v159
	v_add_u32_e32 v190, s46, v162
	s_or_b32 s27, s27, 0x1c000
	s_waitcnt lgkmcnt(0)
	v_mfma_f32_32x32x16_bf16 v[98:113], v[130:133], v[134:137], v[98:113]
	v_add_u32_e32 v242, s27, v159
	v_add_u32_e32 v234, s27, v162
	s_and_b32 s27, s48, s44
	v_mfma_f32_32x32x16_bf16 v[34:49], v[138:141], v[134:137], v[34:49]
	ds_read_b128 v[134:137], v142 offset:53248
	s_waitcnt lgkmcnt(0)
	v_mfma_f32_32x32x16_bf16 v[82:97], v[130:133], v[134:137], v[82:97]
	v_mfma_f32_32x32x16_bf16 v[18:33], v[138:141], v[134:137], v[18:33]
	ds_read_b128 v[134:137], v142 offset:55296
	v_add_u32_e32 v142, s45, v162
	s_add_i32 s45, s45, 0x18000
	v_add_u32_e32 v214, s45, v162
	s_cmp_gt_i32 s40, 3
	s_waitcnt lgkmcnt(0)
	v_mfma_f32_32x32x16_bf16 v[66:81], v[130:133], v[134:137], v[66:81]
	ds_read_b128 v[130:133], v142 offset:32768
	v_mfma_f32_32x32x16_bf16 v[2:17], v[138:141], v[134:137], v[2:17]
	ds_read_b128 v[138:141], v142 offset:34816
	ds_read_b128 v[134:137], v143 offset:49152
	s_waitcnt lgkmcnt(0)
	v_mfma_f32_32x32x16_bf16 v[114:129], v[130:133], v[134:137], v[114:129]
	v_mfma_f32_32x32x16_bf16 v[50:65], v[138:141], v[134:137], v[50:65]
	ds_read_b128 v[134:137], v143 offset:51200
	s_waitcnt lgkmcnt(0)
	v_mfma_f32_32x32x16_bf16 v[98:113], v[130:133], v[134:137], v[98:113]
	v_mfma_f32_32x32x16_bf16 v[34:49], v[138:141], v[134:137], v[34:49]
	ds_read_b128 v[134:137], v143 offset:53248
	ds_read_b128 v[142:145], v143 offset:55296
	s_waitcnt vmcnt(4)
	s_waitcnt lgkmcnt(0)
	s_barrier
; #define MFMA(a, b, c) __builtin_amdgcn_mfma_f32_32x32x16_bf16((a), (b), (c), 0, 0, 0)
; DI unsigned pk2(float a, float b) { fl2_t f = {a, b}; bf2_t r = __builtin_convertvector(f, bf2_t); return __builtin_bit_cast(unsigned, r); }
; #define RAW_BARRIER() do { asm volatile("s_waitcnt lgkmcnt(0)" ::: "memory"); __builtin_amdgcn_s_barrier(); } while (0)
; template <typename FA, typename FB, typename FE>
; DI void gemm_tile(char* lds, int K, int astride, int bstride, FA arow, FB brow, FE epi) {
;     ...
;       bf16x8 a0 = *(const bf16x8*)(sa + foff[ks]), a1 = *(const bf16x8*)(sa + 2048 + foff[ks]);
; #pragma unroll
;       for (int nt = 0; nt < 4; ++nt) {
;         bf16x8 bb = *(const bf16x8*)(sb + nt * 2048 + foff[ks]);
;         acc[0][nt] = MFMA(a0, bb, acc[0][nt]);
;         acc[1][nt] = MFMA(a1, bb, acc[1][nt]);
;       }
;     }
;   }
;   RAW_BARRIER();
;   bfr* Cs = (bfr*)lds;
; #pragma unroll
;   for (int mt = 0; mt < 2; ++mt)
; #pragma unroll
;     for (int nt = 0; nt < 4; ++nt)
; #pragma unroll
;       for (int i = 0; i < 16; i += 2) {
;         const int row = wm * 64 + mt * 32 + (i & 3) + 8 * (i >> 2) + 4 * h8;
;         const unsigned pr = pk2(acc[mt][nt][i], acc[mt][nt][i + 1]);
;         Cs[row * CSS + wn * 128 + nt * 32 + r] = (bfr)(pr & 0xffffu);
;         Cs[(row + 1) * CSS + wn * 128 + nt * 32 + r] = (bfr)(pr >> 16);
;       }
	s_waitcnt lgkmcnt(0)
	v_mfma_f32_32x32x16_bf16 v[82:97], v[130:133], v[134:137], v[82:97]
	v_mfma_f32_32x32x16_bf16 v[18:33], v[138:141], v[134:137], v[18:33]
	v_add_u32_e32 v134, s46, v159
	ds_read_b128 v[178:181], v134
	v_mfma_f32_32x32x16_bf16 v[66:81], v[130:133], v[142:145], v[66:81]
	ds_read_b128 v[130:133], v150
	ds_read_b128 v[134:137], v134 offset:2048
	s_waitcnt lgkmcnt(0)
	v_mfma_f32_32x32x16_bf16 v[114:129], v[178:181], v[130:133], v[114:129]
	v_mfma_f32_32x32x16_bf16 v[2:17], v[138:141], v[142:145], v[2:17]
	ds_read_b128 v[142:145], v150 offset:2048
	v_add_u32_e32 v138, s47, v162
	v_mfma_f32_32x32x16_bf16 v[50:65], v[134:137], v[130:133], v[50:65]
	ds_read_b128 v[130:133], v138 offset:6144
	ds_read_b128 v[146:149], v138 offset:4096
	ds_read_b128 v[182:185], v138 offset:2048
	ds_read_b128 v[186:189], v138
	ds_read_b128 v[138:141], v190 offset:2048
	ds_read_b128 v[190:193], v190
	s_waitcnt lgkmcnt(0)
	v_mfma_f32_32x32x16_bf16 v[98:113], v[178:181], v[142:145], v[98:113]
	v_mfma_f32_32x32x16_bf16 v[34:49], v[134:137], v[142:145], v[34:49]
	ds_read_b128 v[142:145], v150 offset:6144
	ds_read_b128 v[194:197], v150 offset:4096
	s_waitcnt vmcnt(0)
	v_add_u32_e32 v150, s45, v159
	s_waitcnt lgkmcnt(0)
	s_barrier
	ds_read_b128 v[198:201], v150
	ds_read_b128 v[202:205], v242
	ds_read_b128 v[206:209], v242 offset:2048
	v_mfma_f32_32x32x16_bf16 v[114:129], v[190:193], v[186:189], v[114:129]
	ds_read_b128 v[210:213], v214 offset:2048
	ds_read_b128 v[214:217], v214
	ds_read_b128 v[218:221], v234 offset:2048
	ds_read_b128 v[222:225], v234
	ds_read_b128 v[226:229], v150 offset:2048
	ds_read_b128 v[230:233], v234 offset:6144
	ds_read_b128 v[234:237], v234 offset:4096
	ds_read_b128 v[238:241], v242 offset:6144
	ds_read_b128 v[242:245], v242 offset:4096
	v_lshl_or_b32 v150, s8, 6, v163
	s_waitcnt lgkmcnt(0)
	s_barrier
	s_waitcnt lgkmcnt(0)
	v_mfma_f32_32x32x16_bf16 v[82:97], v[178:181], v[194:197], v[82:97]
	v_mfma_f32_32x32x16_bf16 v[114:129], v[198:201], v[202:205], v[114:129]
	v_mfma_f32_32x32x16_bf16 v[98:113], v[190:193], v[182:185], v[98:113]
	v_mfma_f32_32x32x16_bf16 v[66:81], v[178:181], v[142:145], v[66:81]
	v_mfma_f32_32x32x16_bf16 v[82:97], v[190:193], v[146:149], v[82:97]
	v_mfma_f32_32x32x16_bf16 v[114:129], v[214:217], v[222:225], v[114:129]
	v_mfma_f32_32x32x16_bf16 v[98:113], v[198:201], v[206:209], v[98:113]
	s_nop 10
	v_cvt_pk_bf16_f32 v246, v114, v115
	v_lshl_or_b32 v114, s26, 8, v173
	v_mad_u64_u32 v[114:115], s[46:47], v150, s37, v[114:115]
	v_cvt_pk_bf16_f32 v115, v116, v117
	ds_write_b16 v114, v246
	ds_write_b16_d16_hi v114, v246 offset:528
	ds_write_b16 v114, v115 offset:1056
	ds_write_b16_d16_hi v114, v115 offset:1584
	v_mfma_f32_32x32x16_bf16 v[66:81], v[190:193], v[130:133], v[66:81]
	v_cvt_pk_bf16_f32 v115, v118, v119
	ds_write_b16 v114, v115 offset:4224
	ds_write_b16_d16_hi v114, v115 offset:4752
	v_cvt_pk_bf16_f32 v115, v120, v121
	ds_write_b16 v114, v115 offset:5280
	ds_write_b16_d16_hi v114, v115 offset:5808
	v_cvt_pk_bf16_f32 v115, v122, v123
	ds_write_b16 v114, v115 offset:8448
	ds_write_b16_d16_hi v114, v115 offset:8976
	v_mfma_f32_32x32x16_bf16 v[82:97], v[198:201], v[242:245], v[82:97]
	v_cvt_pk_bf16_f32 v115, v124, v125
	ds_write_b16 v114, v115 offset:9504
	ds_write_b16_d16_hi v114, v115 offset:10032
	v_cvt_pk_bf16_f32 v115, v126, v127
	ds_write_b16 v114, v115 offset:12672
	ds_write_b16_d16_hi v114, v115 offset:13200
	v_cvt_pk_bf16_f32 v115, v128, v129
	ds_write_b16 v114, v115 offset:13728
	ds_write_b16_d16_hi v114, v115 offset:14256
	v_mfma_f32_32x32x16_bf16 v[98:113], v[214:217], v[218:221], v[98:113]
	v_mfma_f32_32x32x16_bf16 v[50:65], v[138:141], v[186:189], v[50:65]
	s_nop 10
	v_cvt_pk_bf16_f32 v98, v98, v99
	ds_write_b16 v114, v98 offset:64
	ds_write_b16_d16_hi v114, v98 offset:592
	v_cvt_pk_bf16_f32 v98, v100, v101
	ds_write_b16 v114, v98 offset:1120
	ds_write_b16_d16_hi v114, v98 offset:1648
	v_cvt_pk_bf16_f32 v98, v102, v103
	ds_write_b16 v114, v98 offset:4288
	ds_write_b16_d16_hi v114, v98 offset:4816
	v_cvt_pk_bf16_f32 v98, v104, v105
	v_mfma_f32_32x32x16_bf16 v[66:81], v[198:201], v[238:241], v[66:81]
	ds_write_b16 v114, v98 offset:5344
	ds_write_b16_d16_hi v114, v98 offset:5872
	v_cvt_pk_bf16_f32 v98, v106, v107
	ds_write_b16 v114, v98 offset:8512
	ds_write_b16_d16_hi v114, v98 offset:9040
	v_cvt_pk_bf16_f32 v98, v108, v109
	ds_write_b16 v114, v98 offset:9568
	ds_write_b16_d16_hi v114, v98 offset:10096
	v_cvt_pk_bf16_f32 v98, v110, v111
	v_mfma_f32_32x32x16_bf16 v[82:97], v[214:217], v[234:237], v[82:97]
	ds_write_b16 v114, v98 offset:12736
	ds_write_b16_d16_hi v114, v98 offset:13264
	v_cvt_pk_bf16_f32 v98, v112, v113
	ds_write_b16 v114, v98 offset:13792
	ds_write_b16_d16_hi v114, v98 offset:14320
	s_nop 6
	v_cvt_pk_bf16_f32 v82, v82, v83
	v_mfma_f32_32x32x16_bf16 v[18:33], v[134:137], v[194:197], v[18:33]
	ds_write_b16 v114, v82 offset:128
	ds_write_b16_d16_hi v114, v82 offset:656
	v_cvt_pk_bf16_f32 v82, v84, v85
	ds_write_b16 v114, v82 offset:1184
	ds_write_b16_d16_hi v114, v82 offset:1712
	v_cvt_pk_bf16_f32 v82, v86, v87
	ds_write_b16 v114, v82 offset:4352
	ds_write_b16_d16_hi v114, v82 offset:4880
	v_cvt_pk_bf16_f32 v82, v88, v89
	v_mfma_f32_32x32x16_bf16 v[34:49], v[138:141], v[182:185], v[34:49]
	ds_write_b16 v114, v82 offset:5408
	ds_write_b16_d16_hi v114, v82 offset:5936
	v_cvt_pk_bf16_f32 v82, v90, v91
	ds_write_b16 v114, v82 offset:8576
	ds_write_b16_d16_hi v114, v82 offset:9104
	v_cvt_pk_bf16_f32 v82, v92, v93
	ds_write_b16 v114, v82 offset:9632
	ds_write_b16_d16_hi v114, v82 offset:10160
	v_cvt_pk_bf16_f32 v82, v94, v95
	ds_write_b16 v114, v82 offset:12800
	ds_write_b16_d16_hi v114, v82 offset:13328
; DI unsigned pk2(float a, float b) { fl2_t f = {a, b}; bf2_t r = __builtin_convertvector(f, bf2_t); return __builtin_bit_cast(unsigned, r); }
; template <typename FA, typename FB, typename FE>
; DI void gemm_tile(char* lds, int K, int astride, int bstride, FA arow, FB brow, FE epi) {
;     ...
;   for (int mt = 0; mt < 2; ++mt)
; #pragma unroll
;     for (int nt = 0; nt < 4; ++nt)
; #pragma unroll
;       for (int i = 0; i < 16; i += 2) {
;         const int row = wm * 64 + mt * 32 + (i & 3) + 8 * (i >> 2) + 4 * h8;
;         const unsigned pr = pk2(acc[mt][nt][i], acc[mt][nt][i + 1]);
;         Cs[row * CSS + wn * 128 + nt * 32 + r] = (bfr)(pr & 0xffffu);
;         Cs[(row + 1) * CSS + wn * 128 + nt * 32 + r] = (bfr)(pr >> 16);
;       }
;   __syncthreads();
; DI void phase2(const Params& p, char* lds) {
;     ...
;     if (nt < 8) {
	v_mfma_f32_32x32x16_bf16 v[50:65], v[226:229], v[202:205], v[50:65]
	v_cvt_pk_bf16_f32 v82, v96, v97
	ds_write_b16 v114, v82 offset:13856
	ds_write_b16_d16_hi v114, v82 offset:14384
	v_mfma_f32_32x32x16_bf16 v[66:81], v[214:217], v[230:233], v[66:81]
	v_mfma_f32_32x32x16_bf16 v[2:17], v[134:137], v[142:145], v[2:17]
	s_nop 10
	v_cvt_pk_bf16_f32 v66, v66, v67
	ds_write_b16 v114, v66 offset:192
	ds_write_b16_d16_hi v114, v66 offset:720
	v_cvt_pk_bf16_f32 v66, v68, v69
	ds_write_b16 v114, v66 offset:1248
	ds_write_b16_d16_hi v114, v66 offset:1776
	v_cvt_pk_bf16_f32 v66, v70, v71
	ds_write_b16 v114, v66 offset:4416
	ds_write_b16_d16_hi v114, v66 offset:4944
	v_mfma_f32_32x32x16_bf16 v[18:33], v[138:141], v[146:149], v[18:33]
	v_cvt_pk_bf16_f32 v66, v72, v73
	ds_write_b16 v114, v66 offset:5472
	ds_write_b16_d16_hi v114, v66 offset:6000
	v_cvt_pk_bf16_f32 v66, v74, v75
	ds_write_b16 v114, v66 offset:8640
	ds_write_b16_d16_hi v114, v66 offset:9168
	v_cvt_pk_bf16_f32 v66, v76, v77
	ds_write_b16 v114, v66 offset:9696
	ds_write_b16_d16_hi v114, v66 offset:10224
	v_cvt_pk_bf16_f32 v66, v78, v79
	v_mfma_f32_32x32x16_bf16 v[34:49], v[226:229], v[206:209], v[34:49]
	ds_write_b16 v114, v66 offset:12864
	ds_write_b16_d16_hi v114, v66 offset:13392
	v_cvt_pk_bf16_f32 v66, v80, v81
	ds_write_b16 v114, v66 offset:13920
	ds_write_b16_d16_hi v114, v66 offset:14448
	v_mfma_f32_32x32x16_bf16 v[50:65], v[210:213], v[222:225], v[50:65]
	v_mfma_f32_32x32x16_bf16 v[2:17], v[138:141], v[130:133], v[2:17]
	s_nop 10
	v_cvt_pk_bf16_f32 v50, v50, v51
	ds_write_b16 v114, v50 offset:16896
	ds_write_b16_d16_hi v114, v50 offset:17424
	v_cvt_pk_bf16_f32 v50, v52, v53
	ds_write_b16 v114, v50 offset:17952
	ds_write_b16_d16_hi v114, v50 offset:18480
	v_cvt_pk_bf16_f32 v50, v54, v55
	ds_write_b16 v114, v50 offset:21120
	ds_write_b16_d16_hi v114, v50 offset:21648
	v_mfma_f32_32x32x16_bf16 v[18:33], v[226:229], v[242:245], v[18:33]
	v_cvt_pk_bf16_f32 v50, v56, v57
	ds_write_b16 v114, v50 offset:22176
	ds_write_b16_d16_hi v114, v50 offset:22704
	v_cvt_pk_bf16_f32 v50, v58, v59
	ds_write_b16 v114, v50 offset:25344
	ds_write_b16_d16_hi v114, v50 offset:25872
	v_cvt_pk_bf16_f32 v50, v60, v61
	ds_write_b16 v114, v50 offset:26400
	ds_write_b16_d16_hi v114, v50 offset:26928
	v_cvt_pk_bf16_f32 v50, v62, v63
	v_mfma_f32_32x32x16_bf16 v[34:49], v[210:213], v[218:221], v[34:49]
	ds_write_b16 v114, v50 offset:29568
	ds_write_b16_d16_hi v114, v50 offset:30096
	v_cvt_pk_bf16_f32 v50, v64, v65
	ds_write_b16 v114, v50 offset:30624
	ds_write_b16_d16_hi v114, v50 offset:31152
	s_nop 6
	v_cvt_pk_bf16_f32 v34, v34, v35
	v_mfma_f32_32x32x16_bf16 v[2:17], v[226:229], v[238:241], v[2:17]
	ds_write_b16 v114, v34 offset:16960
	ds_write_b16_d16_hi v114, v34 offset:17488
	v_cvt_pk_bf16_f32 v34, v36, v37
	ds_write_b16 v114, v34 offset:18016
	ds_write_b16_d16_hi v114, v34 offset:18544
	v_cvt_pk_bf16_f32 v34, v38, v39
	ds_write_b16 v114, v34 offset:21184
	ds_write_b16_d16_hi v114, v34 offset:21712
	v_cvt_pk_bf16_f32 v34, v40, v41
	ds_write_b16 v114, v34 offset:22240
	ds_write_b16_d16_hi v114, v34 offset:22768
	v_mfma_f32_32x32x16_bf16 v[18:33], v[210:213], v[234:237], v[18:33]
	v_cvt_pk_bf16_f32 v34, v42, v43
	ds_write_b16 v114, v34 offset:25408
	ds_write_b16_d16_hi v114, v34 offset:25936
	v_cvt_pk_bf16_f32 v34, v44, v45
	ds_write_b16 v114, v34 offset:26464
	ds_write_b16_d16_hi v114, v34 offset:26992
	v_cvt_pk_bf16_f32 v34, v46, v47
	ds_write_b16 v114, v34 offset:29632
	ds_write_b16_d16_hi v114, v34 offset:30160
	v_mfma_f32_32x32x16_bf16 v[2:17], v[210:213], v[230:233], v[2:17]
	v_cvt_pk_bf16_f32 v34, v48, v49
	s_nop 0
	v_cvt_pk_bf16_f32 v18, v18, v19
	ds_write_b16 v114, v34 offset:30688
	ds_write_b16_d16_hi v114, v34 offset:31216
	ds_write_b16 v114, v18 offset:17024
	ds_write_b16_d16_hi v114, v18 offset:17552
	v_cvt_pk_bf16_f32 v18, v20, v21
	ds_write_b16 v114, v18 offset:18080
	ds_write_b16_d16_hi v114, v18 offset:18608
	v_cvt_pk_bf16_f32 v18, v22, v23
	ds_write_b16 v114, v18 offset:21248
	ds_write_b16_d16_hi v114, v18 offset:21776
	v_cvt_pk_bf16_f32 v18, v24, v25
	ds_write_b16 v114, v18 offset:22304
	ds_write_b16_d16_hi v114, v18 offset:22832
	v_cvt_pk_bf16_f32 v18, v26, v27
	ds_write_b16 v114, v18 offset:25472
	ds_write_b16_d16_hi v114, v18 offset:26000
	v_cvt_pk_bf16_f32 v18, v28, v29
	ds_write_b16 v114, v18 offset:26528
	ds_write_b16_d16_hi v114, v18 offset:27056
	v_cvt_pk_bf16_f32 v18, v30, v31
	ds_write_b16 v114, v18 offset:29696
	ds_write_b16_d16_hi v114, v18 offset:30224
	v_cvt_pk_bf16_f32 v18, v32, v33
	v_cvt_pk_bf16_f32 v2, v2, v3
	ds_write_b16 v114, v18 offset:30752
	ds_write_b16_d16_hi v114, v18 offset:31280
	ds_write_b16 v114, v2 offset:17088
	ds_write_b16_d16_hi v114, v2 offset:17616
	v_cvt_pk_bf16_f32 v2, v4, v5
	ds_write_b16 v114, v2 offset:18144
	ds_write_b16_d16_hi v114, v2 offset:18672
	v_cvt_pk_bf16_f32 v2, v6, v7
	ds_write_b16 v114, v2 offset:21312
	ds_write_b16_d16_hi v114, v2 offset:21840
	v_cvt_pk_bf16_f32 v2, v8, v9
	ds_write_b16 v114, v2 offset:22368
	ds_write_b16_d16_hi v114, v2 offset:22896
	v_cvt_pk_bf16_f32 v2, v10, v11
	ds_write_b16 v114, v2 offset:25536
	ds_write_b16_d16_hi v114, v2 offset:26064
	v_cvt_pk_bf16_f32 v2, v12, v13
	ds_write_b16 v114, v2 offset:26592
	ds_write_b16_d16_hi v114, v2 offset:27120
	v_cvt_pk_bf16_f32 v2, v14, v15
	ds_write_b16 v114, v2 offset:29760
	ds_write_b16_d16_hi v114, v2 offset:30288
	v_cvt_pk_bf16_f32 v2, v16, v17
	v_add_u32_e32 v48, s27, v164
	s_mov_b64 s[26:27], -1
	ds_write_b16 v114, v2 offset:30816
	ds_write_b16_d16_hi v114, v2 offset:31344
	s_waitcnt vmcnt(0) lgkmcnt(0)
	s_barrier
	s_cbranch_scc1 .LBB0_125
	v_or_b32_e32 v150, v48, v165
	s_andn2_b64 vcc, exec, s[26:27]
	v_lshlrev_b32_e32 v49, 6, v150
	s_cbranch_vccz .LBB0_130

; #define MFMA(a, b, c) __builtin_amdgcn_mfma_f32_32x32x16_bf16((a), (b), (c), 0, 0, 0)
; #define WAIT_V(n) asm volatile("s_waitcnt vmcnt(%0)" ::"n"(n) : "memory")
; #define RAW_BARRIER() do { asm volatile("s_waitcnt lgkmcnt(0)" ::: "memory"); __builtin_amdgcn_s_barrier(); } while (0)
; DI void attn_item(const Params& p, char* lds, int S, const bfr* Qb, const bfr* Kb, const bfr* Vtb, int h, int q0, int tok0) {
;     ...
;   const char* qimg = lds + w * 8192;
; #pragma unroll 8
;   for (int kt = 0; kt < nkt; ++kt) {
;     if (kt + 2 < nkt) WAIT_V(4); else if (kt + 1 < nkt) WAIT_V(2); else WAIT_V(0);
;     RAW_BARRIER();
;     if (kt + 3 < nkt) stage((kt + 3) & 3, kt + 3);
;     const char* sb = lds + 65536 + (kt & 3) * 16384;
;     const char* kimg = sb + c * 4096;
;     const char* vimg = sb + 8192;
;     f32x16 st[2];
;     {
;       bf16x8 kf[4];
; #pragma unroll
;       for (int ks = 0; ks < 4; ++ks) kf[ks] = *(const bf16x8*)(kimg + voffK[ks]);
; #pragma unroll
;       for (int t = 0; t < 2; ++t) {
;         const float negm = -m[t];
; #pragma unroll
;         for (int i = 0; i < 16; ++i) st[t][i] = negm;
; #pragma unroll
;         for (int ks = 0; ks < 4; ++ks) st[t] = MFMA(kf[ks], *(const bf16x8*)(qimg + t * 4096 + voffK[ks]), st[t]);
;       }
;     }
; #pragma unroll
;     for (int t = 0; t < 2; ++t) {
;       float mx = st[t][0];
; #pragma unroll
;       for (int i = 1; i < 16; ++i) mx = fmaxf(mx, st[t][i]);
;       mx = fmaxf(mx, __shfl_xor(mx, 32, 64));
;       if (__any(mx > 6.f)) {
;         const float d = fmaxf(mx, 0.f);
;         const float alpha = __builtin_amdgcn_exp2f(-d);
;         m[t] += d;
;         l[t] *= alpha;
; #pragma unroll
;         for (int i = 0; i < 16; ++i) st[t][i] -= d;
; #pragma unroll
;         for (int e = 0; e < 4; ++e)
; #pragma unroll
;           for (int i = 0; i < 16; ++i) O[t][e][i] *= alpha;
;       }
;     }
;     __builtin_amdgcn_iglp_opt(0);
; #pragma unroll
;     for (int t = 0; t < 2; ++t) {
;       float rs = 0.f;
; #pragma unroll
;       for (int i = 0; i < 16; ++i) { float pv = __builtin_amdgcn_exp2f(st[t][i]); st[t][i] = pv; rs += pv; }
.Lfa_entry:
	s_waitcnt vmcnt(4)
	s_waitcnt lgkmcnt(0)
	s_barrier
	s_mov_b32 s5, 0x10000
	s_or_b32 s5, s5, s3
	ds_read_b128 v[192:195], v185
	ds_read_b128 v[196:199], v184
	ds_read_b128 v[218:221], v183
	v_add_u32_e32 v200, s5, v203
	ds_read_b128 v[168:171], v200
	v_add_u32_e32 v200, s5, v204
	ds_read_b128 v[172:175], v200
	v_add_u32_e32 v200, s5, v205
	ds_read_b128 v[176:179], v200
	v_add_u32_e32 v200, s5, v206
	ds_read_b128 v[188:191], v200
	s_waitcnt lgkmcnt(3)
	v_mfma_f32_32x32x16_bf16 v[132:147], v[168:171], v[192:195], 0
	ds_read_b128 v[192:195], v182
	s_waitcnt lgkmcnt(3)
	v_mfma_f32_32x32x16_bf16 v[132:147], v[172:175], v[196:199], v[132:147]
	ds_read_b128 v[196:199], v185 offset:4096
	s_waitcnt lgkmcnt(3)
	v_mfma_f32_32x32x16_bf16 v[132:147], v[176:179], v[218:221], v[132:147]
	ds_read_b128 v[218:221], v184 offset:4096
	s_waitcnt lgkmcnt(2)
	v_mfma_f32_32x32x16_bf16 v[132:147], v[188:191], v[192:195], v[132:147]
	ds_read_b128 v[192:195], v183 offset:4096
	s_nop 15
	v_exp_f32_e32 v132, v132
	v_exp_f32_e32 v133, v133
	v_exp_f32_e32 v134, v134
	v_exp_f32_e32 v135, v135
	v_exp_f32_e32 v136, v136
	v_exp_f32_e32 v137, v137
	v_exp_f32_e32 v138, v138
	v_exp_f32_e32 v139, v139
	.p2align 6
; DI void attn_item(const Params& p, char* lds, int S, const bfr* Qb, const bfr* Kb, const bfr* Vtb, int h, int q0, int tok0) {
;     ...
;   for (int kt = 0; kt < nkt; ++kt) {
;     if (kt + 2 < nkt) WAIT_V(4); else if (kt + 1 < nkt) WAIT_V(2); else WAIT_V(0);
;     RAW_BARRIER();
;     if (kt + 3 < nkt) stage((kt + 3) & 3, kt + 3);
;     const char* sb = lds + 65536 + (kt & 3) * 16384;
;     const char* kimg = sb + c * 4096;
;     const char* vimg = sb + 8192;
;     f32x16 st[2];
;     {
;       bf16x8 kf[4];
; #pragma unroll
;       for (int ks = 0; ks < 4; ++ks) kf[ks] = *(const bf16x8*)(kimg + voffK[ks]);
; #pragma unroll
;       for (int t = 0; t < 2; ++t) {
;         const float negm = -m[t];
; #pragma unroll
;         for (int i = 0; i < 16; ++i) st[t][i] = negm;
; #pragma unroll
;         for (int ks = 0; ks < 4; ++ks) st[t] = MFMA(kf[ks], *(const bf16x8*)(qimg + t * 4096 + voffK[ks]), st[t]);
;       }
;     }
; #pragma unroll
;     for (int t = 0; t < 2; ++t) {
;       float mx = st[t][0];
; #pragma unroll
;       for (int i = 1; i < 16; ++i) mx = fmaxf(mx, st[t][i]);
;       mx = fmaxf(mx, __shfl_xor(mx, 32, 64));
;       if (__any(mx > 6.f)) {
;         const float d = fmaxf(mx, 0.f);
;         const float alpha = __builtin_amdgcn_exp2f(-d);
;         m[t] += d;
;         l[t] *= alpha;
; #pragma unroll
;         for (int i = 0; i < 16; ++i) st[t][i] -= d;
; #pragma unroll
;         for (int e = 0; e < 4; ++e)
; #pragma unroll
;           for (int i = 0; i < 16; ++i) O[t][e][i] *= alpha;
;       }
;     }
;     __builtin_amdgcn_iglp_opt(0);
; #pragma unroll
;     for (int t = 0; t < 2; ++t) {
;       float rs = 0.f;
; #pragma unroll
;       for (int i = 0; i < 16; ++i) { float pv = __builtin_amdgcn_exp2f(st[t][i]); st[t][i] = pv; rs += pv; }
;       l[t] += rs;
;       bf16x8 pf[2];
; #pragma unroll
;       for (int kc = 0; kc < 2; ++kc) {
;         u32x4 pp;
;         pp[0] = pk2(st[t][kc * 8 + 0], st[t][kc * 8 + 1]); pp[1] = pk2(st[t][kc * 8 + 2], st[t][kc * 8 + 3]);
;         pp[2] = pk2(st[t][kc * 8 + 4], st[t][kc * 8 + 5]); pp[3] = pk2(st[t][kc * 8 + 6], st[t][kc * 8 + 7]);
;         pf[kc] = __builtin_bit_cast(bf16x8, pp);
;       }
; #pragma unroll
;       for (int e = 0; e < 4; ++e)
; #pragma unroll
;         for (int kc = 0; kc < 2; ++kc) O[t][e] = MFMA(*(const bf16x8*)(vimg + e * 2048 + (voffV0 ^ (kc << 5))), pf[kc], O[t][e]);
;     }
.Lfa_loop:
	s_add_i32 s4, s0, 0xc000
	s_and_b32 s4, s4, 0xc000
	s_add_i32 s4, s58, s4
	s_waitcnt vmcnt(2)
	s_add_i32 s5, s4, 0x2000
	s_mov_b32 m0, s4
	s_barrier
	s_waitcnt lgkmcnt(2)
	v_mfma_f32_32x32x16_bf16 v[148:163], v[168:171], v[196:199], 0
	global_load_lds_dwordx4 v[164:165], off
	s_mov_b32 m0, s5
	s_and_b32 s4, s0, 0xc000
	global_load_lds_dwordx4 v[166:167], off
	ds_read_b128 v[196:199], v182 offset:4096
	s_bitset1_b32 s4, 16
	v_add_u32_e32 v255, s4, v209
	v_add_u32_e32 v254, s4, v210
	v_add_f32_e32 v180, v180, v132
	v_add_f32_e32 v180, v180, v133
	v_add_f32_e32 v180, v180, v134
	v_add_f32_e32 v180, v180, v135
	s_waitcnt lgkmcnt(2)
	v_mfma_f32_32x32x16_bf16 v[148:163], v[172:175], v[218:221], v[148:163]
	ds_read_b128 v[226:229], v255 offset:8192
	ds_read_b128 v[234:237], v255 offset:10240
	ds_read_b128 v[242:245], v255 offset:12288
	v_add_f32_e32 v180, v180, v136
	v_add_f32_e32 v180, v180, v137
	v_cvt_pk_bf16_f32 v132, v132, v133
	v_cvt_pk_bf16_f32 v133, v134, v135
	v_cvt_pk_bf16_f32 v134, v136, v137
	v_cvt_pk_bf16_f32 v135, v138, v139
	s_waitcnt lgkmcnt(4)
	v_mfma_f32_32x32x16_bf16 v[148:163], v[176:179], v[192:195], v[148:163]
	ds_read_b128 v[250:253], v255 offset:14336
	ds_read_b128 v[230:233], v254 offset:8192
	v_add_f32_e32 v180, v180, v138
	ds_read_b128 v[238:241], v254 offset:10240
	v_add_f32_e32 v180, v180, v139
	v_exp_f32_e32 v140, v140
	v_lshl_add_u64 v[164:165], v[164:165], 0, s[50:51]
	v_exp_f32_e32 v141, v141
	s_waitcnt lgkmcnt(6)
	v_mfma_f32_32x32x16_bf16 v[148:163], v[188:191], v[196:199], v[148:163]
	ds_read_b128 v[246:249], v254 offset:12288
	ds_read_b128 v[222:225], v254 offset:14336
	v_exp_f32_e32 v142, v142
	v_exp_f32_e32 v143, v143
	v_lshl_add_u64 v[166:167], v[166:167], 0, s[52:53]
	s_add_i32 s5, s0, 0x4000
	s_and_b32 s5, s5, 0xc000
	s_bitset1_b32 s5, 16
	s_or_b32 s5, s5, s3
	s_waitcnt lgkmcnt(7)
	v_exp_f32_e32 v144, v144
	v_mfma_f32_32x32x16_bf16 v[116:131], v[226:229], v[132:135], v[116:131]
	v_exp_f32_e32 v145, v145
	v_add_f32_e32 v180, v180, v140
	v_add_u32_e32 v200, s5, v203
	ds_read_b128 v[168:171], v200
	s_waitcnt lgkmcnt(7)
	v_mfma_f32_32x32x16_bf16 v[100:115], v[234:237], v[132:135], v[100:115]
	v_exp_f32_e32 v146, v146
	v_exp_f32_e32 v147, v147
	v_add_f32_e32 v180, v180, v141
	v_add_u32_e32 v200, s5, v204
	ds_read_b128 v[172:175], v200
	s_waitcnt lgkmcnt(7)
	v_add_f32_e32 v180, v180, v142
	v_mfma_f32_32x32x16_bf16 v[84:99], v[242:245], v[132:135], v[84:99]
	v_add_f32_e32 v180, v180, v143
	v_add_f32_e32 v180, v180, v144
	v_add_f32_e32 v180, v180, v145
	v_add_u32_e32 v200, s5, v205
	ds_read_b128 v[176:179], v200
	s_waitcnt lgkmcnt(7)
	v_mfma_f32_32x32x16_bf16 v[68:83], v[250:253], v[132:135], v[68:83]
	v_cvt_pk_bf16_f32 v140, v140, v141
	v_cvt_pk_bf16_f32 v141, v142, v143
	v_cvt_pk_bf16_f32 v142, v144, v145
	v_add_f32_e32 v180, v180, v146
	v_cvt_pk_bf16_f32 v143, v146, v147
	v_add_f32_e32 v180, v180, v147
	v_add_u32_e32 v200, s5, v206
	ds_read_b128 v[188:191], v200
	s_waitcnt lgkmcnt(7)
	v_exp_f32_e32 v148, v148
	v_mfma_f32_32x32x16_bf16 v[116:131], v[230:233], v[140:143], v[116:131]
	v_exp_f32_e32 v149, v149
	v_exp_f32_e32 v150, v150
	s_waitcnt lgkmcnt(6)
	v_exp_f32_e32 v151, v151
	v_mfma_f32_32x32x16_bf16 v[100:115], v[238:241], v[140:143], v[100:115]
	v_add_f32_e32 v181, v181, v148
	v_exp_f32_e32 v152, v152
	v_add_f32_e32 v181, v181, v149
	v_exp_f32_e32 v153, v153
	s_waitcnt lgkmcnt(5)
	v_add_f32_e32 v181, v181, v150
	v_mfma_f32_32x32x16_bf16 v[84:99], v[246:249], v[140:143], v[84:99]
	v_exp_f32_e32 v154, v154
	v_add_f32_e32 v181, v181, v151
	v_exp_f32_e32 v155, v155
	v_add_f32_e32 v181, v181, v152
	v_add_f32_e32 v181, v181, v153
	s_waitcnt lgkmcnt(4)
	v_mfma_f32_32x32x16_bf16 v[68:83], v[222:225], v[140:143], v[68:83]
	v_cvt_pk_bf16_f32 v148, v148, v149
	v_cvt_pk_bf16_f32 v149, v150, v151
	v_cvt_pk_bf16_f32 v150, v152, v153
	v_cvt_pk_bf16_f32 v151, v154, v155
	v_add_f32_e32 v181, v181, v154
	v_add_f32_e32 v181, v181, v155
	v_mfma_f32_32x32x16_bf16 v[52:67], v[226:229], v[148:151], v[52:67]
	v_exp_f32_e32 v156, v156
	v_exp_f32_e32 v157, v157
	ds_read_b128 v[192:195], v185
	v_mfma_f32_32x32x16_bf16 v[36:51], v[234:237], v[148:151], v[36:51]
	v_exp_f32_e32 v158, v158
	v_exp_f32_e32 v159, v159
	ds_read_b128 v[196:199], v184
	v_mfma_f32_32x32x16_bf16 v[20:35], v[242:245], v[148:151], v[20:35]
	v_exp_f32_e32 v160, v160
	v_exp_f32_e32 v161, v161
	ds_read_b128 v[218:221], v183
	v_mfma_f32_32x32x16_bf16 v[4:19], v[250:253], v[148:151], v[4:19]
	v_add_f32_e32 v181, v181, v156
	v_exp_f32_e32 v162, v162
	v_exp_f32_e32 v163, v163
	v_add_f32_e32 v181, v181, v157
	s_waitcnt lgkmcnt(2)
	v_mfma_f32_32x32x16_bf16 v[132:147], v[168:171], v[192:195], 0
	v_add_f32_e32 v181, v181, v158
	ds_read_b128 v[192:195], v182
	v_add_f32_e32 v181, v181, v159
	v_add_f32_e32 v181, v181, v160
	v_add_f32_e32 v181, v181, v161
	s_waitcnt lgkmcnt(2)
	v_mfma_f32_32x32x16_bf16 v[132:147], v[172:175], v[196:199], v[132:147]
	v_cvt_pk_bf16_f32 v156, v156, v157
	v_cvt_pk_bf16_f32 v157, v158, v159
	v_cvt_pk_bf16_f32 v158, v160, v161
	v_cvt_pk_bf16_f32 v159, v162, v163
	v_add_f32_e32 v181, v181, v162
	v_add_f32_e32 v181, v181, v163
	ds_read_b128 v[196:199], v185 offset:4096
	s_waitcnt lgkmcnt(2)
	v_mfma_f32_32x32x16_bf16 v[132:147], v[176:179], v[218:221], v[132:147]
	s_add_i32 s1, s1, 1
	ds_read_b128 v[218:221], v184 offset:4096
	s_addk_i32 s0, 0x4000
	s_waitcnt lgkmcnt(2)
	v_mfma_f32_32x32x16_bf16 v[132:147], v[188:191], v[192:195], v[132:147]
	ds_read_b128 v[192:195], v183 offset:4096
	v_mfma_f32_32x32x16_bf16 v[52:67], v[230:233], v[156:159], v[52:67]
	s_nop 3
	v_mfma_f32_32x32x16_bf16 v[36:51], v[238:241], v[156:159], v[36:51]
	s_nop 3
	v_mfma_f32_32x32x16_bf16 v[20:35], v[246:249], v[156:159], v[20:35]
	v_exp_f32_e32 v132, v132
	v_exp_f32_e32 v133, v133
	v_exp_f32_e32 v134, v134
	v_exp_f32_e32 v135, v135
	v_mfma_f32_32x32x16_bf16 v[4:19], v[222:225], v[156:159], v[4:19]
	v_exp_f32_e32 v136, v136
	v_exp_f32_e32 v137, v137
	v_exp_f32_e32 v138, v138
	v_exp_f32_e32 v139, v139
	s_cmp_eq_u32 s38, s1
	s_cbranch_scc0 .Lfa_loop
	v_mov_b32_e32 v186, 0
	v_mov_b32_e32 v187, 0
	v_cmp_lt_i32_e32 vcc, v213, v214
	s_nop 1
	v_cndmask_b32_e32 v2, v212, v213, vcc
	v_lshlrev_b32_e32 v216, 2, v2
	s_branch .LBB0_165

; DI void conv_item(const Params& p, char* lds, int t0, int tid) {
;     ...
;   for (int idx = tid; idx < 62 * 64; idx += 256) {
;     const int row = idx >> 6, c16 = idx & 63;
;     const int s = s0 - 15 + row;
;     u32x4 v = {0u, 0u, 0u, 0u};
;     if (s >= 0 && s < S) v = *(const u32x4*)(Z + (size_t)(t0 - 15 + row) * 512 + c16 * 8);
;     *(u32x4*)(zl + row * 256 + c16 * 4) = v;
;   }
.LBB0_192:
	v_cmp_lt_u32_e32 vcc, v9, v8
	v_mov_b32_e32 v84, 0
	v_mov_b32_e32 v85, 0
	v_mov_b32_e32 v86, 0
	v_mov_b32_e32 v87, 0
	s_and_saveexec_b64 s[8:9], vcc
	v_ashrrev_i32_e32 v3, 31, v6
	v_mov_b32_e32 v2, v6
	v_lshlrev_b64 v[2:3], 10, v[2:3]
	v_lshl_add_u64 v[2:3], v[10:11], 0, v[2:3]
	global_load_dwordx4 v[84:87], v[2:3], off
	s_or_b64 exec, exec, s[8:9]
	v_add_u32_e32 v2, 4, v9
	v_cmp_lt_u32_e32 vcc, v2, v8
	v_mov_b32_e32 v88, 0
	v_mov_b32_e32 v89, 0
	v_mov_b32_e32 v90, 0
	v_mov_b32_e32 v91, 0
	s_and_saveexec_b64 s[8:9], vcc
	v_add_u32_e32 v2, 4, v6
	v_ashrrev_i32_e32 v3, 31, v2
	v_lshlrev_b64 v[2:3], 10, v[2:3]
	v_lshl_add_u64 v[2:3], v[10:11], 0, v[2:3]
	global_load_dwordx4 v[88:91], v[2:3], off
	s_or_b64 exec, exec, s[8:9]
	v_add_u32_e32 v2, 8, v9
	v_cmp_lt_u32_e32 vcc, v2, v8
	v_mov_b32_e32 v92, 0
	v_mov_b32_e32 v93, 0
	v_mov_b32_e32 v94, 0
	v_mov_b32_e32 v95, 0
	s_and_saveexec_b64 s[8:9], vcc
	v_add_u32_e32 v2, 8, v6
	v_ashrrev_i32_e32 v3, 31, v2
	v_lshlrev_b64 v[2:3], 10, v[2:3]
	v_lshl_add_u64 v[2:3], v[10:11], 0, v[2:3]
	global_load_dwordx4 v[92:95], v[2:3], off
	s_or_b64 exec, exec, s[8:9]
	v_add_u32_e32 v2, 12, v9
	v_cmp_lt_u32_e32 vcc, v2, v8
	v_mov_b32_e32 v96, 0
	v_mov_b32_e32 v97, 0
	v_mov_b32_e32 v98, 0
	v_mov_b32_e32 v99, 0
	s_and_saveexec_b64 s[8:9], vcc
	v_add_u32_e32 v2, 12, v6
	v_ashrrev_i32_e32 v3, 31, v2
	v_lshlrev_b64 v[2:3], 10, v[2:3]
	v_lshl_add_u64 v[2:3], v[10:11], 0, v[2:3]
	global_load_dwordx4 v[96:99], v[2:3], off
	s_or_b64 exec, exec, s[8:9]
	v_add_u32_e32 v2, 16, v9
	v_cmp_lt_u32_e32 vcc, v2, v8
	v_mov_b32_e32 v100, 0
	v_mov_b32_e32 v101, 0
	v_mov_b32_e32 v102, 0
	v_mov_b32_e32 v103, 0
	s_and_saveexec_b64 s[8:9], vcc
	v_add_u32_e32 v2, 16, v6
	v_ashrrev_i32_e32 v3, 31, v2
	v_lshlrev_b64 v[2:3], 10, v[2:3]
	v_lshl_add_u64 v[2:3], v[10:11], 0, v[2:3]
	global_load_dwordx4 v[100:103], v[2:3], off
	s_or_b64 exec, exec, s[8:9]
	v_add_u32_e32 v2, 20, v9
	v_cmp_lt_u32_e32 vcc, v2, v8
	v_mov_b32_e32 v104, 0
	v_mov_b32_e32 v105, 0
	v_mov_b32_e32 v106, 0
	v_mov_b32_e32 v107, 0
	s_and_saveexec_b64 s[8:9], vcc
	v_add_u32_e32 v2, 20, v6
	v_ashrrev_i32_e32 v3, 31, v2
	v_lshlrev_b64 v[2:3], 10, v[2:3]
	v_lshl_add_u64 v[2:3], v[10:11], 0, v[2:3]
	global_load_dwordx4 v[104:107], v[2:3], off
	s_or_b64 exec, exec, s[8:9]
	v_add_u32_e32 v2, 24, v9
	v_cmp_lt_u32_e32 vcc, v2, v8
	v_mov_b32_e32 v108, 0
	v_mov_b32_e32 v109, 0
	v_mov_b32_e32 v110, 0
	v_mov_b32_e32 v111, 0
	s_and_saveexec_b64 s[8:9], vcc
	v_add_u32_e32 v2, 24, v6
	v_ashrrev_i32_e32 v3, 31, v2
	v_lshlrev_b64 v[2:3], 10, v[2:3]
	v_lshl_add_u64 v[2:3], v[10:11], 0, v[2:3]
	global_load_dwordx4 v[108:111], v[2:3], off
	s_or_b64 exec, exec, s[8:9]
	v_add_u32_e32 v2, 28, v9
	v_cmp_lt_u32_e32 vcc, v2, v8
	v_mov_b32_e32 v112, 0
	v_mov_b32_e32 v113, 0
	v_mov_b32_e32 v114, 0
	v_mov_b32_e32 v115, 0
	s_and_saveexec_b64 s[8:9], vcc
	v_add_u32_e32 v2, 28, v6
	v_ashrrev_i32_e32 v3, 31, v2
	v_lshlrev_b64 v[2:3], 10, v[2:3]
	v_lshl_add_u64 v[2:3], v[10:11], 0, v[2:3]
	global_load_dwordx4 v[112:115], v[2:3], off
	s_or_b64 exec, exec, s[8:9]
	v_add_u32_e32 v2, 32, v9
	v_cmp_lt_u32_e32 vcc, v2, v8
	v_mov_b32_e32 v116, 0
	v_mov_b32_e32 v117, 0
	v_mov_b32_e32 v118, 0
	v_mov_b32_e32 v119, 0
	s_and_saveexec_b64 s[8:9], vcc
	v_add_u32_e32 v2, 32, v6
	v_ashrrev_i32_e32 v3, 31, v2
	v_lshlrev_b64 v[2:3], 10, v[2:3]
	v_lshl_add_u64 v[2:3], v[10:11], 0, v[2:3]
	global_load_dwordx4 v[116:119], v[2:3], off
	s_or_b64 exec, exec, s[8:9]
	v_add_u32_e32 v2, 36, v9
	v_cmp_lt_u32_e32 vcc, v2, v8
	v_mov_b32_e32 v120, 0
	v_mov_b32_e32 v121, 0
	v_mov_b32_e32 v122, 0
	v_mov_b32_e32 v123, 0
	s_and_saveexec_b64 s[8:9], vcc
	v_add_u32_e32 v2, 36, v6
	v_ashrrev_i32_e32 v3, 31, v2
	v_lshlrev_b64 v[2:3], 10, v[2:3]
	v_lshl_add_u64 v[2:3], v[10:11], 0, v[2:3]
	global_load_dwordx4 v[120:123], v[2:3], off
	s_or_b64 exec, exec, s[8:9]
	v_add_u32_e32 v2, 40, v9
	v_cmp_lt_u32_e32 vcc, v2, v8
	v_mov_b32_e32 v124, 0
	v_mov_b32_e32 v125, 0
	v_mov_b32_e32 v126, 0
	v_mov_b32_e32 v127, 0
	s_and_saveexec_b64 s[8:9], vcc
	v_add_u32_e32 v2, 40, v6
	v_ashrrev_i32_e32 v3, 31, v2
	v_lshlrev_b64 v[2:3], 10, v[2:3]
	v_lshl_add_u64 v[2:3], v[10:11], 0, v[2:3]
	global_load_dwordx4 v[124:127], v[2:3], off
	s_or_b64 exec, exec, s[8:9]
	v_add_u32_e32 v2, 44, v9
	v_cmp_lt_u32_e32 vcc, v2, v8
	v_mov_b32_e32 v128, 0
	v_mov_b32_e32 v129, 0
	v_mov_b32_e32 v130, 0
	v_mov_b32_e32 v131, 0
	s_and_saveexec_b64 s[8:9], vcc
	v_add_u32_e32 v2, 44, v6
	v_ashrrev_i32_e32 v3, 31, v2
	v_lshlrev_b64 v[2:3], 10, v[2:3]
	v_lshl_add_u64 v[2:3], v[10:11], 0, v[2:3]
	global_load_dwordx4 v[128:131], v[2:3], off
	s_or_b64 exec, exec, s[8:9]
	v_add_u32_e32 v2, 48, v9
	v_cmp_lt_u32_e32 vcc, v2, v8
	v_mov_b32_e32 v132, 0
	v_mov_b32_e32 v133, 0
	v_mov_b32_e32 v134, 0
	v_mov_b32_e32 v135, 0
	s_and_saveexec_b64 s[8:9], vcc
	v_add_u32_e32 v2, 48, v6
	v_ashrrev_i32_e32 v3, 31, v2
	v_lshlrev_b64 v[2:3], 10, v[2:3]
	v_lshl_add_u64 v[2:3], v[10:11], 0, v[2:3]
	global_load_dwordx4 v[132:135], v[2:3], off
	s_or_b64 exec, exec, s[8:9]
	v_add_u32_e32 v2, 52, v9
	v_cmp_lt_u32_e32 vcc, v2, v8
	v_mov_b32_e32 v136, 0
	v_mov_b32_e32 v137, 0
	v_mov_b32_e32 v138, 0
	v_mov_b32_e32 v139, 0
	s_and_saveexec_b64 s[8:9], vcc
	v_add_u32_e32 v2, 52, v6
	v_ashrrev_i32_e32 v3, 31, v2
	v_lshlrev_b64 v[2:3], 10, v[2:3]
	v_lshl_add_u64 v[2:3], v[10:11], 0, v[2:3]
	global_load_dwordx4 v[136:139], v[2:3], off
	s_or_b64 exec, exec, s[8:9]
	v_add_u32_e32 v2, 56, v9
	v_cmp_lt_u32_e32 vcc, v2, v8
	v_mov_b32_e32 v140, 0
	v_mov_b32_e32 v141, 0
	v_mov_b32_e32 v142, 0
	v_mov_b32_e32 v143, 0
	s_and_saveexec_b64 s[8:9], vcc
	v_add_u32_e32 v2, 56, v6
	v_ashrrev_i32_e32 v3, 31, v2
	v_lshlrev_b64 v[2:3], 10, v[2:3]
	v_lshl_add_u64 v[2:3], v[10:11], 0, v[2:3]
	global_load_dwordx4 v[140:143], v[2:3], off
	s_or_b64 exec, exec, s[8:9]
	v_add_u32_e32 v7, 0xf00, v81
	v_cmp_ge_u32_e32 vcc, s10, v7
	s_nop 1
	s_and_saveexec_b64 s[6:7], vcc
	v_add_u32_e32 v2, 60, v9
	v_cmp_lt_u32_e32 vcc, v2, v8
	v_mov_b32_e32 v144, 0
	v_mov_b32_e32 v145, 0
	v_mov_b32_e32 v146, 0
	v_mov_b32_e32 v147, 0
	s_and_saveexec_b64 s[8:9], vcc
	v_add_u32_e32 v2, 60, v6
	v_ashrrev_i32_e32 v3, 31, v2
	v_lshlrev_b64 v[2:3], 10, v[2:3]
	v_lshl_add_u64 v[2:3], v[10:11], 0, v[2:3]
	global_load_dwordx4 v[144:147], v[2:3], off
	s_or_b64 exec, exec, s[8:9]
	s_or_b64 exec, exec, s[6:7]
	s_waitcnt vmcnt(0)
; DI void conv_item(const Params& p, char* lds, int t0, int tid) {
;     ...
;     *(u32x4*)(zl + row * 256 + c16 * 4) = v;
	ds_write_b128 v80, v[84:87]
	ds_write_b128 v80, v[88:91] offset:4096
	ds_write_b128 v80, v[92:95] offset:8192
	ds_write_b128 v80, v[96:99] offset:12288
	ds_write_b128 v80, v[100:103] offset:16384
	ds_write_b128 v80, v[104:107] offset:20480
	ds_write_b128 v80, v[108:111] offset:24576
	ds_write_b128 v80, v[112:115] offset:28672
	ds_write_b128 v80, v[116:119] offset:32768
	ds_write_b128 v80, v[120:123] offset:36864
	ds_write_b128 v80, v[124:127] offset:40960
	ds_write_b128 v80, v[128:131] offset:45056
	ds_write_b128 v80, v[132:135] offset:49152
	ds_write_b128 v80, v[136:139] offset:53248
	ds_write_b128 v80, v[140:143] offset:57344
	v_add_u32_e32 v7, 0xf00, v81
	v_cmp_ge_u32_e32 vcc, s10, v7
	s_nop 1
	s_and_saveexec_b64 s[6:7], vcc
	ds_write_b128 v80, v[144:147] offset:61440
	s_or_b64 exec, exec, s[6:7]
	s_mov_b64 s[6:7], 0

; #define MFMA(a, b, c) __builtin_amdgcn_mfma_f32_32x32x16_bf16((a), (b), (c), 0, 0, 0)
; #define WAIT_V(n) asm volatile("s_waitcnt vmcnt(%0)" ::"n"(n) : "memory")
; #define RAW_BARRIER() do { asm volatile("s_waitcnt lgkmcnt(0)" ::: "memory"); __builtin_amdgcn_s_barrier(); } while (0)
; template <typename FA, typename FB, typename FE>
; DI void gemm_tile(char* lds, int K, int astride, int bstride, FA arow, FB brow, FE epi) {
;     ...
;   stage(0, 0); stage(1, 1); stage(2, 2);
;   for (int kt = 0; kt < nk; ++kt) {
;     if (kt + 2 < nk) WAIT_V(8); else if (kt + 1 < nk) WAIT_V(4); else WAIT_V(0);
;     RAW_BARRIER();
;     if (kt + 3 < nk) stage((kt + 3) & 3, kt + 3);
;     const char* sa = lds + (kt & 3) * 32768 + wm * 4096;
;     const char* sb = lds + (kt & 3) * 32768 + 16384 + wn * 8192;
; #pragma unroll
;     for (int ks = 0; ks < 2; ++ks) {
;       bf16x8 a0 = *(const bf16x8*)(sa + foff[ks]), a1 = *(const bf16x8*)(sa + 2048 + foff[ks]);
; #pragma unroll
;       for (int nt = 0; nt < 4; ++nt) {
;         bf16x8 bb = *(const bf16x8*)(sb + nt * 2048 + foff[ks]);
;         acc[0][nt] = MFMA(a0, bb, acc[0][nt]);
;         acc[1][nt] = MFMA(a1, bb, acc[1][nt]);
;       }
;     }
;   }
; DI void phase4(const Params& p, char* lds) {
;     ...
;     const int t0 = mt * 256;
;     int br, s0, S; tok_info(t0, br, s0, S);
;     auto arow = [&](int row) { return H + (size_t)(t0 + row) * D; };
;     auto brow = [&](int row) { return Wt + (size_t)(nt2 * 256 + row) * 32; };
;     auto epi = [&](int half, int ch, int tid) {
;       const bfr* Cs = Cs0 + half * 128 * CSS + ch * 128;
;       const int c4 = (tid & 31) * 4, col = nt2 * 256 + ch * 128 + c4, t0h = t0 + half * 128;
;       const float4 g1 = *(const float4*)(mod + br * 6144 + 2 * 1024 + col);
.LBB0_230:
	s_waitcnt lgkmcnt(0)
	s_waitcnt vmcnt(8)
	s_barrier
	s_add_i32 s41, s39, 0xfffe8000
	s_and_b32 s41, s41, 0x18000
	s_add_i32 s42, s41, s36
	s_or_b32 s41, s41, s37
	v_add_u32_e32 v244, s42, v145
	v_add_u32_e32 v245, s41, v145
	ds_read_b128 v[196:199], v244
	ds_read_b128 v[204:207], v245 offset:16384
	ds_read_b128 v[200:203], v244 offset:2048
	ds_read_b128 v[208:211], v245 offset:18432
	ds_read_b128 v[212:215], v245 offset:20480
	ds_read_b128 v[216:219], v245 offset:22528
	.p2align 6
.Lgm_P4_loop:
	s_and_b32 s40, s39, 0x18000
	s_add_i32 s40, s38, s40
	s_waitcnt vmcnt(4)
	v_lshl_add_u64 v[176:177], v[140:141], 0, v[130:131]
	v_lshl_add_u64 v[178:179], v[136:137], 0, v[130:131]
	s_mov_b32 m0, s40
	s_barrier
	s_add_i32 s41, s39, 0xfffe8000
	s_and_b32 s41, s41, 0x18000
	s_add_i32 s42, s41, s36
	s_or_b32 s41, s41, s37
	v_add_u32_e32 v246, s42, v146
	v_add_u32_e32 v247, s41, v146
	s_waitcnt lgkmcnt(4)
	v_mfma_f32_32x32x16_bf16 v[114:129], v[196:199], v[204:207], v[114:129]
	global_load_lds_dwordx4 v[176:177], off
	s_add_i32 m0, s40, 0x4000
	ds_read_b128 v[220:223], v246
	s_waitcnt lgkmcnt(4)
	v_mfma_f32_32x32x16_bf16 v[50:65], v[200:203], v[204:207], v[50:65]
	v_lshl_add_u64 v[180:181], v[142:143], 0, v[130:131]
	global_load_lds_dwordx4 v[178:179], off
	s_add_i32 m0, s40, 0x400
	ds_read_b128 v[228:231], v247 offset:16384
	s_waitcnt lgkmcnt(4)
	v_mfma_f32_32x32x16_bf16 v[98:113], v[196:199], v[208:211], v[98:113]
	v_lshl_add_u64 v[182:183], v[138:139], 0, v[130:131]
	global_load_lds_dwordx4 v[180:181], off
	s_add_i32 m0, s40, 0x4400
	ds_read_b128 v[224:227], v246 offset:2048
	v_mfma_f32_32x32x16_bf16 v[34:49], v[200:203], v[208:211], v[34:49]
	ds_read_b128 v[232:235], v247 offset:18432
	global_load_lds_dwordx4 v[182:183], off
	s_waitcnt lgkmcnt(5)
	v_mfma_f32_32x32x16_bf16 v[82:97], v[196:199], v[212:215], v[82:97]
	ds_read_b128 v[236:239], v247 offset:20480
	v_lshl_add_u64 v[136:137], v[136:137], 0, s[18:19]
	v_lshl_add_u64 v[138:139], v[138:139], 0, s[18:19]
	v_mfma_f32_32x32x16_bf16 v[18:33], v[200:203], v[212:215], v[18:33]
	ds_read_b128 v[240:243], v247 offset:22528
	v_lshl_add_u64 v[140:141], v[140:141], 0, 64
	v_lshl_add_u64 v[142:143], v[142:143], 0, 64
	s_waitcnt lgkmcnt(6)
	v_mfma_f32_32x32x16_bf16 v[66:81], v[196:199], v[216:219], v[66:81]
	s_add_i32 s41, s39, 0xffff0000
	s_and_b32 s41, s41, 0x18000
	s_add_i32 s42, s41, s36
	v_mfma_f32_32x32x16_bf16 v[2:17], v[200:203], v[216:219], v[2:17]
	s_or_b32 s41, s41, s37
	v_add_u32_e32 v244, s42, v145
	v_add_u32_e32 v245, s41, v145
	s_waitcnt lgkmcnt(4)
	v_mfma_f32_32x32x16_bf16 v[114:129], v[220:223], v[228:231], v[114:129]
	ds_read_b128 v[196:199], v244
	s_waitcnt lgkmcnt(4)
	v_mfma_f32_32x32x16_bf16 v[50:65], v[224:227], v[228:231], v[50:65]
	ds_read_b128 v[204:207], v245 offset:16384
	s_waitcnt lgkmcnt(4)
	v_mfma_f32_32x32x16_bf16 v[98:113], v[220:223], v[232:235], v[98:113]
	ds_read_b128 v[200:203], v244 offset:2048
	v_mfma_f32_32x32x16_bf16 v[34:49], v[224:227], v[232:235], v[34:49]
	ds_read_b128 v[208:211], v245 offset:18432
	s_waitcnt lgkmcnt(5)
	v_mfma_f32_32x32x16_bf16 v[82:97], v[220:223], v[236:239], v[82:97]
	ds_read_b128 v[212:215], v245 offset:20480
	v_mfma_f32_32x32x16_bf16 v[18:33], v[224:227], v[236:239], v[18:33]
	ds_read_b128 v[216:219], v245 offset:22528
	s_waitcnt lgkmcnt(6)
	v_mfma_f32_32x32x16_bf16 v[66:81], v[220:223], v[240:243], v[66:81]
	s_add_i32 s39, s39, 0x8000
	v_mfma_f32_32x32x16_bf16 v[2:17], v[224:227], v[240:243], v[2:17]
	s_cmp_lg_u32 s39, 0x100000
	s_cbranch_scc1 .Lgm_P4_loop
	s_waitcnt vmcnt(8)
	v_add_u32_e32 v175, s37, v146
	s_waitcnt lgkmcnt(0)
	s_barrier
	ds_read_b128 v[136:139], v175 offset:55296
	ds_read_b128 v[140:143], v175 offset:53248
	ds_read_b128 v[176:179], v175 offset:51200
	ds_read_b128 v[180:183], v175 offset:49152
	v_add_u32_e32 v175, s36, v146
	ds_read_b128 v[184:187], v175 offset:34816
	ds_read_b128 v[188:191], v175 offset:32768
	v_add_u32_e32 v175, s37, v145
	ds_read_b128 v[192:195], v175 offset:55296
	ds_read_b128 v[196:199], v175 offset:53248
	ds_read_b128 v[200:203], v175 offset:51200
	ds_read_b128 v[204:207], v175 offset:49152
	v_add_u32_e32 v175, s36, v145
	ds_read_b128 v[208:211], v175 offset:34816
	ds_read_b128 v[212:215], v175 offset:32768
	s_waitcnt lgkmcnt(0)
	v_mfma_f32_32x32x16_bf16 v[114:129], v[212:215], v[204:207], v[114:129]
	s_or_b32 s40, s37, 0x14000
	s_waitcnt vmcnt(4)
	v_add_u32_e32 v175, s40, v146
	s_add_i32 s41, s36, 0x10000
	s_waitcnt lgkmcnt(0)
	s_barrier
	s_add_i32 s38, s24, 0xffff0000
	v_mfma_f32_32x32x16_bf16 v[50:65], v[208:211], v[204:207], v[50:65]
	s_lshr_b32 s38, s38, 14
	s_lshr_b32 s39, s35, 4
	s_add_i32 s27, s27, s28
	s_add_i32 s38, s38, 16
	s_cmpk_lt_i32 s35, 0x100
	s_cselect_b32 s35, s39, s38
	s_or_b32 s37, s37, 0x1c000
	v_mfma_f32_32x32x16_bf16 v[98:113], v[212:215], v[200:203], v[98:113]
	s_add_i32 s36, s36, 0x18000
	v_add_u32_e32 v172, s29, v172
	v_add_u32_e32 v173, s29, v173
	v_mfma_f32_32x32x16_bf16 v[34:49], v[208:211], v[200:203], v[34:49]
	v_mfma_f32_32x32x16_bf16 v[82:97], v[212:215], v[196:199], v[82:97]
	v_mfma_f32_32x32x16_bf16 v[18:33], v[208:211], v[196:199], v[18:33]
	v_mfma_f32_32x32x16_bf16 v[66:81], v[212:215], v[192:195], v[66:81]
	v_mfma_f32_32x32x16_bf16 v[2:17], v[208:211], v[192:195], v[2:17]
	v_mfma_f32_32x32x16_bf16 v[114:129], v[188:191], v[180:183], v[114:129]
	v_mfma_f32_32x32x16_bf16 v[50:65], v[184:187], v[180:183], v[50:65]
	v_mfma_f32_32x32x16_bf16 v[98:113], v[188:191], v[176:179], v[98:113]
	v_mfma_f32_32x32x16_bf16 v[34:49], v[184:187], v[176:179], v[34:49]
	v_mfma_f32_32x32x16_bf16 v[82:97], v[188:191], v[140:143], v[82:97]
	v_mfma_f32_32x32x16_bf16 v[18:33], v[184:187], v[140:143], v[18:33]
	v_mfma_f32_32x32x16_bf16 v[66:81], v[188:191], v[136:139], v[66:81]
	v_mfma_f32_32x32x16_bf16 v[2:17], v[184:187], v[136:139], v[2:17]
	ds_read_b128 v[136:139], v175 offset:6144
	ds_read_b128 v[140:143], v175 offset:4096
	ds_read_b128 v[176:179], v175 offset:2048
	ds_read_b128 v[180:183], v175
	v_add_u32_e32 v175, s41, v146
	ds_read_b128 v[184:187], v175 offset:2048
	ds_read_b128 v[188:191], v175
	v_add_u32_e32 v175, s40, v145
	ds_read_b128 v[192:195], v175 offset:6144
	ds_read_b128 v[196:199], v175 offset:4096
	ds_read_b128 v[200:203], v175 offset:2048
	ds_read_b128 v[204:207], v175
	v_add_u32_e32 v175, s41, v145
	ds_read_b128 v[208:211], v175 offset:2048
	ds_read_b128 v[212:215], v175
	s_waitcnt lgkmcnt(0)
	v_mfma_f32_32x32x16_bf16 v[114:129], v[212:215], v[204:207], v[114:129]
	s_waitcnt vmcnt(0)
	v_add_u32_e32 v175, s37, v146
	s_waitcnt lgkmcnt(0)
	s_barrier
; #define MFMA(a, b, c) __builtin_amdgcn_mfma_f32_32x32x16_bf16((a), (b), (c), 0, 0, 0)
; DI unsigned pk2(float a, float b) { fl2_t f = {a, b}; bf2_t r = __builtin_convertvector(f, bf2_t); return __builtin_bit_cast(unsigned, r); }
; #define RAW_BARRIER() do { asm volatile("s_waitcnt lgkmcnt(0)" ::: "memory"); __builtin_amdgcn_s_barrier(); } while (0)
; template <typename FA, typename FB, typename FE>
; DI void gemm_tile(char* lds, int K, int astride, int bstride, FA arow, FB brow, FE epi) {
;     ...
;       bf16x8 a0 = *(const bf16x8*)(sa + foff[ks]), a1 = *(const bf16x8*)(sa + 2048 + foff[ks]);
; #pragma unroll
;       for (int nt = 0; nt < 4; ++nt) {
;         bf16x8 bb = *(const bf16x8*)(sb + nt * 2048 + foff[ks]);
;         acc[0][nt] = MFMA(a0, bb, acc[0][nt]);
;         acc[1][nt] = MFMA(a1, bb, acc[1][nt]);
;       }
;     }
;   }
;   RAW_BARRIER();
;   bfr* Cs = (bfr*)lds;
; #pragma unroll
;   for (int mt = 0; mt < 2; ++mt)
; #pragma unroll
;     for (int nt = 0; nt < 4; ++nt)
; #pragma unroll
;       for (int i = 0; i < 16; i += 2) {
;         const int row = wm * 64 + mt * 32 + (i & 3) + 8 * (i >> 2) + 4 * h8;
;         const unsigned pr = pk2(acc[mt][nt][i], acc[mt][nt][i + 1]);
;         Cs[row * CSS + wn * 128 + nt * 32 + r] = (bfr)(pr & 0xffffu);
;         Cs[(row + 1) * CSS + wn * 128 + nt * 32 + r] = (bfr)(pr >> 16);
;       }
	v_mfma_f32_32x32x16_bf16 v[50:65], v[208:211], v[204:207], v[50:65]
	v_mfma_f32_32x32x16_bf16 v[98:113], v[212:215], v[200:203], v[98:113]
	v_mfma_f32_32x32x16_bf16 v[34:49], v[208:211], v[200:203], v[34:49]
	v_mfma_f32_32x32x16_bf16 v[82:97], v[212:215], v[196:199], v[82:97]
	v_mfma_f32_32x32x16_bf16 v[18:33], v[208:211], v[196:199], v[18:33]
	v_mfma_f32_32x32x16_bf16 v[66:81], v[212:215], v[192:195], v[66:81]
	v_mfma_f32_32x32x16_bf16 v[2:17], v[208:211], v[192:195], v[2:17]
	v_mfma_f32_32x32x16_bf16 v[114:129], v[188:191], v[180:183], v[114:129]
	v_mfma_f32_32x32x16_bf16 v[50:65], v[184:187], v[180:183], v[50:65]
	v_mfma_f32_32x32x16_bf16 v[98:113], v[188:191], v[176:179], v[98:113]
	v_mfma_f32_32x32x16_bf16 v[34:49], v[184:187], v[176:179], v[34:49]
	v_mfma_f32_32x32x16_bf16 v[82:97], v[188:191], v[140:143], v[82:97]
	v_mfma_f32_32x32x16_bf16 v[18:33], v[184:187], v[140:143], v[18:33]
	v_mfma_f32_32x32x16_bf16 v[66:81], v[188:191], v[136:139], v[66:81]
	v_mfma_f32_32x32x16_bf16 v[2:17], v[184:187], v[136:139], v[2:17]
	ds_read_b128 v[136:139], v175 offset:6144
	ds_read_b128 v[140:143], v175 offset:4096
	ds_read_b128 v[176:179], v175 offset:2048
	ds_read_b128 v[180:183], v175
	v_add_u32_e32 v175, s36, v146
	ds_read_b128 v[184:187], v175 offset:2048
	ds_read_b128 v[188:191], v175
	v_add_u32_e32 v175, s37, v145
	ds_read_b128 v[192:195], v175 offset:6144
	ds_read_b128 v[196:199], v175 offset:4096
	ds_read_b128 v[200:203], v175 offset:2048
	ds_read_b128 v[204:207], v175
	v_add_u32_e32 v175, s36, v145
	ds_read_b128 v[208:211], v175 offset:2048
	ds_read_b128 v[212:215], v175
	s_waitcnt lgkmcnt(0)
	v_mfma_f32_32x32x16_bf16 v[114:129], v[212:215], v[204:207], v[114:129]
	s_waitcnt lgkmcnt(0)
	s_barrier
	v_mfma_f32_32x32x16_bf16 v[98:113], v[212:215], v[200:203], v[98:113]
	v_mfma_f32_32x32x16_bf16 v[66:81], v[212:215], v[192:195], v[66:81]
	v_mfma_f32_32x32x16_bf16 v[2:17], v[208:211], v[192:195], v[2:17]
	v_mfma_f32_32x32x16_bf16 v[114:129], v[188:191], v[180:183], v[114:129]
	v_mfma_f32_32x32x16_bf16 v[82:97], v[212:215], v[196:199], v[82:97]
	v_mfma_f32_32x32x16_bf16 v[98:113], v[188:191], v[176:179], v[98:113]
	v_mfma_f32_32x32x16_bf16 v[66:81], v[188:191], v[136:139], v[66:81]
	s_nop 10
	v_cvt_pk_bf16_f32 v98, v98, v99
	v_mfma_f32_32x32x16_bf16 v[2:17], v[184:187], v[136:139], v[2:17]
	v_lshl_or_b32 v136, s34, 6, v147
	v_cvt_pk_bf16_f32 v137, v114, v115
	v_lshl_or_b32 v114, s33, 8, v171
	v_mad_u64_u32 v[114:115], s[36:37], v136, s31, v[114:115]
	v_cvt_pk_bf16_f32 v115, v116, v117
	ds_write_b16 v114, v137
	ds_write_b16_d16_hi v114, v137 offset:528
	ds_write_b16 v114, v115 offset:1056
	ds_write_b16_d16_hi v114, v115 offset:1584
	v_cvt_pk_bf16_f32 v115, v118, v119
	ds_write_b16 v114, v115 offset:4224
	ds_write_b16_d16_hi v114, v115 offset:4752
	v_cvt_pk_bf16_f32 v115, v120, v121
	ds_write_b16 v114, v115 offset:5280
	ds_write_b16_d16_hi v114, v115 offset:5808
	v_cvt_pk_bf16_f32 v115, v122, v123
	ds_write_b16 v114, v115 offset:8448
	ds_write_b16_d16_hi v114, v115 offset:8976
	v_cvt_pk_bf16_f32 v115, v124, v125
	v_mfma_f32_32x32x16_bf16 v[82:97], v[188:191], v[140:143], v[82:97]
	ds_write_b16 v114, v115 offset:9504
	ds_write_b16_d16_hi v114, v115 offset:10032
	v_cvt_pk_bf16_f32 v115, v126, v127
	ds_write_b16 v114, v115 offset:12672
	ds_write_b16_d16_hi v114, v115 offset:13200
	v_cvt_pk_bf16_f32 v115, v128, v129
	ds_write_b16 v114, v115 offset:13728
	ds_write_b16_d16_hi v114, v115 offset:14256
	ds_write_b16 v114, v98 offset:64
	ds_write_b16_d16_hi v114, v98 offset:592
	v_cvt_pk_bf16_f32 v98, v100, v101
	ds_write_b16 v114, v98 offset:1120
	ds_write_b16_d16_hi v114, v98 offset:1648
	v_cvt_pk_bf16_f32 v98, v102, v103
	ds_write_b16 v114, v98 offset:4288
	ds_write_b16_d16_hi v114, v98 offset:4816
	v_cvt_pk_bf16_f32 v98, v104, v105
	ds_write_b16 v114, v98 offset:5344
	ds_write_b16_d16_hi v114, v98 offset:5872
	v_cvt_pk_bf16_f32 v98, v106, v107
	v_mfma_f32_32x32x16_bf16 v[50:65], v[208:211], v[204:207], v[50:65]
	ds_write_b16 v114, v98 offset:8512
	ds_write_b16_d16_hi v114, v98 offset:9040
	v_cvt_pk_bf16_f32 v98, v108, v109
	ds_write_b16 v114, v98 offset:9568
	ds_write_b16_d16_hi v114, v98 offset:10096
	v_cvt_pk_bf16_f32 v98, v110, v111
	ds_write_b16 v114, v98 offset:12736
	ds_write_b16_d16_hi v114, v98 offset:13264
	v_cvt_pk_bf16_f32 v98, v112, v113
	v_cvt_pk_bf16_f32 v82, v82, v83
	ds_write_b16 v114, v98 offset:13792
	ds_write_b16_d16_hi v114, v98 offset:14320
	ds_write_b16 v114, v82 offset:128
	ds_write_b16_d16_hi v114, v82 offset:656
	v_cvt_pk_bf16_f32 v82, v84, v85
	ds_write_b16 v114, v82 offset:1184
	ds_write_b16_d16_hi v114, v82 offset:1712
	v_cvt_pk_bf16_f32 v82, v86, v87
	ds_write_b16 v114, v82 offset:4352
	ds_write_b16_d16_hi v114, v82 offset:4880
	v_cvt_pk_bf16_f32 v82, v88, v89
	ds_write_b16 v114, v82 offset:5408
	ds_write_b16_d16_hi v114, v82 offset:5936
	v_cvt_pk_bf16_f32 v82, v90, v91
	v_mfma_f32_32x32x16_bf16 v[34:49], v[208:211], v[200:203], v[34:49]
	ds_write_b16 v114, v82 offset:8576
	ds_write_b16_d16_hi v114, v82 offset:9104
	v_cvt_pk_bf16_f32 v82, v92, v93
	ds_write_b16 v114, v82 offset:9632
	ds_write_b16_d16_hi v114, v82 offset:10160
	v_cvt_pk_bf16_f32 v82, v94, v95
	ds_write_b16 v114, v82 offset:12800
	ds_write_b16_d16_hi v114, v82 offset:13328
	v_cvt_pk_bf16_f32 v82, v96, v97
	v_cvt_pk_bf16_f32 v66, v66, v67
	v_mfma_f32_32x32x16_bf16 v[50:65], v[184:187], v[180:183], v[50:65]
	ds_write_b16 v114, v82 offset:13856
	ds_write_b16_d16_hi v114, v82 offset:14384
	ds_write_b16 v114, v66 offset:192
	ds_write_b16_d16_hi v114, v66 offset:720
	v_cvt_pk_bf16_f32 v66, v68, v69
	ds_write_b16 v114, v66 offset:1248
	ds_write_b16_d16_hi v114, v66 offset:1776
; DI unsigned pk2(float a, float b) { fl2_t f = {a, b}; bf2_t r = __builtin_convertvector(f, bf2_t); return __builtin_bit_cast(unsigned, r); }
; template <typename FA, typename FB, typename FE>
; DI void gemm_tile(char* lds, int K, int astride, int bstride, FA arow, FB brow, FE epi) {
;     ...
;         const int row = wm * 64 + mt * 32 + (i & 3) + 8 * (i >> 2) + 4 * h8;
;         const unsigned pr = pk2(acc[mt][nt][i], acc[mt][nt][i + 1]);
;         Cs[row * CSS + wn * 128 + nt * 32 + r] = (bfr)(pr & 0xffffu);
;         Cs[(row + 1) * CSS + wn * 128 + nt * 32 + r] = (bfr)(pr >> 16);
; DI void phase4(const Params& p, char* lds) {
;     ...
;       const int c4 = (tid & 31) * 4, col = nt2 * 256 + ch * 128 + c4, t0h = t0 + half * 128;
;       const float4 g1 = *(const float4*)(mod + br * 6144 + 2 * 1024 + col);
;       float4 xv[16];
; #pragma unroll
;       for (int ps = 0; ps < 16; ++ps) xv[ps] = *(const float4*)(xrow(p, t0h + ps * 8 + (tid >> 5)) + col);
	v_cvt_pk_bf16_f32 v66, v70, v71
	ds_write_b16 v114, v66 offset:4416
	ds_write_b16_d16_hi v114, v66 offset:4944
	v_cvt_pk_bf16_f32 v66, v72, v73
	ds_write_b16 v114, v66 offset:5472
	ds_write_b16_d16_hi v114, v66 offset:6000
	v_cvt_pk_bf16_f32 v66, v74, v75
	v_mfma_f32_32x32x16_bf16 v[18:33], v[208:211], v[196:199], v[18:33]
	ds_write_b16 v114, v66 offset:8640
	ds_write_b16_d16_hi v114, v66 offset:9168
	v_cvt_pk_bf16_f32 v66, v76, v77
	ds_write_b16 v114, v66 offset:9696
	ds_write_b16_d16_hi v114, v66 offset:10224
	v_cvt_pk_bf16_f32 v66, v78, v79
	ds_write_b16 v114, v66 offset:12864
	ds_write_b16_d16_hi v114, v66 offset:13392
	v_cvt_pk_bf16_f32 v66, v80, v81
	v_cvt_pk_bf16_f32 v50, v50, v51
	v_mfma_f32_32x32x16_bf16 v[34:49], v[184:187], v[176:179], v[34:49]
	ds_write_b16 v114, v66 offset:13920
	ds_write_b16_d16_hi v114, v66 offset:14448
	ds_write_b16 v114, v50 offset:16896
	ds_write_b16_d16_hi v114, v50 offset:17424
	v_cvt_pk_bf16_f32 v50, v52, v53
	ds_write_b16 v114, v50 offset:17952
	ds_write_b16_d16_hi v114, v50 offset:18480
	v_cvt_pk_bf16_f32 v50, v54, v55
	ds_write_b16 v114, v50 offset:21120
	ds_write_b16_d16_hi v114, v50 offset:21648
	v_cvt_pk_bf16_f32 v50, v56, v57
	ds_write_b16 v114, v50 offset:22176
	ds_write_b16_d16_hi v114, v50 offset:22704
	v_cvt_pk_bf16_f32 v50, v58, v59
	ds_write_b16 v114, v50 offset:25344
	ds_write_b16_d16_hi v114, v50 offset:25872
	v_cvt_pk_bf16_f32 v50, v60, v61
	v_mfma_f32_32x32x16_bf16 v[18:33], v[184:187], v[140:143], v[18:33]
	ds_write_b16 v114, v50 offset:26400
	ds_write_b16_d16_hi v114, v50 offset:26928
	v_cvt_pk_bf16_f32 v50, v62, v63
	ds_write_b16 v114, v50 offset:29568
	ds_write_b16_d16_hi v114, v50 offset:30096
	v_cvt_pk_bf16_f32 v50, v64, v65
	v_cvt_pk_bf16_f32 v34, v34, v35
	ds_write_b16 v114, v50 offset:30624
	ds_write_b16_d16_hi v114, v50 offset:31152
	ds_write_b16 v114, v34 offset:16960
	ds_write_b16_d16_hi v114, v34 offset:17488
	v_cvt_pk_bf16_f32 v34, v36, v37
	ds_write_b16 v114, v34 offset:18016
	ds_write_b16_d16_hi v114, v34 offset:18544
	v_cvt_pk_bf16_f32 v34, v38, v39
	ds_write_b16 v114, v34 offset:21184
	ds_write_b16_d16_hi v114, v34 offset:21712
	v_cvt_pk_bf16_f32 v34, v40, v41
	ds_write_b16 v114, v34 offset:22240
	ds_write_b16_d16_hi v114, v34 offset:22768
	v_cvt_pk_bf16_f32 v34, v42, v43
	ds_write_b16 v114, v34 offset:25408
	ds_write_b16_d16_hi v114, v34 offset:25936
	v_cvt_pk_bf16_f32 v34, v44, v45
	ds_write_b16 v114, v34 offset:26464
	ds_write_b16_d16_hi v114, v34 offset:26992
	v_cvt_pk_bf16_f32 v34, v46, v47
	ds_write_b16 v114, v34 offset:29632
	ds_write_b16_d16_hi v114, v34 offset:30160
	v_cvt_pk_bf16_f32 v34, v48, v49
	v_cvt_pk_bf16_f32 v18, v18, v19
	ds_write_b16 v114, v34 offset:30688
	ds_write_b16_d16_hi v114, v34 offset:31216
	ds_write_b16 v114, v18 offset:17024
	ds_write_b16_d16_hi v114, v18 offset:17552
	v_cvt_pk_bf16_f32 v18, v20, v21
	ds_write_b16 v114, v18 offset:18080
	ds_write_b16_d16_hi v114, v18 offset:18608
	v_cvt_pk_bf16_f32 v18, v22, v23
	ds_write_b16 v114, v18 offset:21248
	ds_write_b16_d16_hi v114, v18 offset:21776
	v_cvt_pk_bf16_f32 v18, v24, v25
	ds_write_b16 v114, v18 offset:22304
	ds_write_b16_d16_hi v114, v18 offset:22832
	v_cvt_pk_bf16_f32 v18, v26, v27
	ds_write_b16 v114, v18 offset:25472
	ds_write_b16_d16_hi v114, v18 offset:26000
	v_cvt_pk_bf16_f32 v18, v28, v29
	ds_write_b16 v114, v18 offset:26528
	ds_write_b16_d16_hi v114, v18 offset:27056
	v_cvt_pk_bf16_f32 v18, v30, v31
	ds_write_b16 v114, v18 offset:29696
	ds_write_b16_d16_hi v114, v18 offset:30224
	v_cvt_pk_bf16_f32 v18, v32, v33
	v_cvt_pk_bf16_f32 v2, v2, v3
	ds_write_b16 v114, v18 offset:30752
	ds_write_b16_d16_hi v114, v18 offset:31280
	ds_write_b16 v114, v2 offset:17088
	ds_write_b16_d16_hi v114, v2 offset:17616
	v_cvt_pk_bf16_f32 v2, v4, v5
	ds_write_b16 v114, v2 offset:18144
	ds_write_b16_d16_hi v114, v2 offset:18672
	v_cvt_pk_bf16_f32 v2, v6, v7
	ds_write_b16 v114, v2 offset:21312
	ds_write_b16_d16_hi v114, v2 offset:21840
	v_cvt_pk_bf16_f32 v2, v8, v9
	ds_write_b16 v114, v2 offset:22368
	ds_write_b16_d16_hi v114, v2 offset:22896
	v_cvt_pk_bf16_f32 v2, v10, v11
	v_add_u32_e32 v10, s24, v148
	v_or_b32_e32 v4, v10, v150
	ds_write_b16 v114, v2 offset:25536
	ds_write_b16_d16_hi v114, v2 offset:26064
	v_cvt_pk_bf16_f32 v2, v12, v13
	v_cmp_gt_i32_e32 vcc, s30, v4
	v_add_u32_e32 v6, 0xffff0000, v4
	v_ashrrev_i32_e32 v5, 31, v4
	ds_write_b16 v114, v2 offset:26592
	ds_write_b16_d16_hi v114, v2 offset:27120
	v_cvt_pk_bf16_f32 v2, v14, v15
	v_or_b32_e32 v70, s25, v149
	v_cndmask_b32_e32 v7, 0, v5, vcc
	v_cndmask_b32_e32 v6, v6, v4, vcc
	v_mov_b32_e32 v11, s11
	v_mov_b32_e32 v12, s9
	v_mov_b32_e32 v13, s10
	v_mov_b32_e32 v14, s8
	ds_write_b16 v114, v2 offset:29760
	ds_write_b16_d16_hi v114, v2 offset:30288
	v_cvt_pk_bf16_f32 v2, v16, v17
	v_ashrrev_i32_e32 v71, 31, v70
	v_cndmask_b32_e32 v9, v11, v12, vcc
	v_cndmask_b32_e32 v8, v13, v14, vcc
	v_lshlrev_b64 v[6:7], 12, v[6:7]
	ds_write_b16 v114, v2 offset:30816
	ds_write_b16_d16_hi v114, v2 offset:31344
	v_lshlrev_b64 v[2:3], 2, v[70:71]
	v_lshl_add_u64 v[6:7], v[8:9], 0, v[6:7]
	v_lshl_add_u64 v[68:69], v[6:7], 0, v[2:3]
	v_or_b32_e32 v6, 8, v4
	v_cmp_gt_i32_e32 vcc, s30, v6
	v_add_u32_e32 v8, 0xffff0008, v4
	v_ashrrev_i32_e32 v7, 31, v6
	v_cndmask_b32_e32 v7, 0, v7, vcc
	v_cndmask_b32_e32 v6, v8, v6, vcc
	v_cndmask_b32_e32 v9, v11, v12, vcc
	v_cndmask_b32_e32 v8, v13, v14, vcc
	v_lshlrev_b64 v[6:7], 12, v[6:7]
	v_lshl_add_u64 v[6:7], v[8:9], 0, v[6:7]
	v_lshl_add_u64 v[74:75], v[6:7], 0, v[2:3]
	v_or_b32_e32 v6, 16, v4
	v_cmp_gt_i32_e32 vcc, s30, v6
	v_add_u32_e32 v8, 0xffff0010, v4
	v_ashrrev_i32_e32 v7, 31, v6
	v_cndmask_b32_e32 v7, 0, v7, vcc
; DI void phase4(const Params& p, char* lds) {
;     ...
;       const int c4 = (tid & 31) * 4, col = nt2 * 256 + ch * 128 + c4, t0h = t0 + half * 128;
;       const float4 g1 = *(const float4*)(mod + br * 6144 + 2 * 1024 + col);
;       float4 xv[16];
; #pragma unroll
;       for (int ps = 0; ps < 16; ++ps) xv[ps] = *(const float4*)(xrow(p, t0h + ps * 8 + (tid >> 5)) + col);
;       asm volatile("" ::: "memory");
; #pragma unroll
;       for (int ps = 0; ps < 16; ++ps) {
;         const int row = ps * 8 + (tid >> 5), t = t0h + row;
;         float4 c = cs4(Cs, row, c4);
;         float4 o = make_float4(xv[ps].x + g1.x * c.x, xv[ps].y + g1.y * c.y, xv[ps].z + g1.z * c.z, xv[ps].w + g1.w * c.w);
;         *(float4*)(p.out + (size_t)t * D + col) = o;
	v_cndmask_b32_e32 v6, v8, v6, vcc
	v_cndmask_b32_e32 v9, v11, v12, vcc
	v_cndmask_b32_e32 v8, v13, v14, vcc
	v_lshlrev_b64 v[6:7], 12, v[6:7]
	v_lshl_add_u64 v[6:7], v[8:9], 0, v[6:7]
	v_lshl_add_u64 v[78:79], v[6:7], 0, v[2:3]
	v_or_b32_e32 v6, 24, v4
	v_cmp_gt_i32_e32 vcc, s30, v6
	v_add_u32_e32 v8, 0xffff0018, v4
	v_ashrrev_i32_e32 v7, 31, v6
	v_cndmask_b32_e32 v7, 0, v7, vcc
	v_cndmask_b32_e32 v6, v8, v6, vcc
	v_cndmask_b32_e32 v9, v11, v12, vcc
	v_cndmask_b32_e32 v8, v13, v14, vcc
	v_lshlrev_b64 v[6:7], 12, v[6:7]
	v_lshl_add_u64 v[6:7], v[8:9], 0, v[6:7]
	v_lshl_add_u64 v[84:85], v[6:7], 0, v[2:3]
	v_or_b32_e32 v6, 32, v4
	v_cmp_gt_i32_e32 vcc, s30, v6
	v_add_u32_e32 v8, 0xffff0020, v4
	v_ashrrev_i32_e32 v7, 31, v6
	v_cndmask_b32_e32 v7, 0, v7, vcc
	v_cndmask_b32_e32 v6, v8, v6, vcc
	v_cndmask_b32_e32 v9, v11, v12, vcc
	v_cndmask_b32_e32 v8, v13, v14, vcc
	v_lshlrev_b64 v[6:7], 12, v[6:7]
	v_lshl_add_u64 v[6:7], v[8:9], 0, v[6:7]
	v_lshl_add_u64 v[90:91], v[6:7], 0, v[2:3]
	v_or_b32_e32 v6, 40, v4
	v_cmp_gt_i32_e32 vcc, s30, v6
	v_add_u32_e32 v8, 0xffff0028, v4
	v_ashrrev_i32_e32 v7, 31, v6
	v_cndmask_b32_e32 v7, 0, v7, vcc
	v_cndmask_b32_e32 v6, v8, v6, vcc
	v_cndmask_b32_e32 v9, v11, v12, vcc
	v_cndmask_b32_e32 v8, v13, v14, vcc
	v_lshlrev_b64 v[6:7], 12, v[6:7]
	v_lshl_add_u64 v[6:7], v[8:9], 0, v[6:7]
	v_lshl_add_u64 v[94:95], v[6:7], 0, v[2:3]
	v_or_b32_e32 v6, 48, v4
	v_cmp_gt_i32_e32 vcc, s30, v6
	v_add_u32_e32 v8, 0xffff0030, v4
	v_ashrrev_i32_e32 v7, 31, v6
	v_cndmask_b32_e32 v7, 0, v7, vcc
	v_cndmask_b32_e32 v6, v8, v6, vcc
	v_cndmask_b32_e32 v9, v11, v12, vcc
	v_cndmask_b32_e32 v8, v13, v14, vcc
	v_lshlrev_b64 v[6:7], 12, v[6:7]
	v_lshl_add_u64 v[6:7], v[8:9], 0, v[6:7]
	v_lshl_add_u64 v[100:101], v[6:7], 0, v[2:3]
	v_or_b32_e32 v6, 56, v4
	v_cmp_gt_i32_e32 vcc, s30, v6
	v_add_u32_e32 v8, 0xffff0038, v4
	v_ashrrev_i32_e32 v7, 31, v6
	v_cndmask_b32_e32 v7, 0, v7, vcc
	v_cndmask_b32_e32 v6, v8, v6, vcc
	v_cndmask_b32_e32 v9, v11, v12, vcc
	v_cndmask_b32_e32 v8, v13, v14, vcc
	v_lshlrev_b64 v[6:7], 12, v[6:7]
	v_lshl_add_u64 v[6:7], v[8:9], 0, v[6:7]
	v_lshl_add_u64 v[106:107], v[6:7], 0, v[2:3]
	v_or_b32_e32 v6, 64, v4
	v_cmp_gt_i32_e32 vcc, s30, v6
	v_add_u32_e32 v8, 0xffff0040, v4
	v_ashrrev_i32_e32 v7, 31, v6
	v_cndmask_b32_e32 v7, 0, v7, vcc
	v_cndmask_b32_e32 v6, v8, v6, vcc
	v_cndmask_b32_e32 v9, v11, v12, vcc
	v_cndmask_b32_e32 v8, v13, v14, vcc
	v_lshlrev_b64 v[6:7], 12, v[6:7]
	v_lshl_add_u64 v[6:7], v[8:9], 0, v[6:7]
	v_lshl_add_u64 v[110:111], v[6:7], 0, v[2:3]
	v_or_b32_e32 v6, 0x48, v4
	v_cmp_gt_i32_e32 vcc, s30, v6
	v_add_u32_e32 v8, 0xffff0048, v4
	v_ashrrev_i32_e32 v7, 31, v6
	v_cndmask_b32_e32 v7, 0, v7, vcc
	v_cndmask_b32_e32 v6, v8, v6, vcc
	v_cndmask_b32_e32 v9, v11, v12, vcc
	v_cndmask_b32_e32 v8, v13, v14, vcc
	v_lshlrev_b64 v[6:7], 12, v[6:7]
	v_lshl_add_u64 v[6:7], v[8:9], 0, v[6:7]
	v_lshl_add_u64 v[114:115], v[6:7], 0, v[2:3]
	v_or_b32_e32 v6, 0x50, v4
	v_cmp_gt_i32_e32 vcc, s30, v6
	v_add_u32_e32 v8, 0xffff0050, v4
	v_ashrrev_i32_e32 v7, 31, v6
	v_cndmask_b32_e32 v7, 0, v7, vcc
	v_cndmask_b32_e32 v6, v8, v6, vcc
	v_cndmask_b32_e32 v9, v11, v12, vcc
	v_cndmask_b32_e32 v8, v13, v14, vcc
	v_lshlrev_b64 v[6:7], 12, v[6:7]
	v_lshl_add_u64 v[6:7], v[8:9], 0, v[6:7]
	v_lshl_add_u64 v[116:117], v[6:7], 0, v[2:3]
	v_or_b32_e32 v6, 0x58, v4
	v_cmp_gt_i32_e32 vcc, s30, v6
	v_add_u32_e32 v8, 0xffff0058, v4
	v_ashrrev_i32_e32 v7, 31, v6
	v_cndmask_b32_e32 v7, 0, v7, vcc
	v_cndmask_b32_e32 v6, v8, v6, vcc
	v_cndmask_b32_e32 v9, v11, v12, vcc
	v_cndmask_b32_e32 v8, v13, v14, vcc
	v_lshlrev_b64 v[6:7], 12, v[6:7]
	v_lshl_add_u64 v[6:7], v[8:9], 0, v[6:7]
	v_lshl_add_u64 v[118:119], v[6:7], 0, v[2:3]
	v_or_b32_e32 v6, 0x60, v4
	v_cmp_gt_i32_e32 vcc, s30, v6
	v_add_u32_e32 v8, 0xffff0060, v4
	v_ashrrev_i32_e32 v7, 31, v6
	v_cndmask_b32_e32 v7, 0, v7, vcc
	v_cndmask_b32_e32 v6, v8, v6, vcc
	v_cndmask_b32_e32 v9, v11, v12, vcc
	v_cndmask_b32_e32 v8, v13, v14, vcc
	v_lshlrev_b64 v[6:7], 12, v[6:7]
	v_lshl_add_u64 v[6:7], v[8:9], 0, v[6:7]
	v_lshl_add_u64 v[120:121], v[6:7], 0, v[2:3]
	v_or_b32_e32 v6, 0x68, v4
	v_cmp_gt_i32_e32 vcc, s30, v6
	v_add_u32_e32 v8, 0xffff0068, v4
	v_ashrrev_i32_e32 v7, 31, v6
	v_cndmask_b32_e32 v7, 0, v7, vcc
	v_cndmask_b32_e32 v6, v8, v6, vcc
	v_cndmask_b32_e32 v9, v11, v12, vcc
	v_cndmask_b32_e32 v8, v13, v14, vcc
	v_lshlrev_b64 v[6:7], 12, v[6:7]
	v_lshl_add_u64 v[6:7], v[8:9], 0, v[6:7]
	v_lshl_add_u64 v[122:123], v[6:7], 0, v[2:3]
	v_or_b32_e32 v6, 0x70, v4
	v_cmp_gt_i32_e32 vcc, s30, v6
	v_add_u32_e32 v8, 0xffff0070, v4
	v_ashrrev_i32_e32 v7, 31, v6
	v_cndmask_b32_e32 v7, 0, v7, vcc
	v_cndmask_b32_e32 v6, v8, v6, vcc
	v_cndmask_b32_e32 v9, v11, v12, vcc
	v_cndmask_b32_e32 v8, v13, v14, vcc
	v_lshlrev_b64 v[6:7], 12, v[6:7]
	v_lshl_add_u64 v[6:7], v[8:9], 0, v[6:7]
	v_lshl_add_u64 v[124:125], v[6:7], 0, v[2:3]
	v_or_b32_e32 v6, 0x78, v4
	v_add_u32_e32 v8, 0xffff0078, v4
	v_lshlrev_b64 v[4:5], 12, v[4:5]
	v_lshl_add_u64 v[4:5], s[4:5], 0, v[4:5]
	v_lshl_add_u64 v[112:113], v[4:5], 0, v[2:3]
	v_or_b32_e32 v4, v10, v152
	v_ashrrev_i32_e32 v5, 31, v4
	v_lshlrev_b64 v[4:5], 12, v[4:5]
	v_lshl_add_u64 v[4:5], s[4:5], 0, v[4:5]
	v_lshl_add_u64 v[108:109], v[4:5], 0, v[2:3]
	v_or_b32_e32 v4, v10, v153
	v_ashrrev_i32_e32 v5, 31, v4
	v_lshlrev_b64 v[4:5], 12, v[4:5]
	v_lshl_add_u64 v[4:5], s[4:5], 0, v[4:5]
	v_lshl_add_u64 v[104:105], v[4:5], 0, v[2:3]
	v_or_b32_e32 v4, v10, v154
	v_ashrrev_i32_e32 v5, 31, v4
	v_lshlrev_b64 v[4:5], 12, v[4:5]
	v_lshl_add_u64 v[4:5], s[4:5], 0, v[4:5]
	v_lshl_add_u64 v[102:103], v[4:5], 0, v[2:3]
	v_or_b32_e32 v4, v10, v156
	v_ashrrev_i32_e32 v5, 31, v4
; DI void phase4(const Params& p, char* lds) {
;     ...
;       const int c4 = (tid & 31) * 4, col = nt2 * 256 + ch * 128 + c4, t0h = t0 + half * 128;
;       const float4 g1 = *(const float4*)(mod + br * 6144 + 2 * 1024 + col);
;       float4 xv[16];
; #pragma unroll
;       for (int ps = 0; ps < 16; ++ps) xv[ps] = *(const float4*)(xrow(p, t0h + ps * 8 + (tid >> 5)) + col);
;       asm volatile("" ::: "memory");
; #pragma unroll
;       for (int ps = 0; ps < 16; ++ps) {
;         const int row = ps * 8 + (tid >> 5), t = t0h + row;
;         float4 c = cs4(Cs, row, c4);
;         float4 o = make_float4(xv[ps].x + g1.x * c.x, xv[ps].y + g1.y * c.y, xv[ps].z + g1.z * c.z, xv[ps].w + g1.w * c.w);
;         *(float4*)(p.out + (size_t)t * D + col) = o;
;       }
	v_lshlrev_b64 v[4:5], 12, v[4:5]
	v_lshl_add_u64 v[4:5], s[4:5], 0, v[4:5]
	v_lshl_add_u64 v[98:99], v[4:5], 0, v[2:3]
	v_or_b32_e32 v4, v10, v157
	v_ashrrev_i32_e32 v5, 31, v4
	v_lshlrev_b64 v[4:5], 12, v[4:5]
	v_lshl_add_u64 v[4:5], s[4:5], 0, v[4:5]
	v_lshl_add_u64 v[96:97], v[4:5], 0, v[2:3]
	v_or_b32_e32 v4, v10, v158
	v_ashrrev_i32_e32 v5, 31, v4
	v_lshlrev_b64 v[4:5], 12, v[4:5]
	v_lshl_add_u64 v[4:5], s[4:5], 0, v[4:5]
	v_lshl_add_u64 v[92:93], v[4:5], 0, v[2:3]
	v_or_b32_e32 v4, v10, v159
	v_ashrrev_i32_e32 v5, 31, v4
	v_lshlrev_b64 v[4:5], 12, v[4:5]
	v_lshl_add_u64 v[4:5], s[4:5], 0, v[4:5]
	v_lshl_add_u64 v[88:89], v[4:5], 0, v[2:3]
	v_or_b32_e32 v4, v10, v161
	v_ashrrev_i32_e32 v5, 31, v4
	v_lshlrev_b64 v[4:5], 12, v[4:5]
	v_lshl_add_u64 v[4:5], s[4:5], 0, v[4:5]
	v_lshl_add_u64 v[86:87], v[4:5], 0, v[2:3]
	v_or_b32_e32 v4, v10, v162
	v_ashrrev_i32_e32 v5, 31, v4
	v_lshlrev_b64 v[4:5], 12, v[4:5]
	v_lshl_add_u64 v[4:5], s[4:5], 0, v[4:5]
	v_lshl_add_u64 v[82:83], v[4:5], 0, v[2:3]
	v_or_b32_e32 v4, v10, v163
	v_ashrrev_i32_e32 v5, 31, v4
	v_lshlrev_b64 v[4:5], 12, v[4:5]
	v_lshl_add_u64 v[4:5], s[4:5], 0, v[4:5]
	v_lshl_add_u64 v[80:81], v[4:5], 0, v[2:3]
	v_or_b32_e32 v4, v10, v164
	v_ashrrev_i32_e32 v5, 31, v4
	v_lshlrev_b64 v[4:5], 12, v[4:5]
	v_lshl_add_u64 v[4:5], s[4:5], 0, v[4:5]
	v_lshl_add_u64 v[76:77], v[4:5], 0, v[2:3]
	v_or_b32_e32 v4, v10, v166
	v_ashrrev_i32_e32 v5, 31, v4
	v_lshlrev_b64 v[4:5], 12, v[4:5]
	v_lshl_add_u64 v[4:5], s[4:5], 0, v[4:5]
	v_lshl_add_u64 v[72:73], v[4:5], 0, v[2:3]
	v_or_b32_e32 v4, v10, v167
	v_ashrrev_i32_e32 v5, 31, v4
	v_lshlrev_b64 v[4:5], 12, v[4:5]
	v_lshl_add_u64 v[4:5], s[4:5], 0, v[4:5]
	s_mul_i32 s24, s35, 0x1800
	v_lshl_add_u64 v[66:67], v[4:5], 0, v[2:3]
	v_or_b32_e32 v4, v10, v168
	s_ashr_i32 s25, s24, 31
	v_ashrrev_i32_e32 v5, 31, v4
	s_lshl_b64 s[24:25], s[24:25], 2
	v_lshlrev_b64 v[4:5], 12, v[4:5]
	s_add_u32 s24, s6, s24
	v_lshl_add_u64 v[4:5], s[4:5], 0, v[4:5]
	s_addc_u32 s25, s7, s25
	v_cmp_gt_i32_e32 vcc, s30, v6
	v_ashrrev_i32_e32 v7, 31, v6
	v_lshl_add_u64 v[64:65], v[4:5], 0, v[2:3]
	v_or_b32_e32 v4, v10, v169
	s_add_u32 s24, s24, 0x2000
	v_cndmask_b32_e32 v7, 0, v7, vcc
	v_cndmask_b32_e32 v6, v8, v6, vcc
	v_ashrrev_i32_e32 v5, 31, v4
	s_addc_u32 s25, s25, 0
	v_cndmask_b32_e32 v9, v11, v12, vcc
	v_cndmask_b32_e32 v8, v13, v14, vcc
	v_lshlrev_b64 v[6:7], 12, v[6:7]
	v_lshlrev_b64 v[4:5], 12, v[4:5]
	v_lshl_add_u64 v[22:23], s[24:25], 0, v[2:3]
	v_lshl_add_u64 v[6:7], v[8:9], 0, v[6:7]
	v_lshl_add_u64 v[4:5], s[4:5], 0, v[4:5]
	s_waitcnt vmcnt(0) lgkmcnt(0)
	s_barrier
	v_lshl_add_u64 v[126:127], v[6:7], 0, v[2:3]
	v_lshl_add_u64 v[62:63], v[4:5], 0, v[2:3]
	global_load_dwordx4 v[2:5], v[22:23], off
	global_load_dwordx4 v[6:9], v[126:127], off
	global_load_dwordx4 v[10:13], v[124:125], off
	global_load_dwordx4 v[14:17], v[122:123], off
	global_load_dwordx4 v[18:21], v[120:121], off
	s_nop 0
	global_load_dwordx4 v[22:25], v[118:119], off
	global_load_dwordx4 v[26:29], v[116:117], off
	global_load_dwordx4 v[30:33], v[114:115], off
	global_load_dwordx4 v[34:37], v[110:111], off
	global_load_dwordx4 v[38:41], v[106:107], off
	global_load_dwordx4 v[42:45], v[100:101], off
	global_load_dwordx4 v[46:49], v[94:95], off
	global_load_dwordx4 v[50:53], v[90:91], off
	global_load_dwordx4 v[54:57], v[84:85], off
	global_load_dwordx4 v[58:61], v[78:79], off
	global_load_dwordx4 v[136:139], v[74:75], off
	global_load_dwordx4 v[140:143], v[68:69], off
	ds_read_b64 v[128:129], v151
	s_cmp_lt_i32 s27, s26
	s_waitcnt lgkmcnt(0)
	v_lshlrev_b32_e32 v176, 16, v128
	v_and_b32_e32 v177, 0xffff0000, v128
	v_lshlrev_b32_e32 v128, 16, v129
	v_and_b32_e32 v129, 0xffff0000, v129
	s_waitcnt vmcnt(0)
	v_pk_fma_f32 v[142:143], v[4:5], v[128:129], v[142:143]
	ds_read_b64 v[128:129], v151 offset:4224
	v_pk_fma_f32 v[140:141], v[2:3], v[176:177], v[140:141]
	global_store_dwordx4 v[112:113], v[140:143], off
	s_waitcnt lgkmcnt(0)
	s_nop 0
	v_lshlrev_b32_e32 v140, 16, v128
	v_and_b32_e32 v141, 0xffff0000, v128
	v_lshlrev_b32_e32 v128, 16, v129
	v_and_b32_e32 v129, 0xffff0000, v129
	v_pk_fma_f32 v[138:139], v[4:5], v[128:129], v[138:139]
	ds_read_b64 v[128:129], v151 offset:8448
	v_pk_fma_f32 v[136:137], v[2:3], v[140:141], v[136:137]
	global_store_dwordx4 v[108:109], v[136:139], off
	s_waitcnt lgkmcnt(0)
	s_nop 0
	v_lshlrev_b32_e32 v136, 16, v128
	v_and_b32_e32 v137, 0xffff0000, v128
	v_lshlrev_b32_e32 v128, 16, v129
	v_and_b32_e32 v129, 0xffff0000, v129
	v_pk_fma_f32 v[58:59], v[2:3], v[136:137], v[58:59]
	v_pk_fma_f32 v[60:61], v[4:5], v[128:129], v[60:61]
	global_store_dwordx4 v[104:105], v[58:61], off
	ds_read_b64 v[58:59], v155
	s_waitcnt lgkmcnt(0)
	v_lshlrev_b32_e32 v60, 16, v58
	v_and_b32_e32 v61, 0xffff0000, v58
	v_lshlrev_b32_e32 v58, 16, v59
	v_and_b32_e32 v59, 0xffff0000, v59
	v_pk_fma_f32 v[54:55], v[2:3], v[60:61], v[54:55]
	v_pk_fma_f32 v[56:57], v[4:5], v[58:59], v[56:57]
	global_store_dwordx4 v[102:103], v[54:57], off
	ds_read_b64 v[54:55], v151 offset:16896
	s_waitcnt lgkmcnt(0)
	v_lshlrev_b32_e32 v56, 16, v54
	v_and_b32_e32 v57, 0xffff0000, v54
	v_lshlrev_b32_e32 v54, 16, v55
	v_and_b32_e32 v55, 0xffff0000, v55
	v_pk_fma_f32 v[50:51], v[2:3], v[56:57], v[50:51]
	v_pk_fma_f32 v[52:53], v[4:5], v[54:55], v[52:53]
	global_store_dwordx4 v[98:99], v[50:53], off
	ds_read_b64 v[50:51], v151 offset:21120
	s_waitcnt lgkmcnt(0)
	v_lshlrev_b32_e32 v52, 16, v50
	v_and_b32_e32 v53, 0xffff0000, v50
	v_lshlrev_b32_e32 v50, 16, v51
	v_and_b32_e32 v51, 0xffff0000, v51
	v_pk_fma_f32 v[46:47], v[2:3], v[52:53], v[46:47]
	v_pk_fma_f32 v[48:49], v[4:5], v[50:51], v[48:49]
	global_store_dwordx4 v[96:97], v[46:49], off
	ds_read_b64 v[46:47], v151 offset:25344
	s_waitcnt lgkmcnt(0)
; template <typename FA, typename FB, typename FE>
; DI void gemm_tile(char* lds, int K, int astride, int bstride, FA arow, FB brow, FE epi) {
;     ...
;     epi(vb, 1, vtid);
; DI void phase4(const Params& p, char* lds) {
;     ...
; #pragma unroll
;       for (int ps = 0; ps < 16; ++ps) {
;         const int row = ps * 8 + (tid >> 5), t = t0h + row;
;         float4 c = cs4(Cs, row, c4);
;         float4 o = make_float4(xv[ps].x + g1.x * c.x, xv[ps].y + g1.y * c.y, xv[ps].z + g1.z * c.z, xv[ps].w + g1.w * c.w);
;         *(float4*)(p.out + (size_t)t * D + col) = o;
;       }
	v_lshlrev_b32_e32 v48, 16, v46
	v_and_b32_e32 v49, 0xffff0000, v46
	v_lshlrev_b32_e32 v46, 16, v47
	v_and_b32_e32 v47, 0xffff0000, v47
	v_pk_fma_f32 v[42:43], v[2:3], v[48:49], v[42:43]
	v_pk_fma_f32 v[44:45], v[4:5], v[46:47], v[44:45]
	global_store_dwordx4 v[92:93], v[42:45], off
	ds_read_b64 v[42:43], v160
	s_waitcnt lgkmcnt(0)
	v_lshlrev_b32_e32 v44, 16, v42
	v_and_b32_e32 v45, 0xffff0000, v42
	v_lshlrev_b32_e32 v42, 16, v43
	v_and_b32_e32 v43, 0xffff0000, v43
	v_pk_fma_f32 v[38:39], v[2:3], v[44:45], v[38:39]
	v_pk_fma_f32 v[40:41], v[4:5], v[42:43], v[40:41]
	global_store_dwordx4 v[88:89], v[38:41], off
	ds_read_b64 v[38:39], v151 offset:33792
	s_waitcnt lgkmcnt(0)
	v_lshlrev_b32_e32 v40, 16, v38
	v_and_b32_e32 v41, 0xffff0000, v38
	v_lshlrev_b32_e32 v38, 16, v39
	v_and_b32_e32 v39, 0xffff0000, v39
	v_pk_fma_f32 v[34:35], v[2:3], v[40:41], v[34:35]
	v_pk_fma_f32 v[36:37], v[4:5], v[38:39], v[36:37]
	global_store_dwordx4 v[86:87], v[34:37], off
	ds_read_b64 v[34:35], v151 offset:38016
	s_waitcnt lgkmcnt(0)
	v_lshlrev_b32_e32 v36, 16, v34
	v_and_b32_e32 v37, 0xffff0000, v34
	v_lshlrev_b32_e32 v34, 16, v35
	v_and_b32_e32 v35, 0xffff0000, v35
	v_pk_fma_f32 v[30:31], v[2:3], v[36:37], v[30:31]
	v_pk_fma_f32 v[32:33], v[4:5], v[34:35], v[32:33]
	global_store_dwordx4 v[82:83], v[30:33], off
	ds_read_b64 v[30:31], v151 offset:42240
	s_waitcnt lgkmcnt(0)
	v_lshlrev_b32_e32 v32, 16, v30
	v_and_b32_e32 v33, 0xffff0000, v30
	v_lshlrev_b32_e32 v30, 16, v31
	v_and_b32_e32 v31, 0xffff0000, v31
	v_pk_fma_f32 v[26:27], v[2:3], v[32:33], v[26:27]
	v_pk_fma_f32 v[28:29], v[4:5], v[30:31], v[28:29]
	global_store_dwordx4 v[80:81], v[26:29], off
	ds_read_b64 v[26:27], v165
	s_waitcnt lgkmcnt(0)
	v_lshlrev_b32_e32 v28, 16, v26
	v_and_b32_e32 v29, 0xffff0000, v26
	v_lshlrev_b32_e32 v26, 16, v27
	v_and_b32_e32 v27, 0xffff0000, v27
	v_pk_fma_f32 v[22:23], v[2:3], v[28:29], v[22:23]
	v_pk_fma_f32 v[24:25], v[4:5], v[26:27], v[24:25]
	global_store_dwordx4 v[76:77], v[22:25], off
	ds_read_b64 v[22:23], v151 offset:50688
	s_waitcnt lgkmcnt(0)
	v_lshlrev_b32_e32 v24, 16, v22
	v_and_b32_e32 v25, 0xffff0000, v22
	v_lshlrev_b32_e32 v22, 16, v23
	v_and_b32_e32 v23, 0xffff0000, v23
	v_pk_fma_f32 v[18:19], v[2:3], v[24:25], v[18:19]
	v_pk_fma_f32 v[20:21], v[4:5], v[22:23], v[20:21]
	global_store_dwordx4 v[72:73], v[18:21], off
	ds_read_b64 v[18:19], v151 offset:54912
	s_waitcnt lgkmcnt(0)
	v_lshlrev_b32_e32 v20, 16, v18
	v_and_b32_e32 v21, 0xffff0000, v18
	v_lshlrev_b32_e32 v18, 16, v19
	v_and_b32_e32 v19, 0xffff0000, v19
	v_pk_fma_f32 v[14:15], v[2:3], v[20:21], v[14:15]
	v_pk_fma_f32 v[16:17], v[4:5], v[18:19], v[16:17]
	global_store_dwordx4 v[66:67], v[14:17], off
	ds_read_b64 v[14:15], v151 offset:59136
	s_waitcnt lgkmcnt(0)
	v_lshlrev_b32_e32 v16, 16, v14
	v_and_b32_e32 v17, 0xffff0000, v14
	v_lshlrev_b32_e32 v14, 16, v15
	v_and_b32_e32 v15, 0xffff0000, v15
	v_pk_fma_f32 v[10:11], v[2:3], v[16:17], v[10:11]
	v_pk_fma_f32 v[12:13], v[4:5], v[14:15], v[12:13]
	global_store_dwordx4 v[64:65], v[10:13], off
	ds_read_b64 v[10:11], v170
	s_waitcnt lgkmcnt(0)
	v_lshlrev_b32_e32 v12, 16, v10
	v_and_b32_e32 v13, 0xffff0000, v10
	v_lshlrev_b32_e32 v10, 16, v11
	v_and_b32_e32 v11, 0xffff0000, v11
	v_pk_fma_f32 v[2:3], v[2:3], v[12:13], v[6:7]
	v_pk_fma_f32 v[4:5], v[4:5], v[10:11], v[8:9]
	global_store_dwordx4 v[62:63], v[2:5], off
	s_nop 1
	v_or_b32_e32 v2, 0x80, v70
	v_ashrrev_i32_e32 v3, 31, v2
	v_lshl_add_u64 v[2:3], v[2:3], 2, s[24:25]
	global_load_dwordx4 v[2:5], v[2:3], off
	s_nop 0
	global_load_dwordx4 v[6:9], v[126:127], off offset:512
	global_load_dwordx4 v[10:13], v[124:125], off offset:512
	global_load_dwordx4 v[14:17], v[122:123], off offset:512
	global_load_dwordx4 v[18:21], v[120:121], off offset:512
	global_load_dwordx4 v[22:25], v[118:119], off offset:512
	global_load_dwordx4 v[26:29], v[116:117], off offset:512
	global_load_dwordx4 v[30:33], v[114:115], off offset:512
	global_load_dwordx4 v[34:37], v[110:111], off offset:512
	global_load_dwordx4 v[38:41], v[106:107], off offset:512
	global_load_dwordx4 v[42:45], v[100:101], off offset:512
	global_load_dwordx4 v[46:49], v[94:95], off offset:512
	global_load_dwordx4 v[50:53], v[90:91], off offset:512
	global_load_dwordx4 v[54:57], v[84:85], off offset:512
	global_load_dwordx4 v[58:61], v[78:79], off offset:512
	global_load_dwordx4 v[114:117], v[74:75], off offset:512
	s_nop 0
	global_load_dwordx4 v[68:71], v[68:69], off offset:512
	ds_read_b64 v[74:75], v151 offset:256
	s_waitcnt lgkmcnt(0)
	v_lshlrev_b32_e32 v78, 16, v74
	v_and_b32_e32 v79, 0xffff0000, v74
	v_lshlrev_b32_e32 v74, 16, v75
	v_and_b32_e32 v75, 0xffff0000, v75
	s_waitcnt vmcnt(0)
	v_pk_fma_f32 v[68:69], v[2:3], v[78:79], v[68:69]
	v_pk_fma_f32 v[70:71], v[4:5], v[74:75], v[70:71]
	global_store_dwordx4 v[112:113], v[68:71], off offset:512
	ds_read_b64 v[68:69], v151 offset:4480
	s_waitcnt lgkmcnt(0)
	v_lshlrev_b32_e32 v74, 16, v69
	v_lshlrev_b32_e32 v70, 16, v68
	v_and_b32_e32 v71, 0xffff0000, v68
	v_and_b32_e32 v75, 0xffff0000, v69
	v_pk_fma_f32 v[68:69], v[2:3], v[70:71], v[114:115]
	v_pk_fma_f32 v[70:71], v[4:5], v[74:75], v[116:117]
	global_store_dwordx4 v[108:109], v[68:71], off offset:512
	ds_read_b64 v[68:69], v151 offset:8704
	s_waitcnt lgkmcnt(0)
; DI void phase4(const Params& p, char* lds) {
;     ...
; #pragma unroll
;       for (int ps = 0; ps < 16; ++ps) {
;         const int row = ps * 8 + (tid >> 5), t = t0h + row;
;         float4 c = cs4(Cs, row, c4);
;         float4 o = make_float4(xv[ps].x + g1.x * c.x, xv[ps].y + g1.y * c.y, xv[ps].z + g1.z * c.z, xv[ps].w + g1.w * c.w);
;         *(float4*)(p.out + (size_t)t * D + col) = o;
;       }
;     };
;     gemm_tile(lds, 1024, 32, 1024 * 32, arow, brow, epi);
	v_lshlrev_b32_e32 v70, 16, v68
	v_and_b32_e32 v71, 0xffff0000, v68
	v_lshlrev_b32_e32 v68, 16, v69
	v_and_b32_e32 v69, 0xffff0000, v69
	v_pk_fma_f32 v[58:59], v[2:3], v[70:71], v[58:59]
	v_pk_fma_f32 v[60:61], v[4:5], v[68:69], v[60:61]
	global_store_dwordx4 v[104:105], v[58:61], off offset:512
	ds_read_b64 v[58:59], v155 offset:256
	s_waitcnt lgkmcnt(0)
	v_lshlrev_b32_e32 v60, 16, v58
	v_and_b32_e32 v61, 0xffff0000, v58
	v_lshlrev_b32_e32 v58, 16, v59
	v_and_b32_e32 v59, 0xffff0000, v59
	v_pk_fma_f32 v[54:55], v[2:3], v[60:61], v[54:55]
	v_pk_fma_f32 v[56:57], v[4:5], v[58:59], v[56:57]
	global_store_dwordx4 v[102:103], v[54:57], off offset:512
	ds_read_b64 v[54:55], v151 offset:17152
	s_waitcnt lgkmcnt(0)
	v_lshlrev_b32_e32 v56, 16, v54
	v_and_b32_e32 v57, 0xffff0000, v54
	v_lshlrev_b32_e32 v54, 16, v55
	v_and_b32_e32 v55, 0xffff0000, v55
	v_pk_fma_f32 v[50:51], v[2:3], v[56:57], v[50:51]
	v_pk_fma_f32 v[52:53], v[4:5], v[54:55], v[52:53]
	global_store_dwordx4 v[98:99], v[50:53], off offset:512
	ds_read_b64 v[50:51], v151 offset:21376
	s_waitcnt lgkmcnt(0)
	v_lshlrev_b32_e32 v52, 16, v50
	v_and_b32_e32 v53, 0xffff0000, v50
	v_lshlrev_b32_e32 v50, 16, v51
	v_and_b32_e32 v51, 0xffff0000, v51
	v_pk_fma_f32 v[46:47], v[2:3], v[52:53], v[46:47]
	v_pk_fma_f32 v[48:49], v[4:5], v[50:51], v[48:49]
	global_store_dwordx4 v[96:97], v[46:49], off offset:512
	ds_read_b64 v[46:47], v151 offset:25600
	s_waitcnt lgkmcnt(0)
	v_lshlrev_b32_e32 v48, 16, v46
	v_and_b32_e32 v49, 0xffff0000, v46
	v_lshlrev_b32_e32 v46, 16, v47
	v_and_b32_e32 v47, 0xffff0000, v47
	v_pk_fma_f32 v[42:43], v[2:3], v[48:49], v[42:43]
	v_pk_fma_f32 v[44:45], v[4:5], v[46:47], v[44:45]
	global_store_dwordx4 v[92:93], v[42:45], off offset:512
	ds_read_b64 v[42:43], v160 offset:256
	s_waitcnt lgkmcnt(0)
	v_lshlrev_b32_e32 v44, 16, v42
	v_and_b32_e32 v45, 0xffff0000, v42
	v_lshlrev_b32_e32 v42, 16, v43
	v_and_b32_e32 v43, 0xffff0000, v43
	v_pk_fma_f32 v[38:39], v[2:3], v[44:45], v[38:39]
	v_pk_fma_f32 v[40:41], v[4:5], v[42:43], v[40:41]
	global_store_dwordx4 v[88:89], v[38:41], off offset:512
	ds_read_b64 v[38:39], v151 offset:34048
	s_waitcnt lgkmcnt(0)
	v_lshlrev_b32_e32 v40, 16, v38
	v_and_b32_e32 v41, 0xffff0000, v38
	v_lshlrev_b32_e32 v38, 16, v39
	v_and_b32_e32 v39, 0xffff0000, v39
	v_pk_fma_f32 v[34:35], v[2:3], v[40:41], v[34:35]
	v_pk_fma_f32 v[36:37], v[4:5], v[38:39], v[36:37]
	global_store_dwordx4 v[86:87], v[34:37], off offset:512
	ds_read_b64 v[34:35], v151 offset:38272
	s_waitcnt lgkmcnt(0)
	v_lshlrev_b32_e32 v36, 16, v34
	v_and_b32_e32 v37, 0xffff0000, v34
	v_lshlrev_b32_e32 v34, 16, v35
	v_and_b32_e32 v35, 0xffff0000, v35
	v_pk_fma_f32 v[30:31], v[2:3], v[36:37], v[30:31]
	v_pk_fma_f32 v[32:33], v[4:5], v[34:35], v[32:33]
	global_store_dwordx4 v[82:83], v[30:33], off offset:512
	ds_read_b64 v[30:31], v151 offset:42496
	s_waitcnt lgkmcnt(0)
	v_lshlrev_b32_e32 v32, 16, v30
	v_and_b32_e32 v33, 0xffff0000, v30
	v_lshlrev_b32_e32 v30, 16, v31
	v_and_b32_e32 v31, 0xffff0000, v31
	v_pk_fma_f32 v[26:27], v[2:3], v[32:33], v[26:27]
	v_pk_fma_f32 v[28:29], v[4:5], v[30:31], v[28:29]
	global_store_dwordx4 v[80:81], v[26:29], off offset:512
	ds_read_b64 v[26:27], v165 offset:256
	s_waitcnt lgkmcnt(0)
	v_lshlrev_b32_e32 v28, 16, v26
	v_and_b32_e32 v29, 0xffff0000, v26
	v_lshlrev_b32_e32 v26, 16, v27
	v_and_b32_e32 v27, 0xffff0000, v27
	v_pk_fma_f32 v[22:23], v[2:3], v[28:29], v[22:23]
	v_pk_fma_f32 v[24:25], v[4:5], v[26:27], v[24:25]
	global_store_dwordx4 v[76:77], v[22:25], off offset:512
	ds_read_b64 v[22:23], v151 offset:50944
	s_waitcnt lgkmcnt(0)
	v_lshlrev_b32_e32 v24, 16, v22
	v_and_b32_e32 v25, 0xffff0000, v22
	v_lshlrev_b32_e32 v22, 16, v23
	v_and_b32_e32 v23, 0xffff0000, v23
	v_pk_fma_f32 v[18:19], v[2:3], v[24:25], v[18:19]
	v_pk_fma_f32 v[20:21], v[4:5], v[22:23], v[20:21]
	global_store_dwordx4 v[72:73], v[18:21], off offset:512
	ds_read_b64 v[18:19], v151 offset:55168
	s_waitcnt lgkmcnt(0)
	v_lshlrev_b32_e32 v20, 16, v18
	v_and_b32_e32 v21, 0xffff0000, v18
	v_lshlrev_b32_e32 v18, 16, v19
	v_and_b32_e32 v19, 0xffff0000, v19
	v_pk_fma_f32 v[14:15], v[2:3], v[20:21], v[14:15]
	v_pk_fma_f32 v[16:17], v[4:5], v[18:19], v[16:17]
	global_store_dwordx4 v[66:67], v[14:17], off offset:512
	ds_read_b64 v[14:15], v151 offset:59392
	s_waitcnt lgkmcnt(0)
	v_lshlrev_b32_e32 v16, 16, v14
	v_and_b32_e32 v17, 0xffff0000, v14
	v_lshlrev_b32_e32 v14, 16, v15
	v_and_b32_e32 v15, 0xffff0000, v15
	v_pk_fma_f32 v[10:11], v[2:3], v[16:17], v[10:11]
	v_pk_fma_f32 v[12:13], v[4:5], v[14:15], v[12:13]
	global_store_dwordx4 v[64:65], v[10:13], off offset:512
	ds_read_b64 v[10:11], v170 offset:256
	s_waitcnt lgkmcnt(0)
	v_lshlrev_b32_e32 v12, 16, v10
	v_and_b32_e32 v13, 0xffff0000, v10
	v_lshlrev_b32_e32 v10, 16, v11
	v_and_b32_e32 v11, 0xffff0000, v11
	v_pk_fma_f32 v[2:3], v[2:3], v[12:13], v[6:7]
	v_pk_fma_f32 v[4:5], v[4:5], v[10:11], v[8:9]
	global_store_dwordx4 v[62:63], v[2:5], off offset:512
	s_barrier
	s_cbranch_scc1 .LBB0_229

; #define MFMA(a, b, c) __builtin_amdgcn_mfma_f32_32x32x16_bf16((a), (b), (c), 0, 0, 0)
; #define WAIT_V(n) asm volatile("s_waitcnt vmcnt(%0)" ::"n"(n) : "memory")
; #define RAW_BARRIER() do { asm volatile("s_waitcnt lgkmcnt(0)" ::: "memory"); __builtin_amdgcn_s_barrier(); } while (0)
; template <typename FA, typename FB, typename FE>
; DI void gemm_tile(char* lds, int K, int astride, int bstride, FA arow, FB brow, FE epi) {
;     ...
;   stage(0, 0); stage(1, 1); stage(2, 2);
;   for (int kt = 0; kt < nk; ++kt) {
;     if (kt + 2 < nk) WAIT_V(8); else if (kt + 1 < nk) WAIT_V(4); else WAIT_V(0);
;     RAW_BARRIER();
;     if (kt + 3 < nk) stage((kt + 3) & 3, kt + 3);
;     const char* sa = lds + (kt & 3) * 32768 + wm * 4096;
;     const char* sb = lds + (kt & 3) * 32768 + 16384 + wn * 8192;
; #pragma unroll
;     for (int ks = 0; ks < 2; ++ks) {
;       bf16x8 a0 = *(const bf16x8*)(sa + foff[ks]), a1 = *(const bf16x8*)(sa + 2048 + foff[ks]);
; #pragma unroll
;       for (int nt = 0; nt < 4; ++nt) {
;         bf16x8 bb = *(const bf16x8*)(sb + nt * 2048 + foff[ks]);
;         acc[0][nt] = MFMA(a0, bb, acc[0][nt]);
;         acc[1][nt] = MFMA(a1, bb, acc[1][nt]);
;       }
;     }
;   }
.LBB0_299:
	s_waitcnt lgkmcnt(0)
	s_waitcnt vmcnt(8)
	s_barrier
	s_add_i32 s42, s24, 0xfffe8000
	s_and_b32 s42, s42, 0x18000
	s_add_i32 s43, s42, s40
	s_or_b32 s42, s42, s27
	v_add_u32_e32 v244, s43, v159
	v_add_u32_e32 v245, s42, v159
	ds_read_b128 v[196:199], v244
	ds_read_b128 v[204:207], v245 offset:16384
	ds_read_b128 v[200:203], v244 offset:2048
	ds_read_b128 v[208:211], v245 offset:18432
	ds_read_b128 v[212:215], v245 offset:20480
	ds_read_b128 v[216:219], v245 offset:22528
	.p2align 6
.Lgm_P6_loop:
	s_and_b32 s25, s24, 0x18000
	s_add_i32 s25, s41, s25
	s_waitcnt vmcnt(4)
	v_lshl_add_u64 v[138:139], v[134:135], 0, v[150:151]
	v_lshl_add_u64 v[140:141], v[130:131], 0, v[150:151]
	s_mov_b32 m0, s25
	s_barrier
	s_add_i32 s42, s24, 0xfffe8000
	s_and_b32 s42, s42, 0x18000
	s_add_i32 s43, s42, s40
	s_or_b32 s42, s42, s27
	v_add_u32_e32 v246, s43, v160
	v_add_u32_e32 v247, s42, v160
	s_waitcnt lgkmcnt(4)
	v_mfma_f32_32x32x16_bf16 v[114:129], v[196:199], v[204:207], v[114:129]
	global_load_lds_dwordx4 v[138:139], off
	s_add_i32 m0, s25, 0x4000
	ds_read_b128 v[220:223], v246
	s_waitcnt lgkmcnt(4)
	v_mfma_f32_32x32x16_bf16 v[50:65], v[200:203], v[204:207], v[50:65]
	v_lshl_add_u64 v[142:143], v[136:137], 0, v[150:151]
	global_load_lds_dwordx4 v[140:141], off
	s_add_i32 m0, s25, 0x400
	ds_read_b128 v[228:231], v247 offset:16384
	s_waitcnt lgkmcnt(4)
	v_mfma_f32_32x32x16_bf16 v[98:113], v[196:199], v[208:211], v[98:113]
	v_lshl_add_u64 v[144:145], v[132:133], 0, v[150:151]
	global_load_lds_dwordx4 v[142:143], off
	s_add_i32 m0, s25, 0x4400
	ds_read_b128 v[224:227], v246 offset:2048
	v_mfma_f32_32x32x16_bf16 v[34:49], v[200:203], v[208:211], v[34:49]
	ds_read_b128 v[232:235], v247 offset:18432
	global_load_lds_dwordx4 v[144:145], off
	s_waitcnt lgkmcnt(5)
	v_mfma_f32_32x32x16_bf16 v[82:97], v[196:199], v[212:215], v[82:97]
	ds_read_b128 v[236:239], v247 offset:20480
	v_lshl_add_u64 v[130:131], v[130:131], 0, s[18:19]
	v_lshl_add_u64 v[132:133], v[132:133], 0, s[18:19]
	v_mfma_f32_32x32x16_bf16 v[18:33], v[200:203], v[212:215], v[18:33]
	ds_read_b128 v[240:243], v247 offset:22528
	v_lshl_add_u64 v[134:135], v[134:135], 0, 64
	v_lshl_add_u64 v[136:137], v[136:137], 0, 64
	s_waitcnt lgkmcnt(6)
	v_mfma_f32_32x32x16_bf16 v[66:81], v[196:199], v[216:219], v[66:81]
	s_add_i32 s42, s24, 0xffff0000
	s_and_b32 s42, s42, 0x18000
	s_add_i32 s43, s42, s40
	v_mfma_f32_32x32x16_bf16 v[2:17], v[200:203], v[216:219], v[2:17]
	s_or_b32 s42, s42, s27
	v_add_u32_e32 v244, s43, v159
	v_add_u32_e32 v245, s42, v159
	s_waitcnt lgkmcnt(4)
	v_mfma_f32_32x32x16_bf16 v[114:129], v[220:223], v[228:231], v[114:129]
	ds_read_b128 v[196:199], v244
	s_waitcnt lgkmcnt(4)
	v_mfma_f32_32x32x16_bf16 v[50:65], v[224:227], v[228:231], v[50:65]
	ds_read_b128 v[204:207], v245 offset:16384
	s_waitcnt lgkmcnt(4)
	v_mfma_f32_32x32x16_bf16 v[98:113], v[220:223], v[232:235], v[98:113]
	ds_read_b128 v[200:203], v244 offset:2048
	v_mfma_f32_32x32x16_bf16 v[34:49], v[224:227], v[232:235], v[34:49]
	ds_read_b128 v[208:211], v245 offset:18432
	s_waitcnt lgkmcnt(5)
	v_mfma_f32_32x32x16_bf16 v[82:97], v[220:223], v[236:239], v[82:97]
	ds_read_b128 v[212:215], v245 offset:20480
	v_mfma_f32_32x32x16_bf16 v[18:33], v[224:227], v[236:239], v[18:33]
	ds_read_b128 v[216:219], v245 offset:22528
	s_waitcnt lgkmcnt(6)
	v_mfma_f32_32x32x16_bf16 v[66:81], v[220:223], v[240:243], v[66:81]
	s_add_i32 s24, s24, 0x8000
	v_mfma_f32_32x32x16_bf16 v[2:17], v[224:227], v[240:243], v[2:17]
	s_cmp_eq_u32 s24, 0x100000
	s_cbranch_scc0 .Lgm_P6_loop
	s_waitcnt vmcnt(8)
	v_add_u32_e32 v138, s40, v159
	s_waitcnt lgkmcnt(0)
	s_barrier
	ds_read_b128 v[130:133], v138 offset:32768
	ds_read_b128 v[138:141], v138 offset:34816
	v_add_u32_e32 v142, s27, v159
	ds_read_b128 v[134:137], v142 offset:49152
	v_add_u32_e32 v143, s27, v160
	s_add_i32 s24, s40, 0x10000
	s_waitcnt lgkmcnt(0)
	v_mfma_f32_32x32x16_bf16 v[114:129], v[130:133], v[134:137], v[114:129]
	s_or_b32 s25, s27, 0x14000
	v_add_u32_e32 v169, s25, v159
	v_add_u32_e32 v182, s24, v160
	v_mfma_f32_32x32x16_bf16 v[50:65], v[138:141], v[134:137], v[50:65]
	ds_read_b128 v[134:137], v142 offset:51200
	s_waitcnt lgkmcnt(0)
	v_mfma_f32_32x32x16_bf16 v[98:113], v[130:133], v[134:137], v[98:113]
	v_mfma_f32_32x32x16_bf16 v[34:49], v[138:141], v[134:137], v[34:49]
	ds_read_b128 v[134:137], v142 offset:53248
	s_waitcnt lgkmcnt(0)
	v_mfma_f32_32x32x16_bf16 v[82:97], v[130:133], v[134:137], v[82:97]
	v_mfma_f32_32x32x16_bf16 v[18:33], v[138:141], v[134:137], v[18:33]
	ds_read_b128 v[134:137], v142 offset:55296
	v_add_u32_e32 v142, s40, v160
	s_add_i32 s40, s40, 0x18000
	v_add_u32_e32 v202, s40, v160
	s_waitcnt lgkmcnt(0)
	v_mfma_f32_32x32x16_bf16 v[66:81], v[130:133], v[134:137], v[66:81]
	ds_read_b128 v[130:133], v142 offset:32768
	v_mfma_f32_32x32x16_bf16 v[2:17], v[138:141], v[134:137], v[2:17]
	ds_read_b128 v[138:141], v142 offset:34816
	ds_read_b128 v[134:137], v143 offset:49152
	v_add_u32_e32 v142, s24, v159
	s_or_b32 s24, s27, 0x1c000
	v_add_u32_e32 v234, s24, v159
	v_add_u32_e32 v226, s24, v160
	s_waitcnt lgkmcnt(0)
	v_mfma_f32_32x32x16_bf16 v[114:129], v[130:133], v[134:137], v[114:129]
	v_mfma_f32_32x32x16_bf16 v[50:65], v[138:141], v[134:137], v[50:65]
	ds_read_b128 v[134:137], v143 offset:51200
	s_waitcnt lgkmcnt(0)
	v_mfma_f32_32x32x16_bf16 v[98:113], v[130:133], v[134:137], v[98:113]
	v_mfma_f32_32x32x16_bf16 v[34:49], v[138:141], v[134:137], v[34:49]
	ds_read_b128 v[134:137], v143 offset:53248
	s_waitcnt lgkmcnt(0)
	v_mfma_f32_32x32x16_bf16 v[82:97], v[130:133], v[134:137], v[82:97]
	v_mfma_f32_32x32x16_bf16 v[18:33], v[138:141], v[134:137], v[18:33]
	ds_read_b128 v[134:137], v143 offset:55296
	s_waitcnt vmcnt(4)
	s_waitcnt lgkmcnt(0)
	s_barrier
; #define MFMA(a, b, c) __builtin_amdgcn_mfma_f32_32x32x16_bf16((a), (b), (c), 0, 0, 0)
; DI unsigned pk2(float a, float b) { fl2_t f = {a, b}; bf2_t r = __builtin_convertvector(f, bf2_t); return __builtin_bit_cast(unsigned, r); }
; #define RAW_BARRIER() do { asm volatile("s_waitcnt lgkmcnt(0)" ::: "memory"); __builtin_amdgcn_s_barrier(); } while (0)
; template <typename FA, typename FB, typename FE>
; DI void gemm_tile(char* lds, int K, int astride, int bstride, FA arow, FB brow, FE epi) {
;     ...
;       bf16x8 a0 = *(const bf16x8*)(sa + foff[ks]), a1 = *(const bf16x8*)(sa + 2048 + foff[ks]);
; #pragma unroll
;       for (int nt = 0; nt < 4; ++nt) {
;         bf16x8 bb = *(const bf16x8*)(sb + nt * 2048 + foff[ks]);
;         acc[0][nt] = MFMA(a0, bb, acc[0][nt]);
;         acc[1][nt] = MFMA(a1, bb, acc[1][nt]);
;       }
;     }
;   }
;   RAW_BARRIER();
;   bfr* Cs = (bfr*)lds;
; #pragma unroll
;   for (int mt = 0; mt < 2; ++mt)
; #pragma unroll
;     for (int nt = 0; nt < 4; ++nt)
; #pragma unroll
;       for (int i = 0; i < 16; i += 2) {
;         const int row = wm * 64 + mt * 32 + (i & 3) + 8 * (i >> 2) + 4 * h8;
;         const unsigned pr = pk2(acc[mt][nt][i], acc[mt][nt][i + 1]);
;         Cs[row * CSS + wn * 128 + nt * 32 + r] = (bfr)(pr & 0xffffu);
;         Cs[(row + 1) * CSS + wn * 128 + nt * 32 + r] = (bfr)(pr >> 16);
;       }
	ds_read_b128 v[170:173], v142
	s_waitcnt lgkmcnt(0)
	v_mfma_f32_32x32x16_bf16 v[66:81], v[130:133], v[134:137], v[66:81]
	ds_read_b128 v[130:133], v169
	v_mfma_f32_32x32x16_bf16 v[2:17], v[138:141], v[134:137], v[2:17]
	ds_read_b128 v[134:137], v142 offset:2048
	ds_read_b128 v[142:145], v169 offset:2048
	v_add_u32_e32 v138, s25, v160
	s_waitcnt lgkmcnt(0)
	v_mfma_f32_32x32x16_bf16 v[114:129], v[170:173], v[130:133], v[114:129]
	v_mfma_f32_32x32x16_bf16 v[50:65], v[134:137], v[130:133], v[50:65]
	ds_read_b128 v[130:133], v138 offset:6144
	ds_read_b128 v[146:149], v138 offset:4096
	ds_read_b128 v[174:177], v138 offset:2048
	ds_read_b128 v[178:181], v138
	ds_read_b128 v[138:141], v182 offset:2048
	ds_read_b128 v[182:185], v182
	v_mfma_f32_32x32x16_bf16 v[98:113], v[170:173], v[142:145], v[98:113]
	v_mfma_f32_32x32x16_bf16 v[34:49], v[134:137], v[142:145], v[34:49]
	ds_read_b128 v[142:145], v169 offset:6144
	ds_read_b128 v[186:189], v169 offset:4096
	s_waitcnt vmcnt(0)
	v_add_u32_e32 v169, s40, v159
	s_waitcnt lgkmcnt(0)
	s_barrier
	ds_read_b128 v[190:193], v169
	ds_read_b128 v[194:197], v234
	s_waitcnt lgkmcnt(0)
	v_mfma_f32_32x32x16_bf16 v[114:129], v[182:185], v[178:181], v[114:129]
	ds_read_b128 v[198:201], v202 offset:2048
	ds_read_b128 v[202:205], v202
	ds_read_b128 v[206:209], v226 offset:2048
	ds_read_b128 v[210:213], v226
	ds_read_b128 v[214:217], v234 offset:2048
	ds_read_b128 v[218:221], v169 offset:2048
	ds_read_b128 v[222:225], v226 offset:6144
	ds_read_b128 v[226:229], v226 offset:4096
	ds_read_b128 v[230:233], v234 offset:6144
	ds_read_b128 v[234:237], v234 offset:4096
	v_lshl_or_b32 v169, s16, 6, v161
	s_waitcnt lgkmcnt(0)
	s_barrier
	v_mfma_f32_32x32x16_bf16 v[82:97], v[170:173], v[186:189], v[82:97]
	v_mfma_f32_32x32x16_bf16 v[114:129], v[190:193], v[194:197], v[114:129]
	v_mfma_f32_32x32x16_bf16 v[98:113], v[182:185], v[174:177], v[98:113]
	v_mfma_f32_32x32x16_bf16 v[66:81], v[170:173], v[142:145], v[66:81]
	v_mfma_f32_32x32x16_bf16 v[82:97], v[182:185], v[146:149], v[82:97]
	s_waitcnt lgkmcnt(0)
	v_mfma_f32_32x32x16_bf16 v[114:129], v[202:205], v[210:213], v[114:129]
	v_mfma_f32_32x32x16_bf16 v[98:113], v[190:193], v[214:217], v[98:113]
	s_nop 10
	v_cvt_pk_bf16_f32 v238, v114, v115
	v_lshl_or_b32 v114, s26, 8, v165
	v_mad_u64_u32 v[114:115], s[24:25], v169, s35, v[114:115]
	v_cvt_pk_bf16_f32 v115, v116, v117
	ds_write_b16 v114, v238
	ds_write_b16_d16_hi v114, v238 offset:528
	ds_write_b16 v114, v115 offset:1056
	ds_write_b16_d16_hi v114, v115 offset:1584
	v_mfma_f32_32x32x16_bf16 v[66:81], v[182:185], v[130:133], v[66:81]
	v_cvt_pk_bf16_f32 v115, v118, v119
	ds_write_b16 v114, v115 offset:4224
	ds_write_b16_d16_hi v114, v115 offset:4752
	v_cvt_pk_bf16_f32 v115, v120, v121
	ds_write_b16 v114, v115 offset:5280
	ds_write_b16_d16_hi v114, v115 offset:5808
	v_cvt_pk_bf16_f32 v115, v122, v123
	ds_write_b16 v114, v115 offset:8448
	ds_write_b16_d16_hi v114, v115 offset:8976
	v_mfma_f32_32x32x16_bf16 v[82:97], v[190:193], v[234:237], v[82:97]
	v_cvt_pk_bf16_f32 v115, v124, v125
	ds_write_b16 v114, v115 offset:9504
	ds_write_b16_d16_hi v114, v115 offset:10032
	v_cvt_pk_bf16_f32 v115, v126, v127
	ds_write_b16 v114, v115 offset:12672
	ds_write_b16_d16_hi v114, v115 offset:13200
	v_cvt_pk_bf16_f32 v115, v128, v129
	ds_write_b16 v114, v115 offset:13728
	ds_write_b16_d16_hi v114, v115 offset:14256
	v_mfma_f32_32x32x16_bf16 v[98:113], v[202:205], v[206:209], v[98:113]
	v_mfma_f32_32x32x16_bf16 v[50:65], v[138:141], v[178:181], v[50:65]
	s_nop 10
	v_cvt_pk_bf16_f32 v98, v98, v99
	ds_write_b16 v114, v98 offset:64
	ds_write_b16_d16_hi v114, v98 offset:592
	v_cvt_pk_bf16_f32 v98, v100, v101
	ds_write_b16 v114, v98 offset:1120
	ds_write_b16_d16_hi v114, v98 offset:1648
	v_cvt_pk_bf16_f32 v98, v102, v103
	ds_write_b16 v114, v98 offset:4288
	ds_write_b16_d16_hi v114, v98 offset:4816
	v_cvt_pk_bf16_f32 v98, v104, v105
	v_mfma_f32_32x32x16_bf16 v[66:81], v[190:193], v[230:233], v[66:81]
	ds_write_b16 v114, v98 offset:5344
	ds_write_b16_d16_hi v114, v98 offset:5872
	v_cvt_pk_bf16_f32 v98, v106, v107
	ds_write_b16 v114, v98 offset:8512
	ds_write_b16_d16_hi v114, v98 offset:9040
	v_cvt_pk_bf16_f32 v98, v108, v109
	ds_write_b16 v114, v98 offset:9568
	ds_write_b16_d16_hi v114, v98 offset:10096
	v_cvt_pk_bf16_f32 v98, v110, v111
	v_mfma_f32_32x32x16_bf16 v[82:97], v[202:205], v[226:229], v[82:97]
	ds_write_b16 v114, v98 offset:12736
	ds_write_b16_d16_hi v114, v98 offset:13264
	v_cvt_pk_bf16_f32 v98, v112, v113
	ds_write_b16 v114, v98 offset:13792
	ds_write_b16_d16_hi v114, v98 offset:14320
	s_nop 6
	v_cvt_pk_bf16_f32 v82, v82, v83
	v_mfma_f32_32x32x16_bf16 v[18:33], v[134:137], v[186:189], v[18:33]
	ds_write_b16 v114, v82 offset:128
	ds_write_b16_d16_hi v114, v82 offset:656
	v_cvt_pk_bf16_f32 v82, v84, v85
	ds_write_b16 v114, v82 offset:1184
	ds_write_b16_d16_hi v114, v82 offset:1712
	v_cvt_pk_bf16_f32 v82, v86, v87
	ds_write_b16 v114, v82 offset:4352
	ds_write_b16_d16_hi v114, v82 offset:4880
	v_cvt_pk_bf16_f32 v82, v88, v89
	v_mfma_f32_32x32x16_bf16 v[34:49], v[138:141], v[174:177], v[34:49]
	ds_write_b16 v114, v82 offset:5408
	ds_write_b16_d16_hi v114, v82 offset:5936
	v_cvt_pk_bf16_f32 v82, v90, v91
	ds_write_b16 v114, v82 offset:8576
	ds_write_b16_d16_hi v114, v82 offset:9104
	v_cvt_pk_bf16_f32 v82, v92, v93
	ds_write_b16 v114, v82 offset:9632
	ds_write_b16_d16_hi v114, v82 offset:10160
	v_cvt_pk_bf16_f32 v82, v94, v95
	ds_write_b16 v114, v82 offset:12800
	ds_write_b16_d16_hi v114, v82 offset:13328
	v_mfma_f32_32x32x16_bf16 v[50:65], v[218:221], v[194:197], v[50:65]
	v_cvt_pk_bf16_f32 v82, v96, v97
	ds_write_b16 v114, v82 offset:13856
; DI unsigned pk2(float a, float b) { fl2_t f = {a, b}; bf2_t r = __builtin_convertvector(f, bf2_t); return __builtin_bit_cast(unsigned, r); }
; template <typename FA, typename FB, typename FE>
; DI void gemm_tile(char* lds, int K, int astride, int bstride, FA arow, FB brow, FE epi) {
;     ...
;   for (int mt = 0; mt < 2; ++mt)
; #pragma unroll
;     for (int nt = 0; nt < 4; ++nt)
; #pragma unroll
;       for (int i = 0; i < 16; i += 2) {
;         const int row = wm * 64 + mt * 32 + (i & 3) + 8 * (i >> 2) + 4 * h8;
;         const unsigned pr = pk2(acc[mt][nt][i], acc[mt][nt][i + 1]);
;         Cs[row * CSS + wn * 128 + nt * 32 + r] = (bfr)(pr & 0xffffu);
;         Cs[(row + 1) * CSS + wn * 128 + nt * 32 + r] = (bfr)(pr >> 16);
;       }
;   __syncthreads();
; DI void phase_moe(const Params& p, char* lds, int mode) {
;     ...
;         const int row = tid & 127, hf = tid >> 7, grow = half * 128 + row;
;         if (r0 + grow < n) {
	ds_write_b16_d16_hi v114, v82 offset:14384
	v_mfma_f32_32x32x16_bf16 v[66:81], v[202:205], v[222:225], v[66:81]
	v_mfma_f32_32x32x16_bf16 v[2:17], v[134:137], v[142:145], v[2:17]
	s_nop 10
	v_cvt_pk_bf16_f32 v66, v66, v67
	ds_write_b16 v114, v66 offset:192
	ds_write_b16_d16_hi v114, v66 offset:720
	v_cvt_pk_bf16_f32 v66, v68, v69
	ds_write_b16 v114, v66 offset:1248
	ds_write_b16_d16_hi v114, v66 offset:1776
	v_cvt_pk_bf16_f32 v66, v70, v71
	ds_write_b16 v114, v66 offset:4416
	ds_write_b16_d16_hi v114, v66 offset:4944
	v_mfma_f32_32x32x16_bf16 v[18:33], v[138:141], v[146:149], v[18:33]
	v_cvt_pk_bf16_f32 v66, v72, v73
	ds_write_b16 v114, v66 offset:5472
	ds_write_b16_d16_hi v114, v66 offset:6000
	v_cvt_pk_bf16_f32 v66, v74, v75
	ds_write_b16 v114, v66 offset:8640
	ds_write_b16_d16_hi v114, v66 offset:9168
	v_cvt_pk_bf16_f32 v66, v76, v77
	ds_write_b16 v114, v66 offset:9696
	ds_write_b16_d16_hi v114, v66 offset:10224
	v_cvt_pk_bf16_f32 v66, v78, v79
	v_mfma_f32_32x32x16_bf16 v[34:49], v[218:221], v[214:217], v[34:49]
	ds_write_b16 v114, v66 offset:12864
	ds_write_b16_d16_hi v114, v66 offset:13392
	v_cvt_pk_bf16_f32 v66, v80, v81
	ds_write_b16 v114, v66 offset:13920
	ds_write_b16_d16_hi v114, v66 offset:14448
	v_mfma_f32_32x32x16_bf16 v[50:65], v[198:201], v[210:213], v[50:65]
	v_mfma_f32_32x32x16_bf16 v[2:17], v[138:141], v[130:133], v[2:17]
	s_nop 10
	v_cvt_pk_bf16_f32 v50, v50, v51
	ds_write_b16 v114, v50 offset:16896
	ds_write_b16_d16_hi v114, v50 offset:17424
	v_cvt_pk_bf16_f32 v50, v52, v53
	ds_write_b16 v114, v50 offset:17952
	ds_write_b16_d16_hi v114, v50 offset:18480
	v_cvt_pk_bf16_f32 v50, v54, v55
	ds_write_b16 v114, v50 offset:21120
	ds_write_b16_d16_hi v114, v50 offset:21648
	v_mfma_f32_32x32x16_bf16 v[18:33], v[218:221], v[234:237], v[18:33]
	v_cvt_pk_bf16_f32 v50, v56, v57
	ds_write_b16 v114, v50 offset:22176
	ds_write_b16_d16_hi v114, v50 offset:22704
	v_cvt_pk_bf16_f32 v50, v58, v59
	ds_write_b16 v114, v50 offset:25344
	ds_write_b16_d16_hi v114, v50 offset:25872
	v_cvt_pk_bf16_f32 v50, v60, v61
	ds_write_b16 v114, v50 offset:26400
	ds_write_b16_d16_hi v114, v50 offset:26928
	v_cvt_pk_bf16_f32 v50, v62, v63
	v_mfma_f32_32x32x16_bf16 v[34:49], v[198:201], v[206:209], v[34:49]
	ds_write_b16 v114, v50 offset:29568
	ds_write_b16_d16_hi v114, v50 offset:30096
	v_cvt_pk_bf16_f32 v50, v64, v65
	ds_write_b16 v114, v50 offset:30624
	ds_write_b16_d16_hi v114, v50 offset:31152
	s_nop 6
	v_cvt_pk_bf16_f32 v34, v34, v35
	v_mfma_f32_32x32x16_bf16 v[2:17], v[218:221], v[230:233], v[2:17]
	ds_write_b16 v114, v34 offset:16960
	ds_write_b16_d16_hi v114, v34 offset:17488
	v_cvt_pk_bf16_f32 v34, v36, v37
	ds_write_b16 v114, v34 offset:18016
	ds_write_b16_d16_hi v114, v34 offset:18544
	v_cvt_pk_bf16_f32 v34, v38, v39
	ds_write_b16 v114, v34 offset:21184
	ds_write_b16_d16_hi v114, v34 offset:21712
	v_cvt_pk_bf16_f32 v34, v40, v41
	ds_write_b16 v114, v34 offset:22240
	ds_write_b16_d16_hi v114, v34 offset:22768
	v_mfma_f32_32x32x16_bf16 v[18:33], v[198:201], v[226:229], v[18:33]
	v_cvt_pk_bf16_f32 v34, v42, v43
	ds_write_b16 v114, v34 offset:25408
	ds_write_b16_d16_hi v114, v34 offset:25936
	v_cvt_pk_bf16_f32 v34, v44, v45
	ds_write_b16 v114, v34 offset:26464
	ds_write_b16_d16_hi v114, v34 offset:26992
	v_cvt_pk_bf16_f32 v34, v46, v47
	ds_write_b16 v114, v34 offset:29632
	ds_write_b16_d16_hi v114, v34 offset:30160
	v_mfma_f32_32x32x16_bf16 v[2:17], v[198:201], v[222:225], v[2:17]
	v_cvt_pk_bf16_f32 v34, v48, v49
	s_nop 0
	v_cvt_pk_bf16_f32 v18, v18, v19
	ds_write_b16 v114, v34 offset:30688
	ds_write_b16_d16_hi v114, v34 offset:31216
	ds_write_b16 v114, v18 offset:17024
	ds_write_b16_d16_hi v114, v18 offset:17552
	v_cvt_pk_bf16_f32 v18, v20, v21
	ds_write_b16 v114, v18 offset:18080
	ds_write_b16_d16_hi v114, v18 offset:18608
	v_cvt_pk_bf16_f32 v18, v22, v23
	ds_write_b16 v114, v18 offset:21248
	ds_write_b16_d16_hi v114, v18 offset:21776
	v_cvt_pk_bf16_f32 v18, v24, v25
	ds_write_b16 v114, v18 offset:22304
	ds_write_b16_d16_hi v114, v18 offset:22832
	v_cvt_pk_bf16_f32 v18, v26, v27
	ds_write_b16 v114, v18 offset:25472
	ds_write_b16_d16_hi v114, v18 offset:26000
	v_cvt_pk_bf16_f32 v18, v28, v29
	ds_write_b16 v114, v18 offset:26528
	ds_write_b16_d16_hi v114, v18 offset:27056
	v_cvt_pk_bf16_f32 v18, v30, v31
	ds_write_b16 v114, v18 offset:29696
	ds_write_b16_d16_hi v114, v18 offset:30224
	v_cvt_pk_bf16_f32 v18, v32, v33
	v_cvt_pk_bf16_f32 v2, v2, v3
	ds_write_b16 v114, v18 offset:30752
	ds_write_b16_d16_hi v114, v18 offset:31280
	ds_write_b16 v114, v2 offset:17088
	ds_write_b16_d16_hi v114, v2 offset:17616
	v_cvt_pk_bf16_f32 v2, v4, v5
	ds_write_b16 v114, v2 offset:18144
	ds_write_b16_d16_hi v114, v2 offset:18672
	v_cvt_pk_bf16_f32 v2, v6, v7
	ds_write_b16 v114, v2 offset:21312
	ds_write_b16_d16_hi v114, v2 offset:21840
	v_cvt_pk_bf16_f32 v2, v8, v9
	ds_write_b16 v114, v2 offset:22368
	ds_write_b16_d16_hi v114, v2 offset:22896
	v_cvt_pk_bf16_f32 v2, v10, v11
	ds_write_b16 v114, v2 offset:25536
	ds_write_b16_d16_hi v114, v2 offset:26064
	v_cvt_pk_bf16_f32 v2, v12, v13
	ds_write_b16 v114, v2 offset:26592
	ds_write_b16_d16_hi v114, v2 offset:27120
	v_cvt_pk_bf16_f32 v2, v14, v15
	ds_write_b16 v114, v2 offset:29760
	ds_write_b16_d16_hi v114, v2 offset:30288
	v_cvt_pk_bf16_f32 v2, v16, v17
	ds_write_b16 v114, v2 offset:30816
	ds_write_b16_d16_hi v114, v2 offset:31344
	v_add_u32_e32 v2, v162, v168
	s_waitcnt vmcnt(0)
	v_cmp_lt_i32_e32 vcc, v2, v167
	s_waitcnt lgkmcnt(0)
	s_barrier
	s_and_saveexec_b64 s[24:25], vcc
	s_cbranch_execz .LBB0_289
; DI unsigned pk2(float a, float b) { fl2_t f = {a, b}; bf2_t r = __builtin_convertvector(f, bf2_t); return __builtin_bit_cast(unsigned, r); }
; DI void phase_moe(const Params& p, char* lds, int mode) {
;     ...
;           bfr* dst = act + ((size_t)(nt * 2 + hf) * (2 * T) + (lb[li] + r0 + grow)) * 32;
; #pragma unroll
;           for (int q = 0; q < 4; ++q) {
;             float z[8];
; #pragma unroll
;             for (int u = 0; u < 2; ++u) {
;               float4 g = cs4(Cs, row, hf * 32 + q * 8 + u * 4);
;               float4 up = cs4(Cs, row, 64 + hf * 32 + q * 8 + u * 4);
;               z[u * 4 + 0] = g.x / (1.f + __expf(-g.x)) * up.x; z[u * 4 + 1] = g.y / (1.f + __expf(-g.y)) * up.y;
;               z[u * 4 + 2] = g.z / (1.f + __expf(-g.z)) * up.z; z[u * 4 + 3] = g.w / (1.f + __expf(-g.w)) * up.w;
;             }
;             u32x4 o; o[0] = pk2(z[0], z[1]); o[1] = pk2(z[2], z[3]); o[2] = pk2(z[4], z[5]); o[3] = pk2(z[6], z[7]);
;             *(u32x4*)(dst + q * 8) = o;
	s_add_i32 s16, s39, 0x25e00
	v_mov_b32_e32 v3, s16
	ds_read_b32 v3, v3
	ds_read_b128 v[18:21], v164
	ds_read_b128 v[10:13], v164 offset:16
	v_lshl_or_b32 v30, s37, 2, v163
	s_waitcnt lgkmcnt(1)
	v_lshlrev_b32_e32 v31, 16, v18
	v_add_u32_e32 v26, v3, v2
	v_ashrrev_i32_e32 v27, 31, v26
	v_mad_i64_i32 v[2:3], s[26:27], v30, s36, v[26:27]
	v_lshlrev_b64 v[2:3], 6, v[2:3]
	v_lshl_add_u64 v[28:29], s[10:11], 0, v[2:3]
	v_and_b32_e32 v18, 0xffff0000, v18
	v_mul_f32_e32 v2, 0xbfb8aa3b, v31
	v_exp_f32_e32 v14, v2
	v_mul_f32_e32 v2, 0xbfb8aa3b, v18
	v_exp_f32_e32 v15, v2
	ds_read_b128 v[6:9], v164 offset:32
	ds_read_b128 v[2:5], v164 offset:48
	ds_read_b128 v[22:25], v164 offset:128
	v_pk_add_f32 v[32:33], v[14:15], 1.0 op_sel_hi:[1,0]
	s_nop 0
	v_div_scale_f32 v36, s[26:27], v33, v33, v18
	v_rcp_f32_e32 v37, v36
	s_waitcnt lgkmcnt(0)
	v_lshlrev_b32_e32 v34, 16, v22
	v_and_b32_e32 v35, 0xffff0000, v22
	ds_read_b128 v[14:17], v164 offset:144
	v_fma_f32 v22, -v36, v37, 1.0
	v_fmac_f32_e32 v37, v22, v37
	v_div_scale_f32 v22, vcc, v18, v33, v18
	v_mul_f32_e32 v38, v22, v37
	v_fma_f32 v39, -v36, v38, v22
	v_fmac_f32_e32 v38, v39, v37
	v_fma_f32 v22, -v36, v38, v22
	v_div_scale_f32 v36, s[26:27], v32, v32, v31
	v_rcp_f32_e32 v39, v36
	v_div_fmas_f32 v22, v22, v37, v38
	v_div_fixup_f32 v33, v22, v33, v18
	v_and_b32_e32 v38, 0xffff0000, v19
	v_fma_f32 v18, -v36, v39, 1.0
	v_fmac_f32_e32 v39, v18, v39
	v_div_scale_f32 v18, vcc, v31, v32, v31
	v_mul_f32_e32 v22, v18, v39
	v_fma_f32 v37, -v36, v22, v18
	v_fmac_f32_e32 v22, v37, v39
	v_lshlrev_b32_e32 v37, 16, v19
	v_fma_f32 v36, -v36, v22, v18
	v_mul_f32_e32 v18, 0xbfb8aa3b, v37
	v_mul_f32_e32 v19, 0xbfb8aa3b, v38
	v_exp_f32_e32 v18, v18
	v_exp_f32_e32 v19, v19
	v_div_fmas_f32 v22, v36, v39, v22
	v_div_fixup_f32 v32, v22, v32, v31
	v_pk_mul_f32 v[32:33], v[32:33], v[34:35]
	v_pk_add_f32 v[18:19], v[18:19], 1.0 op_sel_hi:[1,0]
	v_lshlrev_b32_e32 v22, 16, v23
	v_div_scale_f32 v31, s[26:27], v19, v19, v38
	v_rcp_f32_e32 v36, v31
	v_and_b32_e32 v23, 0xffff0000, v23
	v_fma_f32 v34, -v31, v36, 1.0
	v_fmac_f32_e32 v36, v34, v36
	v_div_scale_f32 v34, vcc, v38, v19, v38
	v_mul_f32_e32 v35, v34, v36
	v_fma_f32 v39, -v31, v35, v34
	v_fmac_f32_e32 v35, v39, v36
	v_fma_f32 v31, -v31, v35, v34
	v_div_scale_f32 v34, s[26:27], v18, v18, v37
	v_rcp_f32_e32 v39, v34
	v_div_fmas_f32 v31, v31, v36, v35
	v_div_fixup_f32 v19, v31, v19, v38
	v_lshlrev_b32_e32 v38, 16, v20
	v_fma_f32 v31, -v34, v39, 1.0
	v_fmac_f32_e32 v39, v31, v39
	v_div_scale_f32 v31, vcc, v37, v18, v37
	v_mul_f32_e32 v36, v31, v39
	v_fma_f32 v35, -v34, v36, v31
	v_fmac_f32_e32 v36, v35, v39
	v_and_b32_e32 v20, 0xffff0000, v20
	v_fma_f32 v31, -v34, v36, v31
	v_mul_f32_e32 v34, 0xbfb8aa3b, v38
	v_mul_f32_e32 v35, 0xbfb8aa3b, v20
	v_exp_f32_e32 v34, v34
	v_exp_f32_e32 v35, v35
	v_div_fmas_f32 v31, v31, v39, v36
	v_div_fixup_f32 v18, v31, v18, v37
	v_pk_mul_f32 v[22:23], v[18:19], v[22:23]
	v_pk_add_f32 v[34:35], v[34:35], 1.0 op_sel_hi:[1,0]
	v_lshlrev_b32_e32 v18, 16, v24
	v_div_scale_f32 v31, s[26:27], v35, v35, v20
	v_rcp_f32_e32 v36, v31
	v_and_b32_e32 v19, 0xffff0000, v24
	v_fma_f32 v24, -v31, v36, 1.0
	v_fmac_f32_e32 v36, v24, v36
	v_div_scale_f32 v24, vcc, v20, v35, v20
	v_mul_f32_e32 v37, v24, v36
	v_fma_f32 v39, -v31, v37, v24
	v_fmac_f32_e32 v37, v39, v36
	v_fma_f32 v24, -v31, v37, v24
	v_div_scale_f32 v31, s[26:27], v34, v34, v38
	v_rcp_f32_e32 v39, v31
	v_div_fmas_f32 v24, v24, v36, v37
	v_div_fixup_f32 v35, v24, v35, v20
	v_and_b32_e32 v37, 0xffff0000, v21
	v_fma_f32 v20, -v31, v39, 1.0
	v_fmac_f32_e32 v39, v20, v39
	v_div_scale_f32 v20, vcc, v38, v34, v38
	v_mul_f32_e32 v24, v20, v39
	v_fma_f32 v36, -v31, v24, v20
	v_fmac_f32_e32 v24, v36, v39
	v_lshlrev_b32_e32 v36, 16, v21
	v_fma_f32 v31, -v31, v24, v20
	v_mul_f32_e32 v20, 0xbfb8aa3b, v36
	v_mul_f32_e32 v21, 0xbfb8aa3b, v37
	v_exp_f32_e32 v20, v20
	v_exp_f32_e32 v21, v21
	v_div_fmas_f32 v24, v31, v39, v24
	v_div_fixup_f32 v34, v24, v34, v38
	v_pk_mul_f32 v[34:35], v[34:35], v[18:19]
	v_pk_add_f32 v[20:21], v[20:21], 1.0 op_sel_hi:[1,0]
	v_lshlrev_b32_e32 v18, 16, v25
	v_div_scale_f32 v24, s[26:27], v21, v21, v37
	v_rcp_f32_e32 v31, v24
	v_and_b32_e32 v19, 0xffff0000, v25
	v_fma_f32 v25, -v24, v31, 1.0
	v_fmac_f32_e32 v31, v25, v31
	v_div_scale_f32 v25, vcc, v37, v21, v37
	v_mul_f32_e32 v38, v25, v31
	v_fma_f32 v39, -v24, v38, v25
	v_fmac_f32_e32 v38, v39, v31
	v_fma_f32 v24, -v24, v38, v25
	v_div_scale_f32 v25, s[26:27], v20, v20, v36
	v_rcp_f32_e32 v39, v25
	v_div_fmas_f32 v24, v24, v31, v38
	v_div_fixup_f32 v21, v24, v21, v37
	v_fma_f32 v24, -v25, v39, 1.0
	v_fmac_f32_e32 v39, v24, v39
	v_div_scale_f32 v24, vcc, v36, v20, v36
	v_mul_f32_e32 v31, v24, v39
	v_fma_f32 v37, -v25, v31, v24
	v_fmac_f32_e32 v31, v37, v39
	v_fma_f32 v24, -v25, v31, v24
	v_div_fmas_f32 v24, v24, v39, v31
	v_div_fixup_f32 v20, v24, v20, v36
	v_lshlrev_b32_e32 v31, 16, v10
	v_pk_mul_f32 v[24:25], v[20:21], v[18:19]
	v_and_b32_e32 v10, 0xffff0000, v10
	v_mul_f32_e32 v19, 0xbfb8aa3b, v31
	v_cvt_pk_bf16_f32 v18, v32, v33
	v_exp_f32_e32 v32, v19
	v_mul_f32_e32 v19, 0xbfb8aa3b, v10
	v_exp_f32_e32 v33, v19
	v_cvt_pk_bf16_f32 v19, v22, v23
	v_cvt_pk_bf16_f32 v21, v24, v25
	v_cvt_pk_bf16_f32 v20, v34, v35
	v_pk_add_f32 v[22:23], v[32:33], 1.0 op_sel_hi:[1,0]
	global_store_dwordx4 v[28:29], v[18:21], off
	v_div_scale_f32 v24, s[26:27], v23, v23, v10
	v_rcp_f32_e32 v25, v24
	s_waitcnt lgkmcnt(0)
; DI unsigned pk2(float a, float b) { fl2_t f = {a, b}; bf2_t r = __builtin_convertvector(f, bf2_t); return __builtin_bit_cast(unsigned, r); }
; DI void phase_moe(const Params& p, char* lds, int mode) {
;     ...
;               float4 g = cs4(Cs, row, hf * 32 + q * 8 + u * 4);
;               float4 up = cs4(Cs, row, 64 + hf * 32 + q * 8 + u * 4);
;               z[u * 4 + 0] = g.x / (1.f + __expf(-g.x)) * up.x; z[u * 4 + 1] = g.y / (1.f + __expf(-g.y)) * up.y;
;               z[u * 4 + 2] = g.z / (1.f + __expf(-g.z)) * up.z; z[u * 4 + 3] = g.w / (1.f + __expf(-g.w)) * up.w;
;             }
;             u32x4 o; o[0] = pk2(z[0], z[1]); o[1] = pk2(z[2], z[3]); o[2] = pk2(z[4], z[5]); o[3] = pk2(z[6], z[7]);
;             *(u32x4*)(dst + q * 8) = o;
	v_lshlrev_b32_e32 v18, 16, v14
	v_and_b32_e32 v19, 0xffff0000, v14
	v_fma_f32 v14, -v24, v25, 1.0
	v_fmac_f32_e32 v25, v14, v25
	v_div_scale_f32 v14, vcc, v10, v23, v10
	v_mul_f32_e32 v20, v14, v25
	v_fma_f32 v21, -v24, v20, v14
	v_fmac_f32_e32 v20, v21, v25
	v_fma_f32 v14, -v24, v20, v14
	v_div_scale_f32 v24, s[26:27], v22, v22, v31
	v_rcp_f32_e32 v32, v24
	v_div_fmas_f32 v14, v14, v25, v20
	v_div_fixup_f32 v21, v14, v23, v10
	v_lshlrev_b32_e32 v23, 16, v11
	v_fma_f32 v10, -v24, v32, 1.0
	v_fmac_f32_e32 v32, v10, v32
	v_div_scale_f32 v10, vcc, v31, v22, v31
	v_mul_f32_e32 v14, v10, v32
	v_fma_f32 v20, -v24, v14, v10
	v_fmac_f32_e32 v14, v20, v32
	v_fma_f32 v20, -v24, v14, v10
	v_and_b32_e32 v24, 0xffff0000, v11
	v_mul_f32_e32 v10, 0xbfb8aa3b, v23
	v_mul_f32_e32 v11, 0xbfb8aa3b, v24
	v_exp_f32_e32 v10, v10
	v_exp_f32_e32 v11, v11
	v_div_fmas_f32 v14, v20, v32, v14
	v_div_fixup_f32 v20, v14, v22, v31
	v_pk_mul_f32 v[18:19], v[20:21], v[18:19]
	v_pk_add_f32 v[10:11], v[10:11], 1.0 op_sel_hi:[1,0]
	v_lshlrev_b32_e32 v14, 16, v15
	v_div_scale_f32 v22, s[26:27], v11, v11, v24
	v_rcp_f32_e32 v25, v22
	v_and_b32_e32 v15, 0xffff0000, v15
	v_fma_f32 v20, -v22, v25, 1.0
	v_fmac_f32_e32 v25, v20, v25
	v_div_scale_f32 v20, vcc, v24, v11, v24
	v_mul_f32_e32 v21, v20, v25
	v_fma_f32 v31, -v22, v21, v20
	v_fmac_f32_e32 v21, v31, v25
	v_fma_f32 v20, -v22, v21, v20
	v_div_scale_f32 v22, s[26:27], v10, v10, v23
	v_rcp_f32_e32 v31, v22
	v_div_fmas_f32 v20, v20, v25, v21
	v_div_fixup_f32 v11, v20, v11, v24
	v_lshlrev_b32_e32 v25, 16, v12
	v_fma_f32 v20, -v22, v31, 1.0
	v_fmac_f32_e32 v31, v20, v31
	v_div_scale_f32 v20, vcc, v23, v10, v23
	v_mul_f32_e32 v24, v20, v31
	v_fma_f32 v21, -v22, v24, v20
	v_fmac_f32_e32 v24, v21, v31
	v_and_b32_e32 v12, 0xffff0000, v12
	v_fma_f32 v22, -v22, v24, v20
	v_mul_f32_e32 v20, 0xbfb8aa3b, v25
	v_mul_f32_e32 v21, 0xbfb8aa3b, v12
	v_exp_f32_e32 v20, v20
	v_exp_f32_e32 v21, v21
	v_div_fmas_f32 v22, v22, v31, v24
	v_div_fixup_f32 v10, v22, v10, v23
	v_pk_mul_f32 v[14:15], v[10:11], v[14:15]
	v_pk_add_f32 v[20:21], v[20:21], 1.0 op_sel_hi:[1,0]
	v_lshlrev_b32_e32 v10, 16, v16
	v_div_scale_f32 v22, s[26:27], v21, v21, v12
	v_rcp_f32_e32 v23, v22
	v_and_b32_e32 v11, 0xffff0000, v16
	v_fma_f32 v16, -v22, v23, 1.0
	v_fmac_f32_e32 v23, v16, v23
	v_div_scale_f32 v16, vcc, v12, v21, v12
	v_mul_f32_e32 v24, v16, v23
	v_fma_f32 v31, -v22, v24, v16
	v_fmac_f32_e32 v24, v31, v23
	v_fma_f32 v16, -v22, v24, v16
	v_div_scale_f32 v22, s[26:27], v20, v20, v25
	v_rcp_f32_e32 v31, v22
	v_div_fmas_f32 v16, v16, v23, v24
	v_div_fixup_f32 v21, v16, v21, v12
	v_and_b32_e32 v24, 0xffff0000, v13
	v_fma_f32 v12, -v22, v31, 1.0
	v_fmac_f32_e32 v31, v12, v31
	v_div_scale_f32 v12, vcc, v25, v20, v25
	v_mul_f32_e32 v16, v12, v31
	v_fma_f32 v23, -v22, v16, v12
	v_fmac_f32_e32 v16, v23, v31
	v_lshlrev_b32_e32 v23, 16, v13
	v_fma_f32 v22, -v22, v16, v12
	v_mul_f32_e32 v12, 0xbfb8aa3b, v23
	v_mul_f32_e32 v13, 0xbfb8aa3b, v24
	v_exp_f32_e32 v12, v12
	v_exp_f32_e32 v13, v13
	v_div_fmas_f32 v16, v22, v31, v16
	v_div_fixup_f32 v20, v16, v20, v25
	v_pk_mul_f32 v[20:21], v[20:21], v[10:11]
	v_pk_add_f32 v[12:13], v[12:13], 1.0 op_sel_hi:[1,0]
	v_lshlrev_b32_e32 v10, 16, v17
	v_div_scale_f32 v16, s[26:27], v13, v13, v24
	v_rcp_f32_e32 v22, v16
	v_and_b32_e32 v11, 0xffff0000, v17
	v_fma_f32 v17, -v16, v22, 1.0
	v_fmac_f32_e32 v22, v17, v22
	v_div_scale_f32 v17, vcc, v24, v13, v24
	v_mul_f32_e32 v25, v17, v22
	v_fma_f32 v31, -v16, v25, v17
	v_fmac_f32_e32 v25, v31, v22
	v_fma_f32 v16, -v16, v25, v17
	v_div_scale_f32 v17, s[26:27], v12, v12, v23
	v_rcp_f32_e32 v31, v17
	v_div_fmas_f32 v16, v16, v22, v25
	v_div_fixup_f32 v13, v16, v13, v24
	v_fma_f32 v16, -v17, v31, 1.0
	v_fmac_f32_e32 v31, v16, v31
	v_div_scale_f32 v16, vcc, v23, v12, v23
	v_mul_f32_e32 v22, v16, v31
	v_fma_f32 v24, -v17, v22, v16
	v_fmac_f32_e32 v22, v24, v31
	v_fma_f32 v16, -v17, v22, v16
	v_div_fmas_f32 v16, v16, v31, v22
	v_div_fixup_f32 v12, v16, v12, v23
	v_lshlrev_b32_e32 v22, 16, v6
	v_pk_mul_f32 v[16:17], v[12:13], v[10:11]
	v_and_b32_e32 v6, 0xffff0000, v6
	v_mul_f32_e32 v13, 0xbfb8aa3b, v22
	v_cvt_pk_bf16_f32 v10, v18, v19
	v_exp_f32_e32 v18, v13
	v_mul_f32_e32 v13, 0xbfb8aa3b, v6
	v_exp_f32_e32 v19, v13
	v_cvt_pk_bf16_f32 v11, v14, v15
	v_cvt_pk_bf16_f32 v13, v16, v17
	ds_read_b128 v[14:17], v164 offset:160
	v_pk_add_f32 v[18:19], v[18:19], 1.0 op_sel_hi:[1,0]
	v_cvt_pk_bf16_f32 v12, v20, v21
	v_div_scale_f32 v23, s[26:27], v19, v19, v6
	v_rcp_f32_e32 v24, v23
	s_waitcnt lgkmcnt(0)
; DI unsigned pk2(float a, float b) { fl2_t f = {a, b}; bf2_t r = __builtin_convertvector(f, bf2_t); return __builtin_bit_cast(unsigned, r); }
; DI void phase_moe(const Params& p, char* lds, int mode) {
;     ...
;               float4 g = cs4(Cs, row, hf * 32 + q * 8 + u * 4);
;               float4 up = cs4(Cs, row, 64 + hf * 32 + q * 8 + u * 4);
;               z[u * 4 + 0] = g.x / (1.f + __expf(-g.x)) * up.x; z[u * 4 + 1] = g.y / (1.f + __expf(-g.y)) * up.y;
;               z[u * 4 + 2] = g.z / (1.f + __expf(-g.z)) * up.z; z[u * 4 + 3] = g.w / (1.f + __expf(-g.w)) * up.w;
;             }
;             u32x4 o; o[0] = pk2(z[0], z[1]); o[1] = pk2(z[2], z[3]); o[2] = pk2(z[4], z[5]); o[3] = pk2(z[6], z[7]);
;             *(u32x4*)(dst + q * 8) = o;
	v_lshlrev_b32_e32 v20, 16, v14
	v_and_b32_e32 v21, 0xffff0000, v14
	global_store_dwordx4 v[28:29], v[10:13], off offset:16
	v_fma_f32 v14, -v23, v24, 1.0
	v_fmac_f32_e32 v24, v14, v24
	v_div_scale_f32 v14, vcc, v6, v19, v6
	v_mul_f32_e32 v25, v14, v24
	v_fma_f32 v31, -v23, v25, v14
	v_fmac_f32_e32 v25, v31, v24
	v_fma_f32 v14, -v23, v25, v14
	v_div_scale_f32 v23, s[26:27], v18, v18, v22
	v_rcp_f32_e32 v31, v23
	v_div_fmas_f32 v14, v14, v24, v25
	v_div_fixup_f32 v19, v14, v19, v6
	v_and_b32_e32 v25, 0xffff0000, v7
	v_fma_f32 v6, -v23, v31, 1.0
	v_fmac_f32_e32 v31, v6, v31
	v_div_scale_f32 v6, vcc, v22, v18, v22
	v_mul_f32_e32 v14, v6, v31
	v_fma_f32 v24, -v23, v14, v6
	v_fmac_f32_e32 v14, v24, v31
	v_lshlrev_b32_e32 v24, 16, v7
	v_fma_f32 v23, -v23, v14, v6
	v_mul_f32_e32 v6, 0xbfb8aa3b, v24
	v_mul_f32_e32 v7, 0xbfb8aa3b, v25
	v_exp_f32_e32 v6, v6
	v_exp_f32_e32 v7, v7
	v_div_fmas_f32 v14, v23, v31, v14
	v_div_fixup_f32 v18, v14, v18, v22
	v_pk_mul_f32 v[18:19], v[18:19], v[20:21]
	v_pk_add_f32 v[6:7], v[6:7], 1.0 op_sel_hi:[1,0]
	v_lshlrev_b32_e32 v14, 16, v15
	v_div_scale_f32 v22, s[26:27], v7, v7, v25
	v_rcp_f32_e32 v23, v22
	v_and_b32_e32 v15, 0xffff0000, v15
	ds_read_b128 v[10:13], v164 offset:176
	v_fma_f32 v20, -v22, v23, 1.0
	v_fmac_f32_e32 v23, v20, v23
	v_div_scale_f32 v20, vcc, v25, v7, v25
	v_mul_f32_e32 v21, v20, v23
	v_fma_f32 v31, -v22, v21, v20
	v_fmac_f32_e32 v21, v31, v23
	v_fma_f32 v20, -v22, v21, v20
	v_div_scale_f32 v22, s[26:27], v6, v6, v24
	v_rcp_f32_e32 v31, v22
	v_div_fmas_f32 v20, v20, v23, v21
	v_div_fixup_f32 v7, v20, v7, v25
	v_lshlrev_b32_e32 v25, 16, v8
	v_fma_f32 v20, -v22, v31, 1.0
	v_fmac_f32_e32 v31, v20, v31
	v_div_scale_f32 v20, vcc, v24, v6, v24
	v_mul_f32_e32 v23, v20, v31
	v_fma_f32 v21, -v22, v23, v20
	v_fmac_f32_e32 v23, v21, v31
	v_and_b32_e32 v8, 0xffff0000, v8
	v_fma_f32 v22, -v22, v23, v20
	v_mul_f32_e32 v20, 0xbfb8aa3b, v25
	v_mul_f32_e32 v21, 0xbfb8aa3b, v8
	v_exp_f32_e32 v20, v20
	v_exp_f32_e32 v21, v21
	v_div_fmas_f32 v22, v22, v31, v23
	v_div_fixup_f32 v6, v22, v6, v24
	v_pk_mul_f32 v[14:15], v[6:7], v[14:15]
	v_pk_add_f32 v[20:21], v[20:21], 1.0 op_sel_hi:[1,0]
	v_lshlrev_b32_e32 v6, 16, v16
	v_div_scale_f32 v22, s[26:27], v21, v21, v8
	v_rcp_f32_e32 v23, v22
	v_and_b32_e32 v7, 0xffff0000, v16
	v_fma_f32 v16, -v22, v23, 1.0
	v_fmac_f32_e32 v23, v16, v23
	v_div_scale_f32 v16, vcc, v8, v21, v8
	v_mul_f32_e32 v24, v16, v23
	v_fma_f32 v31, -v22, v24, v16
	v_fmac_f32_e32 v24, v31, v23
	v_fma_f32 v16, -v22, v24, v16
	v_div_scale_f32 v22, s[26:27], v20, v20, v25
	v_rcp_f32_e32 v31, v22
	v_div_fmas_f32 v16, v16, v23, v24
	v_div_fixup_f32 v21, v16, v21, v8
	v_and_b32_e32 v24, 0xffff0000, v9
	v_fma_f32 v8, -v22, v31, 1.0
	v_fmac_f32_e32 v31, v8, v31
	v_div_scale_f32 v8, vcc, v25, v20, v25
	v_mul_f32_e32 v16, v8, v31
	v_fma_f32 v23, -v22, v16, v8
	v_fmac_f32_e32 v16, v23, v31
	v_lshlrev_b32_e32 v23, 16, v9
	v_fma_f32 v22, -v22, v16, v8
	v_mul_f32_e32 v8, 0xbfb8aa3b, v23
	v_mul_f32_e32 v9, 0xbfb8aa3b, v24
	v_exp_f32_e32 v8, v8
	v_exp_f32_e32 v9, v9
	v_div_fmas_f32 v16, v22, v31, v16
	v_div_fixup_f32 v20, v16, v20, v25
	v_pk_mul_f32 v[20:21], v[20:21], v[6:7]
	v_pk_add_f32 v[8:9], v[8:9], 1.0 op_sel_hi:[1,0]
	v_lshlrev_b32_e32 v6, 16, v17
	v_div_scale_f32 v16, s[26:27], v9, v9, v24
	v_rcp_f32_e32 v22, v16
	v_and_b32_e32 v7, 0xffff0000, v17
	v_fma_f32 v17, -v16, v22, 1.0
	v_fmac_f32_e32 v22, v17, v22
	v_div_scale_f32 v17, vcc, v24, v9, v24
	v_mul_f32_e32 v25, v17, v22
	v_fma_f32 v31, -v16, v25, v17
	v_fmac_f32_e32 v25, v31, v22
	v_fma_f32 v16, -v16, v25, v17
	v_div_scale_f32 v17, s[26:27], v8, v8, v23
	v_rcp_f32_e32 v31, v17
	v_div_fmas_f32 v16, v16, v22, v25
	v_div_fixup_f32 v9, v16, v9, v24
	v_fma_f32 v16, -v17, v31, 1.0
	v_fmac_f32_e32 v31, v16, v31
	v_div_scale_f32 v16, vcc, v23, v8, v23
	v_mul_f32_e32 v22, v16, v31
	v_fma_f32 v24, -v17, v22, v16
	v_fmac_f32_e32 v22, v24, v31
	v_fma_f32 v16, -v17, v22, v16
	v_div_fmas_f32 v16, v16, v31, v22
	v_div_fixup_f32 v8, v16, v8, v23
	v_lshlrev_b32_e32 v22, 16, v2
	v_pk_mul_f32 v[16:17], v[8:9], v[6:7]
	v_and_b32_e32 v2, 0xffff0000, v2
	v_mul_f32_e32 v7, 0xbfb8aa3b, v22
	v_cvt_pk_bf16_f32 v6, v18, v19
	v_exp_f32_e32 v18, v7
	v_mul_f32_e32 v7, 0xbfb8aa3b, v2
	v_exp_f32_e32 v19, v7
	v_cvt_pk_bf16_f32 v7, v14, v15
	v_cvt_pk_bf16_f32 v9, v16, v17
	v_cvt_pk_bf16_f32 v8, v20, v21
	v_pk_add_f32 v[14:15], v[18:19], 1.0 op_sel_hi:[1,0]
	global_store_dwordx4 v[28:29], v[6:9], off offset:32
	v_div_scale_f32 v16, s[26:27], v15, v15, v2
	v_rcp_f32_e32 v17, v16
	s_waitcnt lgkmcnt(0)
; DI unsigned pk2(float a, float b) { fl2_t f = {a, b}; bf2_t r = __builtin_convertvector(f, bf2_t); return __builtin_bit_cast(unsigned, r); }
; DI void phase_moe(const Params& p, char* lds, int mode) {
;     ...
; #pragma unroll
;           for (int q = 0; q < 4; ++q) {
;             float z[8];
; #pragma unroll
;             for (int u = 0; u < 2; ++u) {
;               float4 g = cs4(Cs, row, hf * 32 + q * 8 + u * 4);
;               float4 up = cs4(Cs, row, 64 + hf * 32 + q * 8 + u * 4);
;               z[u * 4 + 0] = g.x / (1.f + __expf(-g.x)) * up.x; z[u * 4 + 1] = g.y / (1.f + __expf(-g.y)) * up.y;
;               z[u * 4 + 2] = g.z / (1.f + __expf(-g.z)) * up.z; z[u * 4 + 3] = g.w / (1.f + __expf(-g.w)) * up.w;
;             }
;             u32x4 o; o[0] = pk2(z[0], z[1]); o[1] = pk2(z[2], z[3]); o[2] = pk2(z[4], z[5]); o[3] = pk2(z[6], z[7]);
;             *(u32x4*)(dst + q * 8) = o;
	v_lshlrev_b32_e32 v6, 16, v10
	v_and_b32_e32 v7, 0xffff0000, v10
	v_fma_f32 v8, -v16, v17, 1.0
	v_fmac_f32_e32 v17, v8, v17
	v_div_scale_f32 v8, vcc, v2, v15, v2
	v_mul_f32_e32 v9, v8, v17
	v_fma_f32 v10, -v16, v9, v8
	v_fmac_f32_e32 v9, v10, v17
	v_div_scale_f32 v10, s[26:27], v14, v14, v22
	v_fma_f32 v8, -v16, v9, v8
	v_rcp_f32_e32 v16, v10
	v_div_fmas_f32 v8, v8, v17, v9
	v_div_fixup_f32 v9, v8, v15, v2
	v_and_b32_e32 v17, 0xffff0000, v3
	v_fma_f32 v2, -v10, v16, 1.0
	v_fmac_f32_e32 v16, v2, v16
	v_div_scale_f32 v2, vcc, v22, v14, v22
	v_mul_f32_e32 v8, v2, v16
	v_fma_f32 v15, -v10, v8, v2
	v_fmac_f32_e32 v8, v15, v16
	v_lshlrev_b32_e32 v15, 16, v3
	v_fma_f32 v10, -v10, v8, v2
	v_mul_f32_e32 v2, 0xbfb8aa3b, v15
	v_mul_f32_e32 v3, 0xbfb8aa3b, v17
	v_exp_f32_e32 v2, v2
	v_exp_f32_e32 v3, v3
	v_div_fmas_f32 v8, v10, v16, v8
	v_div_fixup_f32 v8, v8, v14, v22
	v_pk_mul_f32 v[6:7], v[8:9], v[6:7]
	v_pk_add_f32 v[2:3], v[2:3], 1.0 op_sel_hi:[1,0]
	v_lshlrev_b32_e32 v8, 16, v11
	v_div_scale_f32 v10, s[26:27], v3, v3, v17
	v_rcp_f32_e32 v14, v10
	v_and_b32_e32 v9, 0xffff0000, v11
	v_fma_f32 v11, -v10, v14, 1.0
	v_fmac_f32_e32 v14, v11, v14
	v_div_scale_f32 v11, vcc, v17, v3, v17
	v_mul_f32_e32 v16, v11, v14
	v_fma_f32 v18, -v10, v16, v11
	v_fmac_f32_e32 v16, v18, v14
	v_fma_f32 v10, -v10, v16, v11
	v_div_scale_f32 v11, s[26:27], v2, v2, v15
	v_rcp_f32_e32 v18, v11
	v_div_fmas_f32 v10, v10, v14, v16
	v_div_fixup_f32 v3, v10, v3, v17
	v_lshlrev_b32_e32 v17, 16, v4
	v_fma_f32 v10, -v11, v18, 1.0
	v_fmac_f32_e32 v18, v10, v18
	v_div_scale_f32 v10, vcc, v15, v2, v15
	v_mul_f32_e32 v14, v10, v18
	v_fma_f32 v16, -v11, v14, v10
	v_fmac_f32_e32 v14, v16, v18
	v_and_b32_e32 v4, 0xffff0000, v4
	v_fma_f32 v16, -v11, v14, v10
	v_mul_f32_e32 v10, 0xbfb8aa3b, v17
	v_mul_f32_e32 v11, 0xbfb8aa3b, v4
	v_exp_f32_e32 v10, v10
	v_exp_f32_e32 v11, v11
	v_div_fmas_f32 v14, v16, v18, v14
	v_div_fixup_f32 v2, v14, v2, v15
	v_pk_mul_f32 v[8:9], v[2:3], v[8:9]
	v_pk_add_f32 v[10:11], v[10:11], 1.0 op_sel_hi:[1,0]
	v_lshlrev_b32_e32 v2, 16, v12
	v_div_scale_f32 v14, s[26:27], v11, v11, v4
	v_rcp_f32_e32 v15, v14
	v_and_b32_e32 v3, 0xffff0000, v12
	v_fma_f32 v12, -v14, v15, 1.0
	v_fmac_f32_e32 v15, v12, v15
	v_div_scale_f32 v12, vcc, v4, v11, v4
	v_mul_f32_e32 v16, v12, v15
	v_fma_f32 v18, -v14, v16, v12
	v_fmac_f32_e32 v16, v18, v15
	v_fma_f32 v12, -v14, v16, v12
	v_div_scale_f32 v14, s[26:27], v10, v10, v17
	v_rcp_f32_e32 v18, v14
	v_div_fmas_f32 v12, v12, v15, v16
	v_div_fixup_f32 v11, v12, v11, v4
	v_and_b32_e32 v16, 0xffff0000, v5
	v_fma_f32 v4, -v14, v18, 1.0
	v_fmac_f32_e32 v18, v4, v18
	v_div_scale_f32 v4, vcc, v17, v10, v17
	v_mul_f32_e32 v12, v4, v18
	v_fma_f32 v15, -v14, v12, v4
	v_fmac_f32_e32 v12, v15, v18
	v_lshlrev_b32_e32 v15, 16, v5
	v_fma_f32 v14, -v14, v12, v4
	v_mul_f32_e32 v4, 0xbfb8aa3b, v15
	v_mul_f32_e32 v5, 0xbfb8aa3b, v16
	v_exp_f32_e32 v4, v4
	v_exp_f32_e32 v5, v5
	v_div_fmas_f32 v12, v14, v18, v12
	v_div_fixup_f32 v10, v12, v10, v17
	v_pk_mul_f32 v[10:11], v[10:11], v[2:3]
	v_pk_add_f32 v[4:5], v[4:5], 1.0 op_sel_hi:[1,0]
	v_lshlrev_b32_e32 v2, 16, v13
	v_div_scale_f32 v12, s[26:27], v5, v5, v16
	v_rcp_f32_e32 v14, v12
	v_and_b32_e32 v3, 0xffff0000, v13
	v_fma_f32 v13, -v12, v14, 1.0
	v_fmac_f32_e32 v14, v13, v14
	v_div_scale_f32 v13, vcc, v16, v5, v16
	v_mul_f32_e32 v17, v13, v14
	v_fma_f32 v18, -v12, v17, v13
	v_fmac_f32_e32 v17, v18, v14
	v_fma_f32 v12, -v12, v17, v13
	v_div_scale_f32 v13, s[26:27], v4, v4, v15
	v_rcp_f32_e32 v18, v13
	v_div_fmas_f32 v12, v12, v14, v17
	v_div_fixup_f32 v5, v12, v5, v16
	v_fma_f32 v12, -v13, v18, 1.0
	v_fmac_f32_e32 v18, v12, v18
	v_div_scale_f32 v12, vcc, v15, v4, v15
	v_mul_f32_e32 v14, v12, v18
	v_fma_f32 v16, -v13, v14, v12
	v_fmac_f32_e32 v14, v16, v18
	v_fma_f32 v12, -v13, v14, v12
	v_div_fmas_f32 v12, v12, v18, v14
	v_div_fixup_f32 v4, v12, v4, v15
	v_pk_mul_f32 v[12:13], v[4:5], v[2:3]
	v_cvt_pk_bf16_f32 v4, v10, v11
	v_cvt_pk_bf16_f32 v5, v12, v13
	ds_read_b128 v[10:13], v164 offset:256
	v_cvt_pk_bf16_f32 v2, v6, v7
	v_cvt_pk_bf16_f32 v3, v8, v9
	global_store_dwordx4 v[28:29], v[2:5], off offset:48
	ds_read_b128 v[16:19], v164 offset:384
	s_waitcnt lgkmcnt(1)
	v_lshlrev_b32_e32 v24, 16, v10
	v_and_b32_e32 v10, 0xffff0000, v10
	v_mul_f32_e32 v4, 0xbfb8aa3b, v24
	v_mul_f32_e32 v5, 0xbfb8aa3b, v10
	v_exp_f32_e32 v4, v4
	v_exp_f32_e32 v5, v5
	v_or_b32_e32 v2, 2, v30
	v_mad_i64_i32 v[2:3], s[26:27], v2, s36, v[26:27]
	v_pk_add_f32 v[20:21], v[4:5], 1.0 op_sel_hi:[1,0]
	s_waitcnt lgkmcnt(0)
; DI unsigned pk2(float a, float b) { fl2_t f = {a, b}; bf2_t r = __builtin_convertvector(f, bf2_t); return __builtin_bit_cast(unsigned, r); }
; DI void phase_moe(const Params& p, char* lds, int mode) {
;     ...
; #pragma unroll
;           for (int q = 0; q < 4; ++q) {
;             float z[8];
; #pragma unroll
;             for (int u = 0; u < 2; ++u) {
;               float4 g = cs4(Cs, row, hf * 32 + q * 8 + u * 4);
;               float4 up = cs4(Cs, row, 64 + hf * 32 + q * 8 + u * 4);
;               z[u * 4 + 0] = g.x / (1.f + __expf(-g.x)) * up.x; z[u * 4 + 1] = g.y / (1.f + __expf(-g.y)) * up.y;
;               z[u * 4 + 2] = g.z / (1.f + __expf(-g.z)) * up.z; z[u * 4 + 3] = g.w / (1.f + __expf(-g.w)) * up.w;
;             }
;             u32x4 o; o[0] = pk2(z[0], z[1]); o[1] = pk2(z[2], z[3]); o[2] = pk2(z[4], z[5]); o[3] = pk2(z[6], z[7]);
;             *(u32x4*)(dst + q * 8) = o;
;           }
	v_lshlrev_b32_e32 v22, 16, v16
	v_div_scale_f32 v25, s[26:27], v21, v21, v10
	v_rcp_f32_e32 v26, v25
	v_and_b32_e32 v23, 0xffff0000, v16
	ds_read_b128 v[6:9], v164 offset:272
	v_lshlrev_b64 v[2:3], 6, v[2:3]
	v_fma_f32 v16, -v25, v26, 1.0
	v_fmac_f32_e32 v26, v16, v26
	v_div_scale_f32 v16, vcc, v10, v21, v10
	v_mul_f32_e32 v27, v16, v26
	v_fma_f32 v28, -v25, v27, v16
	v_fmac_f32_e32 v27, v28, v26
	v_fma_f32 v16, -v25, v27, v16
	v_div_scale_f32 v25, s[26:27], v20, v20, v24
	v_rcp_f32_e32 v28, v25
	v_div_fmas_f32 v16, v16, v26, v27
	v_div_fixup_f32 v21, v16, v21, v10
	v_and_b32_e32 v27, 0xffff0000, v11
	v_fma_f32 v10, -v25, v28, 1.0
	v_fmac_f32_e32 v28, v10, v28
	v_div_scale_f32 v10, vcc, v24, v20, v24
	v_mul_f32_e32 v16, v10, v28
	v_fma_f32 v26, -v25, v16, v10
	v_fmac_f32_e32 v16, v26, v28
	v_lshlrev_b32_e32 v26, 16, v11
	v_fma_f32 v25, -v25, v16, v10
	v_mul_f32_e32 v10, 0xbfb8aa3b, v26
	v_mul_f32_e32 v11, 0xbfb8aa3b, v27
	v_exp_f32_e32 v10, v10
	v_exp_f32_e32 v11, v11
	v_div_fmas_f32 v16, v25, v28, v16
	v_div_fixup_f32 v20, v16, v20, v24
	v_pk_mul_f32 v[20:21], v[20:21], v[22:23]
	v_pk_add_f32 v[10:11], v[10:11], 1.0 op_sel_hi:[1,0]
	v_lshlrev_b32_e32 v16, 16, v17
	v_div_scale_f32 v24, s[26:27], v11, v11, v27
	v_rcp_f32_e32 v25, v24
	v_and_b32_e32 v17, 0xffff0000, v17
	v_lshl_add_u64 v[14:15], s[10:11], 0, v[2:3]
	ds_read_b128 v[2:5], v164 offset:400
	v_fma_f32 v22, -v24, v25, 1.0
	v_fmac_f32_e32 v25, v22, v25
	v_div_scale_f32 v22, vcc, v27, v11, v27
	v_mul_f32_e32 v23, v22, v25
	v_fma_f32 v28, -v24, v23, v22
	v_fmac_f32_e32 v23, v28, v25
	v_fma_f32 v22, -v24, v23, v22
	v_div_scale_f32 v24, s[26:27], v10, v10, v26
	v_rcp_f32_e32 v28, v24
	v_div_fmas_f32 v22, v22, v25, v23
	v_div_fixup_f32 v11, v22, v11, v27
	v_lshlrev_b32_e32 v27, 16, v12
	v_fma_f32 v22, -v24, v28, 1.0
	v_fmac_f32_e32 v28, v22, v28
	v_div_scale_f32 v22, vcc, v26, v10, v26
	v_mul_f32_e32 v25, v22, v28
	v_fma_f32 v23, -v24, v25, v22
	v_fmac_f32_e32 v25, v23, v28
	v_and_b32_e32 v12, 0xffff0000, v12
	v_fma_f32 v24, -v24, v25, v22
	v_mul_f32_e32 v22, 0xbfb8aa3b, v27
	v_mul_f32_e32 v23, 0xbfb8aa3b, v12
	v_exp_f32_e32 v22, v22
	v_exp_f32_e32 v23, v23
	v_div_fmas_f32 v24, v24, v28, v25
	v_div_fixup_f32 v10, v24, v10, v26
	v_pk_mul_f32 v[16:17], v[10:11], v[16:17]
	v_pk_add_f32 v[22:23], v[22:23], 1.0 op_sel_hi:[1,0]
	v_lshlrev_b32_e32 v10, 16, v18
	v_div_scale_f32 v24, s[26:27], v23, v23, v12
	v_rcp_f32_e32 v25, v24
	v_and_b32_e32 v11, 0xffff0000, v18
	v_fma_f32 v18, -v24, v25, 1.0
	v_fmac_f32_e32 v25, v18, v25
	v_div_scale_f32 v18, vcc, v12, v23, v12
	v_mul_f32_e32 v26, v18, v25
	v_fma_f32 v28, -v24, v26, v18
	v_fmac_f32_e32 v26, v28, v25
	v_fma_f32 v18, -v24, v26, v18
	v_div_scale_f32 v24, s[26:27], v22, v22, v27
	v_rcp_f32_e32 v28, v24
	v_div_fmas_f32 v18, v18, v25, v26
	v_div_fixup_f32 v23, v18, v23, v12
	v_and_b32_e32 v26, 0xffff0000, v13
	v_fma_f32 v12, -v24, v28, 1.0
	v_fmac_f32_e32 v28, v12, v28
	v_div_scale_f32 v12, vcc, v27, v22, v27
	v_mul_f32_e32 v18, v12, v28
	v_fma_f32 v25, -v24, v18, v12
	v_fmac_f32_e32 v18, v25, v28
	v_lshlrev_b32_e32 v25, 16, v13
	v_fma_f32 v24, -v24, v18, v12
	v_mul_f32_e32 v12, 0xbfb8aa3b, v25
	v_mul_f32_e32 v13, 0xbfb8aa3b, v26
	v_exp_f32_e32 v12, v12
	v_exp_f32_e32 v13, v13
	v_div_fmas_f32 v18, v24, v28, v18
	v_div_fixup_f32 v22, v18, v22, v27
	v_pk_mul_f32 v[22:23], v[22:23], v[10:11]
	v_pk_add_f32 v[12:13], v[12:13], 1.0 op_sel_hi:[1,0]
	v_lshlrev_b32_e32 v10, 16, v19
	v_div_scale_f32 v18, s[26:27], v13, v13, v26
	v_rcp_f32_e32 v24, v18
	v_and_b32_e32 v11, 0xffff0000, v19
	v_fma_f32 v19, -v18, v24, 1.0
	v_fmac_f32_e32 v24, v19, v24
	v_div_scale_f32 v19, vcc, v26, v13, v26
	v_mul_f32_e32 v27, v19, v24
	v_fma_f32 v28, -v18, v27, v19
	v_fmac_f32_e32 v27, v28, v24
	v_fma_f32 v18, -v18, v27, v19
	v_div_scale_f32 v19, s[26:27], v12, v12, v25
	v_rcp_f32_e32 v28, v19
	v_div_fmas_f32 v18, v18, v24, v27
	v_div_fixup_f32 v13, v18, v13, v26
	v_fma_f32 v18, -v19, v28, 1.0
	v_fmac_f32_e32 v28, v18, v28
	v_div_scale_f32 v18, vcc, v25, v12, v25
	v_mul_f32_e32 v24, v18, v28
	v_fma_f32 v26, -v19, v24, v18
	v_fmac_f32_e32 v24, v26, v28
	v_fma_f32 v18, -v19, v24, v18
	v_div_fmas_f32 v18, v18, v28, v24
	v_div_fixup_f32 v12, v18, v12, v25
	s_waitcnt lgkmcnt(1)
	v_lshlrev_b32_e32 v24, 16, v6
	v_pk_mul_f32 v[18:19], v[12:13], v[10:11]
	v_and_b32_e32 v6, 0xffff0000, v6
	v_mul_f32_e32 v11, 0xbfb8aa3b, v24
	v_cvt_pk_bf16_f32 v10, v20, v21
	v_exp_f32_e32 v20, v11
	v_mul_f32_e32 v11, 0xbfb8aa3b, v6
	v_exp_f32_e32 v21, v11
	v_cvt_pk_bf16_f32 v11, v16, v17
	v_cvt_pk_bf16_f32 v13, v18, v19
	v_cvt_pk_bf16_f32 v12, v22, v23
	v_pk_add_f32 v[16:17], v[20:21], 1.0 op_sel_hi:[1,0]
	global_store_dwordx4 v[14:15], v[10:13], off
	v_div_scale_f32 v18, s[26:27], v17, v17, v6
	v_rcp_f32_e32 v19, v18
	s_waitcnt lgkmcnt(0)
; DI unsigned pk2(float a, float b) { fl2_t f = {a, b}; bf2_t r = __builtin_convertvector(f, bf2_t); return __builtin_bit_cast(unsigned, r); }
; DI void phase_moe(const Params& p, char* lds, int mode) {
;     ...
; #pragma unroll
;           for (int q = 0; q < 4; ++q) {
;             float z[8];
; #pragma unroll
;             for (int u = 0; u < 2; ++u) {
;               float4 g = cs4(Cs, row, hf * 32 + q * 8 + u * 4);
;               float4 up = cs4(Cs, row, 64 + hf * 32 + q * 8 + u * 4);
;               z[u * 4 + 0] = g.x / (1.f + __expf(-g.x)) * up.x; z[u * 4 + 1] = g.y / (1.f + __expf(-g.y)) * up.y;
;               z[u * 4 + 2] = g.z / (1.f + __expf(-g.z)) * up.z; z[u * 4 + 3] = g.w / (1.f + __expf(-g.w)) * up.w;
;             }
;             u32x4 o; o[0] = pk2(z[0], z[1]); o[1] = pk2(z[2], z[3]); o[2] = pk2(z[4], z[5]); o[3] = pk2(z[6], z[7]);
;             *(u32x4*)(dst + q * 8) = o;
;           }
	v_lshlrev_b32_e32 v10, 16, v2
	v_and_b32_e32 v11, 0xffff0000, v2
	v_fma_f32 v2, -v18, v19, 1.0
	v_fmac_f32_e32 v19, v2, v19
	v_div_scale_f32 v2, vcc, v6, v17, v6
	v_mul_f32_e32 v12, v2, v19
	v_fma_f32 v13, -v18, v12, v2
	v_fmac_f32_e32 v12, v13, v19
	v_fma_f32 v2, -v18, v12, v2
	v_div_scale_f32 v18, s[26:27], v16, v16, v24
	v_rcp_f32_e32 v20, v18
	v_div_fmas_f32 v2, v2, v19, v12
	v_div_fixup_f32 v13, v2, v17, v6
	v_and_b32_e32 v19, 0xffff0000, v7
	v_fma_f32 v2, -v18, v20, 1.0
	v_fmac_f32_e32 v20, v2, v20
	v_div_scale_f32 v2, vcc, v24, v16, v24
	v_mul_f32_e32 v12, v2, v20
	v_fma_f32 v6, -v18, v12, v2
	v_fmac_f32_e32 v12, v6, v20
	v_fma_f32 v2, -v18, v12, v2
	v_lshlrev_b32_e32 v18, 16, v7
	v_mul_f32_e32 v6, 0xbfb8aa3b, v18
	v_mul_f32_e32 v7, 0xbfb8aa3b, v19
	v_exp_f32_e32 v6, v6
	v_exp_f32_e32 v7, v7
	v_div_fmas_f32 v2, v2, v20, v12
	v_div_fixup_f32 v12, v2, v16, v24
	v_pk_mul_f32 v[16:17], v[12:13], v[10:11]
	v_pk_add_f32 v[6:7], v[6:7], 1.0 op_sel_hi:[1,0]
	v_lshlrev_b32_e32 v2, 16, v3
	v_div_scale_f32 v20, s[26:27], v7, v7, v19
	v_rcp_f32_e32 v21, v20
	v_and_b32_e32 v3, 0xffff0000, v3
	v_fma_f32 v10, -v20, v21, 1.0
	v_fmac_f32_e32 v21, v10, v21
	v_div_scale_f32 v10, vcc, v19, v7, v19
	v_mul_f32_e32 v11, v10, v21
	v_fma_f32 v12, -v20, v11, v10
	v_fmac_f32_e32 v11, v12, v21
	v_div_scale_f32 v12, s[26:27], v6, v6, v18
	v_rcp_f32_e32 v13, v12
	v_fma_f32 v10, -v20, v11, v10
	v_div_fmas_f32 v10, v10, v21, v11
	v_div_fixup_f32 v7, v10, v7, v19
	v_fma_f32 v10, -v12, v13, 1.0
	v_fmac_f32_e32 v13, v10, v13
	v_div_scale_f32 v10, vcc, v18, v6, v18
	v_mul_f32_e32 v19, v10, v13
	v_fma_f32 v11, -v12, v19, v10
	v_fmac_f32_e32 v19, v11, v13
	v_lshlrev_b32_e32 v20, 16, v8
	v_and_b32_e32 v8, 0xffff0000, v8
	v_fma_f32 v12, -v12, v19, v10
	v_mul_f32_e32 v10, 0xbfb8aa3b, v20
	v_mul_f32_e32 v11, 0xbfb8aa3b, v8
	v_exp_f32_e32 v10, v10
	v_exp_f32_e32 v11, v11
	v_div_fmas_f32 v12, v12, v13, v19
	v_div_fixup_f32 v6, v12, v6, v18
	v_pk_mul_f32 v[6:7], v[6:7], v[2:3]
	v_pk_add_f32 v[10:11], v[10:11], 1.0 op_sel_hi:[1,0]
	v_lshlrev_b32_e32 v2, 16, v4
	v_div_scale_f32 v12, s[26:27], v11, v11, v8
	v_rcp_f32_e32 v13, v12
	v_and_b32_e32 v3, 0xffff0000, v4
	v_and_b32_e32 v21, 0xffff0000, v9
	v_fma_f32 v4, -v12, v13, 1.0
	v_fmac_f32_e32 v13, v4, v13
	v_div_scale_f32 v4, vcc, v8, v11, v8
	v_mul_f32_e32 v18, v4, v13
	v_fma_f32 v19, -v12, v18, v4
	v_fmac_f32_e32 v18, v19, v13
	v_fma_f32 v4, -v12, v18, v4
	v_div_scale_f32 v12, s[26:27], v10, v10, v20
	v_rcp_f32_e32 v19, v12
	v_div_fmas_f32 v4, v4, v13, v18
	v_div_fixup_f32 v11, v4, v11, v8
	v_fma_f32 v4, -v12, v19, 1.0
	v_fmac_f32_e32 v19, v4, v19
	v_div_scale_f32 v4, vcc, v20, v10, v20
	v_mul_f32_e32 v13, v4, v19
	v_fma_f32 v8, -v12, v13, v4
	v_fmac_f32_e32 v13, v8, v19
	v_fma_f32 v4, -v12, v13, v4
	v_lshlrev_b32_e32 v12, 16, v9
	v_mul_f32_e32 v8, 0xbfb8aa3b, v12
	v_mul_f32_e32 v9, 0xbfb8aa3b, v21
	v_exp_f32_e32 v8, v8
	v_exp_f32_e32 v9, v9
	v_div_fmas_f32 v4, v4, v19, v13
	v_div_fixup_f32 v10, v4, v10, v20
	v_pk_mul_f32 v[18:19], v[10:11], v[2:3]
	v_pk_add_f32 v[8:9], v[8:9], 1.0 op_sel_hi:[1,0]
	v_lshlrev_b32_e32 v2, 16, v5
	v_div_scale_f32 v4, s[26:27], v9, v9, v21
	v_rcp_f32_e32 v13, v4
	v_and_b32_e32 v3, 0xffff0000, v5
	v_fma_f32 v5, -v4, v13, 1.0
	v_fmac_f32_e32 v13, v5, v13
	v_div_scale_f32 v5, vcc, v21, v9, v21
	v_mul_f32_e32 v10, v5, v13
	v_fma_f32 v11, -v4, v10, v5
	v_fmac_f32_e32 v10, v11, v13
	v_div_scale_f32 v11, s[26:27], v8, v8, v12
	v_rcp_f32_e32 v20, v11
	v_fma_f32 v4, -v4, v10, v5
	v_div_fmas_f32 v4, v4, v13, v10
	v_div_fixup_f32 v5, v4, v9, v21
	v_fma_f32 v4, -v11, v20, 1.0
	v_fmac_f32_e32 v20, v4, v20
	v_div_scale_f32 v4, vcc, v12, v8, v12
	v_mul_f32_e32 v9, v4, v20
	v_fma_f32 v10, -v11, v9, v4
	v_fmac_f32_e32 v9, v10, v20
	v_fma_f32 v4, -v11, v9, v4
	v_div_fmas_f32 v4, v4, v20, v9
	v_div_fixup_f32 v4, v4, v8, v12
	ds_read_b128 v[10:13], v164 offset:288
	v_pk_mul_f32 v[20:21], v[4:5], v[2:3]
	v_cvt_pk_bf16_f32 v2, v16, v17
	v_cvt_pk_bf16_f32 v4, v18, v19
	ds_read_b128 v[16:19], v164 offset:416
	s_waitcnt lgkmcnt(1)
	v_lshlrev_b32_e32 v24, 16, v10
	v_and_b32_e32 v10, 0xffff0000, v10
	v_mul_f32_e32 v5, 0xbfb8aa3b, v24
	v_exp_f32_e32 v22, v5
	v_mul_f32_e32 v5, 0xbfb8aa3b, v10
	v_exp_f32_e32 v23, v5
	v_cvt_pk_bf16_f32 v5, v20, v21
	v_cvt_pk_bf16_f32 v3, v6, v7
	ds_read_b128 v[6:9], v164 offset:304
	v_pk_add_f32 v[20:21], v[22:23], 1.0 op_sel_hi:[1,0]
	s_waitcnt lgkmcnt(1)
; DI unsigned pk2(float a, float b) { fl2_t f = {a, b}; bf2_t r = __builtin_convertvector(f, bf2_t); return __builtin_bit_cast(unsigned, r); }
; DI void phase_moe(const Params& p, char* lds, int mode) {
;     ...
; #pragma unroll
;           for (int q = 0; q < 4; ++q) {
;             float z[8];
; #pragma unroll
;             for (int u = 0; u < 2; ++u) {
;               float4 g = cs4(Cs, row, hf * 32 + q * 8 + u * 4);
;               float4 up = cs4(Cs, row, 64 + hf * 32 + q * 8 + u * 4);
;               z[u * 4 + 0] = g.x / (1.f + __expf(-g.x)) * up.x; z[u * 4 + 1] = g.y / (1.f + __expf(-g.y)) * up.y;
;               z[u * 4 + 2] = g.z / (1.f + __expf(-g.z)) * up.z; z[u * 4 + 3] = g.w / (1.f + __expf(-g.w)) * up.w;
;             }
;             u32x4 o; o[0] = pk2(z[0], z[1]); o[1] = pk2(z[2], z[3]); o[2] = pk2(z[4], z[5]); o[3] = pk2(z[6], z[7]);
;             *(u32x4*)(dst + q * 8) = o;
;           }
	v_lshlrev_b32_e32 v22, 16, v16
	v_div_scale_f32 v25, s[26:27], v21, v21, v10
	v_rcp_f32_e32 v26, v25
	v_and_b32_e32 v23, 0xffff0000, v16
	global_store_dwordx4 v[14:15], v[2:5], off offset:16
	ds_read_b128 v[2:5], v164 offset:432
	v_fma_f32 v16, -v25, v26, 1.0
	v_fmac_f32_e32 v26, v16, v26
	v_div_scale_f32 v16, vcc, v10, v21, v10
	v_mul_f32_e32 v27, v16, v26
	v_fma_f32 v28, -v25, v27, v16
	v_fmac_f32_e32 v27, v28, v26
	v_fma_f32 v16, -v25, v27, v16
	v_div_scale_f32 v25, s[26:27], v20, v20, v24
	v_rcp_f32_e32 v28, v25
	v_div_fmas_f32 v16, v16, v26, v27
	v_div_fixup_f32 v21, v16, v21, v10
	v_and_b32_e32 v27, 0xffff0000, v11
	v_fma_f32 v10, -v25, v28, 1.0
	v_fmac_f32_e32 v28, v10, v28
	v_div_scale_f32 v10, vcc, v24, v20, v24
	v_mul_f32_e32 v16, v10, v28
	v_fma_f32 v26, -v25, v16, v10
	v_fmac_f32_e32 v16, v26, v28
	v_lshlrev_b32_e32 v26, 16, v11
	v_fma_f32 v25, -v25, v16, v10
	v_mul_f32_e32 v10, 0xbfb8aa3b, v26
	v_mul_f32_e32 v11, 0xbfb8aa3b, v27
	v_exp_f32_e32 v10, v10
	v_exp_f32_e32 v11, v11
	v_div_fmas_f32 v16, v25, v28, v16
	v_div_fixup_f32 v20, v16, v20, v24
	v_pk_mul_f32 v[20:21], v[20:21], v[22:23]
	v_pk_add_f32 v[10:11], v[10:11], 1.0 op_sel_hi:[1,0]
	v_lshlrev_b32_e32 v16, 16, v17
	v_div_scale_f32 v24, s[26:27], v11, v11, v27
	v_rcp_f32_e32 v25, v24
	v_and_b32_e32 v17, 0xffff0000, v17
	v_fma_f32 v22, -v24, v25, 1.0
	v_fmac_f32_e32 v25, v22, v25
	v_div_scale_f32 v22, vcc, v27, v11, v27
	v_mul_f32_e32 v23, v22, v25
	v_fma_f32 v28, -v24, v23, v22
	v_fmac_f32_e32 v23, v28, v25
	v_fma_f32 v22, -v24, v23, v22
	v_div_scale_f32 v24, s[26:27], v10, v10, v26
	v_rcp_f32_e32 v28, v24
	v_div_fmas_f32 v22, v22, v25, v23
	v_div_fixup_f32 v11, v22, v11, v27
	v_lshlrev_b32_e32 v27, 16, v12
	v_fma_f32 v22, -v24, v28, 1.0
	v_fmac_f32_e32 v28, v22, v28
	v_div_scale_f32 v22, vcc, v26, v10, v26
	v_mul_f32_e32 v25, v22, v28
	v_fma_f32 v23, -v24, v25, v22
	v_fmac_f32_e32 v25, v23, v28
	v_and_b32_e32 v12, 0xffff0000, v12
	v_fma_f32 v24, -v24, v25, v22
	v_mul_f32_e32 v22, 0xbfb8aa3b, v27
	v_mul_f32_e32 v23, 0xbfb8aa3b, v12
	v_exp_f32_e32 v22, v22
	v_exp_f32_e32 v23, v23
	v_div_fmas_f32 v24, v24, v28, v25
	v_div_fixup_f32 v10, v24, v10, v26
	v_pk_mul_f32 v[16:17], v[10:11], v[16:17]
	v_pk_add_f32 v[22:23], v[22:23], 1.0 op_sel_hi:[1,0]
	v_lshlrev_b32_e32 v10, 16, v18
	v_div_scale_f32 v24, s[26:27], v23, v23, v12
	v_rcp_f32_e32 v25, v24
	v_and_b32_e32 v11, 0xffff0000, v18
	v_fma_f32 v18, -v24, v25, 1.0
	v_fmac_f32_e32 v25, v18, v25
	v_div_scale_f32 v18, vcc, v12, v23, v12
	v_mul_f32_e32 v26, v18, v25
	v_fma_f32 v28, -v24, v26, v18
	v_fmac_f32_e32 v26, v28, v25
	v_fma_f32 v18, -v24, v26, v18
	v_div_scale_f32 v24, s[26:27], v22, v22, v27
	v_rcp_f32_e32 v28, v24
	v_div_fmas_f32 v18, v18, v25, v26
	v_div_fixup_f32 v23, v18, v23, v12
	v_and_b32_e32 v26, 0xffff0000, v13
	v_fma_f32 v12, -v24, v28, 1.0
	v_fmac_f32_e32 v28, v12, v28
	v_div_scale_f32 v12, vcc, v27, v22, v27
	v_mul_f32_e32 v18, v12, v28
	v_fma_f32 v25, -v24, v18, v12
	v_fmac_f32_e32 v18, v25, v28
	v_lshlrev_b32_e32 v25, 16, v13
	v_fma_f32 v24, -v24, v18, v12
	v_mul_f32_e32 v12, 0xbfb8aa3b, v25
	v_mul_f32_e32 v13, 0xbfb8aa3b, v26
	v_exp_f32_e32 v12, v12
	v_exp_f32_e32 v13, v13
	v_div_fmas_f32 v18, v24, v28, v18
	v_div_fixup_f32 v22, v18, v22, v27
	v_pk_mul_f32 v[22:23], v[22:23], v[10:11]
	v_pk_add_f32 v[12:13], v[12:13], 1.0 op_sel_hi:[1,0]
	v_lshlrev_b32_e32 v10, 16, v19
	v_div_scale_f32 v18, s[26:27], v13, v13, v26
	v_rcp_f32_e32 v24, v18
	v_and_b32_e32 v11, 0xffff0000, v19
	v_fma_f32 v19, -v18, v24, 1.0
	v_fmac_f32_e32 v24, v19, v24
	v_div_scale_f32 v19, vcc, v26, v13, v26
	v_mul_f32_e32 v27, v19, v24
	v_fma_f32 v28, -v18, v27, v19
	v_fmac_f32_e32 v27, v28, v24
	v_fma_f32 v18, -v18, v27, v19
	v_div_scale_f32 v19, s[26:27], v12, v12, v25
	v_rcp_f32_e32 v28, v19
	v_div_fmas_f32 v18, v18, v24, v27
	v_div_fixup_f32 v13, v18, v13, v26
	v_fma_f32 v18, -v19, v28, 1.0
	v_fmac_f32_e32 v28, v18, v28
	v_div_scale_f32 v18, vcc, v25, v12, v25
	v_mul_f32_e32 v24, v18, v28
	v_fma_f32 v26, -v19, v24, v18
	v_fmac_f32_e32 v24, v26, v28
	v_fma_f32 v18, -v19, v24, v18
	v_div_fmas_f32 v18, v18, v28, v24
	v_div_fixup_f32 v12, v18, v12, v25
	s_waitcnt lgkmcnt(1)
; DI unsigned pk2(float a, float b) { fl2_t f = {a, b}; bf2_t r = __builtin_convertvector(f, bf2_t); return __builtin_bit_cast(unsigned, r); }
; DI void phase_moe(const Params& p, char* lds, int mode) {
;     ...
; #pragma unroll
;           for (int q = 0; q < 4; ++q) {
;             float z[8];
; #pragma unroll
;             for (int u = 0; u < 2; ++u) {
;               float4 g = cs4(Cs, row, hf * 32 + q * 8 + u * 4);
;               float4 up = cs4(Cs, row, 64 + hf * 32 + q * 8 + u * 4);
;               z[u * 4 + 0] = g.x / (1.f + __expf(-g.x)) * up.x; z[u * 4 + 1] = g.y / (1.f + __expf(-g.y)) * up.y;
;               z[u * 4 + 2] = g.z / (1.f + __expf(-g.z)) * up.z; z[u * 4 + 3] = g.w / (1.f + __expf(-g.w)) * up.w;
;             }
;             u32x4 o; o[0] = pk2(z[0], z[1]); o[1] = pk2(z[2], z[3]); o[2] = pk2(z[4], z[5]); o[3] = pk2(z[6], z[7]);
;             *(u32x4*)(dst + q * 8) = o;
;           }
	v_lshlrev_b32_e32 v24, 16, v6
	v_pk_mul_f32 v[18:19], v[12:13], v[10:11]
	v_and_b32_e32 v6, 0xffff0000, v6
	v_mul_f32_e32 v11, 0xbfb8aa3b, v24
	v_cvt_pk_bf16_f32 v10, v20, v21
	v_exp_f32_e32 v20, v11
	v_mul_f32_e32 v11, 0xbfb8aa3b, v6
	v_exp_f32_e32 v21, v11
	v_cvt_pk_bf16_f32 v11, v16, v17
	v_cvt_pk_bf16_f32 v13, v18, v19
	v_cvt_pk_bf16_f32 v12, v22, v23
	v_pk_add_f32 v[16:17], v[20:21], 1.0 op_sel_hi:[1,0]
	global_store_dwordx4 v[14:15], v[10:13], off offset:32
	v_div_scale_f32 v18, s[26:27], v17, v17, v6
	v_rcp_f32_e32 v19, v18
	s_waitcnt lgkmcnt(0)
	v_lshlrev_b32_e32 v10, 16, v2
	v_and_b32_e32 v11, 0xffff0000, v2
	v_fma_f32 v2, -v18, v19, 1.0
	v_fmac_f32_e32 v19, v2, v19
	v_div_scale_f32 v2, vcc, v6, v17, v6
	v_mul_f32_e32 v12, v2, v19
	v_fma_f32 v13, -v18, v12, v2
	v_fmac_f32_e32 v12, v13, v19
	v_fma_f32 v2, -v18, v12, v2
	v_div_scale_f32 v18, s[26:27], v16, v16, v24
	v_rcp_f32_e32 v20, v18
	v_div_fmas_f32 v2, v2, v19, v12
	v_div_fixup_f32 v13, v2, v17, v6
	v_lshlrev_b32_e32 v17, 16, v7
	v_fma_f32 v2, -v18, v20, 1.0
	v_fmac_f32_e32 v20, v2, v20
	v_div_scale_f32 v2, vcc, v24, v16, v24
	v_mul_f32_e32 v12, v2, v20
	v_fma_f32 v6, -v18, v12, v2
	v_fmac_f32_e32 v12, v6, v20
	v_fma_f32 v2, -v18, v12, v2
	v_and_b32_e32 v18, 0xffff0000, v7
	v_mul_f32_e32 v6, 0xbfb8aa3b, v17
	v_mul_f32_e32 v7, 0xbfb8aa3b, v18
	v_exp_f32_e32 v6, v6
	v_exp_f32_e32 v7, v7
	v_div_fmas_f32 v2, v2, v20, v12
	v_div_fixup_f32 v12, v2, v16, v24
	v_pk_mul_f32 v[10:11], v[12:13], v[10:11]
	v_pk_add_f32 v[6:7], v[6:7], 1.0 op_sel_hi:[1,0]
	v_lshlrev_b32_e32 v2, 16, v3
	v_div_scale_f32 v16, s[26:27], v7, v7, v18
	v_rcp_f32_e32 v19, v16
	v_and_b32_e32 v3, 0xffff0000, v3
	v_fma_f32 v12, -v16, v19, 1.0
	v_fmac_f32_e32 v19, v12, v19
	v_div_scale_f32 v12, vcc, v18, v7, v18
	v_mul_f32_e32 v13, v12, v19
	v_fma_f32 v20, -v16, v13, v12
	v_fmac_f32_e32 v13, v20, v19
	v_fma_f32 v12, -v16, v13, v12
	v_div_scale_f32 v16, s[26:27], v6, v6, v17
	v_rcp_f32_e32 v20, v16
	v_div_fmas_f32 v12, v12, v19, v13
	v_div_fixup_f32 v7, v12, v7, v18
	v_lshlrev_b32_e32 v19, 16, v8
	v_fma_f32 v12, -v16, v20, 1.0
	v_fmac_f32_e32 v20, v12, v20
	v_div_scale_f32 v12, vcc, v17, v6, v17
	v_mul_f32_e32 v18, v12, v20
	v_fma_f32 v13, -v16, v18, v12
	v_fmac_f32_e32 v18, v13, v20
	v_and_b32_e32 v8, 0xffff0000, v8
	v_fma_f32 v16, -v16, v18, v12
	v_mul_f32_e32 v12, 0xbfb8aa3b, v19
	v_mul_f32_e32 v13, 0xbfb8aa3b, v8
	v_exp_f32_e32 v12, v12
	v_exp_f32_e32 v13, v13
	v_div_fmas_f32 v16, v16, v20, v18
	v_div_fixup_f32 v6, v16, v6, v17
	v_pk_mul_f32 v[6:7], v[6:7], v[2:3]
	v_pk_add_f32 v[12:13], v[12:13], 1.0 op_sel_hi:[1,0]
	v_lshlrev_b32_e32 v2, 16, v4
	v_div_scale_f32 v16, s[26:27], v13, v13, v8
	v_rcp_f32_e32 v17, v16
	v_and_b32_e32 v3, 0xffff0000, v4
	v_fma_f32 v4, -v16, v17, 1.0
	v_fmac_f32_e32 v17, v4, v17
	v_div_scale_f32 v4, vcc, v8, v13, v8
	v_mul_f32_e32 v18, v4, v17
	v_fma_f32 v20, -v16, v18, v4
	v_fmac_f32_e32 v18, v20, v17
	v_fma_f32 v4, -v16, v18, v4
	v_div_scale_f32 v16, s[26:27], v12, v12, v19
	v_rcp_f32_e32 v20, v16
	v_div_fmas_f32 v4, v4, v17, v18
	v_div_fixup_f32 v13, v4, v13, v8
	v_and_b32_e32 v18, 0xffff0000, v9
	v_fma_f32 v4, -v16, v20, 1.0
	v_fmac_f32_e32 v20, v4, v20
	v_div_scale_f32 v4, vcc, v19, v12, v19
	v_mul_f32_e32 v17, v4, v20
	v_fma_f32 v8, -v16, v17, v4
	v_fmac_f32_e32 v17, v8, v20
	v_fma_f32 v4, -v16, v17, v4
	v_lshlrev_b32_e32 v16, 16, v9
	v_mul_f32_e32 v8, 0xbfb8aa3b, v16
	v_mul_f32_e32 v9, 0xbfb8aa3b, v18
	v_exp_f32_e32 v8, v8
	v_exp_f32_e32 v9, v9
	v_div_fmas_f32 v4, v4, v20, v17
	v_div_fixup_f32 v12, v4, v12, v19
	v_pk_mul_f32 v[12:13], v[12:13], v[2:3]
	v_pk_add_f32 v[8:9], v[8:9], 1.0 op_sel_hi:[1,0]
	v_lshlrev_b32_e32 v2, 16, v5
	v_div_scale_f32 v4, s[26:27], v9, v9, v18
	v_rcp_f32_e32 v17, v4
	v_and_b32_e32 v3, 0xffff0000, v5
	v_fma_f32 v5, -v4, v17, 1.0
	v_fmac_f32_e32 v17, v5, v17
	v_div_scale_f32 v5, vcc, v18, v9, v18
	v_mul_f32_e32 v19, v5, v17
	v_fma_f32 v20, -v4, v19, v5
	v_fmac_f32_e32 v19, v20, v17
	v_div_scale_f32 v20, s[26:27], v8, v8, v16
	v_rcp_f32_e32 v21, v20
	v_fma_f32 v4, -v4, v19, v5
	v_div_fmas_f32 v4, v4, v17, v19
	v_div_fixup_f32 v5, v4, v9, v18
	v_fma_f32 v4, -v20, v21, 1.0
	v_fmac_f32_e32 v21, v4, v21
	v_div_scale_f32 v4, vcc, v16, v8, v16
	v_mul_f32_e32 v9, v4, v21
	v_fma_f32 v17, -v20, v9, v4
	v_fmac_f32_e32 v9, v17, v21
	v_fma_f32 v4, -v20, v9, v4
	v_div_fmas_f32 v4, v4, v21, v9
	v_div_fixup_f32 v4, v4, v8, v16
	v_pk_mul_f32 v[8:9], v[4:5], v[2:3]
	v_cvt_pk_bf16_f32 v2, v10, v11
	v_cvt_pk_bf16_f32 v3, v6, v7
	v_cvt_pk_bf16_f32 v4, v12, v13
	v_cvt_pk_bf16_f32 v5, v8, v9
	global_store_dwordx4 v[14:15], v[2:5], off offset:48
	s_branch .LBB0_289
